# stack: hand-written layer-1 input projection epilogue, scan waves skip the helper register copies, scan chunk prologue waits only for the first vector
# speedup vs baseline: 1.0019x; 1.0019x over previous
; #define SB __builtin_amdgcn_sched_barrier(0)
; #define CMP(G, c8) { CMP1(G, 0, 2 * (c8)) CMP1(G, 1, 2 * (c8) + 1) }
; __device__ __forceinline__ void phase_scan(const Args& a, unsigned char* lds) {
;     ...
;                 if (it >= 1 && it <= nch) {
;                     const int c = it - 1, buf = c & 1;
;                     const float* vb = vec + (size_t)((buf * 2 + hd) * 16) * 384 + cb;
;                     float* yb = ybuf + ((buf * 2 + hd) * 16) * 64;
;     ...
;                     f32x4 KA[8];
; #pragma unroll
;                     for (int j = 0; j < 8; ++j) KA[j] = *(const f32x4*)(vb + 256 + 4 * j);
; #pragma nounroll
;                     for (int s = 0; s < 16; ++s) {
;                         const float* vs = vb + s * 384;
;                         const float vi = vs[128 - cb + srow];
;                         f32x4 G0[8], G1[8], G2[8];
;                         LDG(G0, 0) SB;
;                         LDG(G1, 1) SB;
;                         f32x2 c0 = {0.f, 0.f}, c1 = {0.f, 0.f};
; #pragma unroll
;                         for (int j = 0; j < 8; ++j) { c0 += S2[2 * j] * (f32x2){KA[j][0], KA[j][1]}; c1 += S2[2 * j + 1] * (f32x2){KA[j][2], KA[j][3]}; }
;                         float cs = (c0.x + c0.y) + (c1.x + c1.y);
;                         cs += dpp_f(cs, 0);
;                         const float sa = -cs;
;                         const f32x2 sa2 = {sa, sa}, v2 = {vi, vi};
;                         f32x2 y0 = {0.f, 0.f}, y1 = {0.f, 0.f};
;                         SB; LDG(G2, 2) SB; CMP(G0, 0) SB;
;                         LDG(G0, 3) SB; CMP(G1, 1) SB;
;                         CMP(G2, 2) SB;
; #pragma unroll
;                         for (int j = 0; j < 8; ++j) KA[j] = *(const f32x4*)(vs + 384 + 256 + 4 * j);
;                         SB; CMP(G0, 3) SB;
;                         float ys = (y0.x + y0.y) + (y1.x + y1.y);
;                         ys += dpp_f(ys, 0);
;                         if ((lane & 1) == 0) yb[s * 64 + srow] = ys;
.LBB0_647:
.LBB0_648:
	s_andn2_saveexec_b64 s[54:55], s[54:55]
	s_cbranch_execz .LBB0_655
	s_add_i32 s56, s71, -1
	s_cmp_ge_u32 s56, s69
	s_cbranch_scc1 .LBB0_654
	s_lshl_b32 s56, s71, 1
	s_waitcnt vmcnt(0)
	v_bitop3_b32 v121, s56, 2, v67 bitop3:0x26
	v_and_b32_e32 v232, 3, v168
	v_lshlrev_b32_e32 v232, 6, v232
	v_mad_u32_u24 v232, v121, s66, v232
	v_lshrrev_b32_e32 v233, 2, v168
	v_and_b32_e32 v234, 1, v179
	v_lshlrev_b32_e32 v234, 7, v234
	v_lshl_add_u32 v234, v233, 3, v234
	v_mad_u32_u24 v233, v121, s66, v234
	v_lshl_add_u32 v234, v121, 12, v234
	v_add_u32_e32 v234, 0x18000, v234
	ds_read_b128 v[32:35], v232 offset:1024
	ds_read_b128 v[36:39], v232 offset:1040
	ds_read_b128 v[40:43], v232 offset:1056
	ds_read_b128 v[44:47], v232 offset:1072
	ds_read_b128 v[88:91], v232 offset:1280
	ds_read_b128 v[92:95], v232 offset:1296
	ds_read_b128 v[96:99], v232 offset:1312
	ds_read_b128 v[100:103], v232 offset:1328
	ds_read_b128 v[104:107], v232 offset:256
	ds_read_b128 v[108:111], v232 offset:272
	ds_read_b128 v[112:115], v232 offset:288
	ds_read_b128 v[116:119], v232 offset:304
	ds_read_b128 v[180:183], v232 offset:768
	ds_read_b128 v[184:187], v232 offset:784
	ds_read_b128 v[188:191], v232 offset:800
	ds_read_b128 v[192:195], v232 offset:816
	ds_read_b64 v[120:121], v233 offset:512
	s_waitcnt lgkmcnt(13)
	s_waitcnt lgkmcnt(13)
	v_pk_mul_f32 v[196:197], v[0:1], v[32:33]
	v_pk_mul_f32 v[200:201], v[16:17], v[32:33]
	v_pk_mul_f32 v[204:205], v[0:1], v[48:49]
	v_pk_mul_f32 v[208:209], v[16:17], v[48:49]
	v_pk_fma_f32 v[196:197], v[2:3], v[34:35], v[196:197]
	v_pk_fma_f32 v[200:201], v[18:19], v[34:35], v[200:201]
	v_pk_fma_f32 v[204:205], v[2:3], v[50:51], v[204:205]
	v_pk_fma_f32 v[208:209], v[18:19], v[50:51], v[208:209]
	ds_read_b128 v[32:35], v232 offset:2560
	ds_read_b128 v[48:51], v232 offset:0
	v_pk_fma_f32 v[196:197], v[4:5], v[36:37], v[196:197]
	v_pk_fma_f32 v[200:201], v[20:21], v[36:37], v[200:201]
	v_pk_fma_f32 v[204:205], v[4:5], v[52:53], v[204:205]
	v_pk_fma_f32 v[208:209], v[20:21], v[52:53], v[208:209]
	v_pk_fma_f32 v[196:197], v[6:7], v[38:39], v[196:197]
	v_pk_fma_f32 v[200:201], v[22:23], v[38:39], v[200:201]
	v_pk_fma_f32 v[204:205], v[6:7], v[54:55], v[204:205]
	v_pk_fma_f32 v[208:209], v[22:23], v[54:55], v[208:209]
	ds_read_b128 v[36:39], v232 offset:2576
	ds_read_b128 v[52:55], v232 offset:16
	v_pk_fma_f32 v[196:197], v[8:9], v[40:41], v[196:197]
	v_pk_fma_f32 v[200:201], v[24:25], v[40:41], v[200:201]
	v_pk_fma_f32 v[204:205], v[8:9], v[56:57], v[204:205]
	v_pk_fma_f32 v[208:209], v[24:25], v[56:57], v[208:209]
	v_pk_fma_f32 v[196:197], v[10:11], v[42:43], v[196:197]
	v_pk_fma_f32 v[200:201], v[26:27], v[42:43], v[200:201]
	v_pk_fma_f32 v[204:205], v[10:11], v[58:59], v[204:205]
	v_pk_fma_f32 v[208:209], v[26:27], v[58:59], v[208:209]
	ds_read_b128 v[40:43], v232 offset:2592
	ds_read_b128 v[56:59], v232 offset:32
	v_pk_fma_f32 v[196:197], v[12:13], v[44:45], v[196:197]
	v_pk_fma_f32 v[200:201], v[28:29], v[44:45], v[200:201]
	v_pk_fma_f32 v[204:205], v[12:13], v[60:61], v[204:205]
	v_pk_fma_f32 v[208:209], v[28:29], v[60:61], v[208:209]
	v_pk_fma_f32 v[196:197], v[14:15], v[46:47], v[196:197]
	v_pk_fma_f32 v[200:201], v[30:31], v[46:47], v[200:201]
	v_pk_fma_f32 v[204:205], v[14:15], v[62:63], v[204:205]
	v_pk_fma_f32 v[208:209], v[30:31], v[62:63], v[208:209]
	ds_read_b128 v[44:47], v232 offset:2608
	ds_read_b128 v[60:63], v232 offset:48
	v_add_f32_e32 v212, v196, v197
	v_add_f32_e32 v213, v200, v201
	v_add_f32_e32 v214, v204, v205
	v_add_f32_e32 v215, v208, v209
	v_add_f32_dpp v212, v212, v212 quad_perm:[1,0,3,2] row_mask:0xf bank_mask:0xf
	v_add_f32_dpp v213, v213, v213 quad_perm:[1,0,3,2] row_mask:0xf bank_mask:0xf
	v_add_f32_dpp v214, v214, v214 quad_perm:[1,0,3,2] row_mask:0xf bank_mask:0xf
	v_add_f32_dpp v215, v215, v215 quad_perm:[1,0,3,2] row_mask:0xf bank_mask:0xf
	v_add_f32_dpp v212, v212, v212 quad_perm:[2,3,0,1] row_mask:0xf bank_mask:0xf
	v_add_f32_dpp v213, v213, v213 quad_perm:[2,3,0,1] row_mask:0xf bank_mask:0xf
	v_add_f32_dpp v214, v214, v214 quad_perm:[2,3,0,1] row_mask:0xf bank_mask:0xf
	v_add_f32_dpp v215, v215, v215 quad_perm:[2,3,0,1] row_mask:0xf bank_mask:0xf
	s_waitcnt lgkmcnt(8)
	ds_read_b64 v[122:123], v233 offset:2048
	v_pk_mul_f32 v[216:217], v[88:89], v[212:213] op_sel_hi:[1,0] neg_lo:[0,1] neg_hi:[0,1]
	v_pk_mul_f32 v[218:219], v[90:91], v[212:213] op_sel_hi:[1,0] neg_lo:[0,1] neg_hi:[0,1]
	v_pk_mul_f32 v[220:221], v[88:89], v[212:213] op_sel:[0,1] op_sel_hi:[1,1] neg_lo:[0,1] neg_hi:[0,1]
	v_pk_mul_f32 v[222:223], v[90:91], v[212:213] op_sel:[0,1] op_sel_hi:[1,1] neg_lo:[0,1] neg_hi:[0,1]
	v_pk_fma_f32 v[216:217], v[104:105], v[120:121], v[216:217] op_sel_hi:[1,0,1]
	v_pk_fma_f32 v[218:219], v[106:107], v[120:121], v[218:219] op_sel_hi:[1,0,1]
	v_pk_fma_f32 v[220:221], v[104:105], v[120:121], v[220:221] op_sel:[0,1,0] op_sel_hi:[1,1,1]
	v_pk_fma_f32 v[222:223], v[106:107], v[120:121], v[222:223] op_sel:[0,1,0] op_sel_hi:[1,1,1]
	v_pk_fma_f32 v[0:1], v[0:1], v[180:181], v[216:217]
	v_pk_fma_f32 v[2:3], v[2:3], v[182:183], v[218:219]
	v_pk_fma_f32 v[16:17], v[16:17], v[180:181], v[220:221]
	v_pk_fma_f32 v[18:19], v[18:19], v[182:183], v[222:223]
	ds_read_b128 v[88:91], v232 offset:2816
	ds_read_b128 v[104:107], v232 offset:1792
	ds_read_b128 v[180:183], v232 offset:2304
	v_pk_mul_f32 v[224:225], v[92:93], v[212:213] op_sel_hi:[1,0] neg_lo:[0,1] neg_hi:[0,1]
	v_pk_mul_f32 v[226:227], v[94:95], v[212:213] op_sel_hi:[1,0] neg_lo:[0,1] neg_hi:[0,1]
	v_pk_mul_f32 v[228:229], v[92:93], v[212:213] op_sel:[0,1] op_sel_hi:[1,1] neg_lo:[0,1] neg_hi:[0,1]
; #define SB __builtin_amdgcn_sched_barrier(0)
; #define CMP(G, c8) { CMP1(G, 0, 2 * (c8)) CMP1(G, 1, 2 * (c8) + 1) }
; __device__ __forceinline__ void phase_scan(const Args& a, unsigned char* lds) {
;     ...
;                     f32x4 KA[8];
; #pragma unroll
;                     for (int j = 0; j < 8; ++j) KA[j] = *(const f32x4*)(vb + 256 + 4 * j);
; #pragma nounroll
;                     for (int s = 0; s < 16; ++s) {
;                         const float* vs = vb + s * 384;
;                         const float vi = vs[128 - cb + srow];
;                         f32x4 G0[8], G1[8], G2[8];
;                         LDG(G0, 0) SB;
;                         LDG(G1, 1) SB;
;                         f32x2 c0 = {0.f, 0.f}, c1 = {0.f, 0.f};
; #pragma unroll
;                         for (int j = 0; j < 8; ++j) { c0 += S2[2 * j] * (f32x2){KA[j][0], KA[j][1]}; c1 += S2[2 * j + 1] * (f32x2){KA[j][2], KA[j][3]}; }
;                         float cs = (c0.x + c0.y) + (c1.x + c1.y);
;                         cs += dpp_f(cs, 0);
;                         const float sa = -cs;
;                         const f32x2 sa2 = {sa, sa}, v2 = {vi, vi};
;                         f32x2 y0 = {0.f, 0.f}, y1 = {0.f, 0.f};
;                         SB; LDG(G2, 2) SB; CMP(G0, 0) SB;
;                         LDG(G0, 3) SB; CMP(G1, 1) SB;
;                         CMP(G2, 2) SB;
; #pragma unroll
;                         for (int j = 0; j < 8; ++j) KA[j] = *(const f32x4*)(vs + 384 + 256 + 4 * j);
;                         SB; CMP(G0, 3) SB;
;                         float ys = (y0.x + y0.y) + (y1.x + y1.y);
;                         ys += dpp_f(ys, 0);
;                         if ((lane & 1) == 0) yb[s * 64 + srow] = ys;
	v_pk_mul_f32 v[230:231], v[94:95], v[212:213] op_sel:[0,1] op_sel_hi:[1,1] neg_lo:[0,1] neg_hi:[0,1]
	v_pk_fma_f32 v[224:225], v[108:109], v[120:121], v[224:225] op_sel_hi:[1,0,1]
	v_pk_fma_f32 v[226:227], v[110:111], v[120:121], v[226:227] op_sel_hi:[1,0,1]
	v_pk_fma_f32 v[228:229], v[108:109], v[120:121], v[228:229] op_sel:[0,1,0] op_sel_hi:[1,1,1]
	v_pk_fma_f32 v[230:231], v[110:111], v[120:121], v[230:231] op_sel:[0,1,0] op_sel_hi:[1,1,1]
	v_pk_fma_f32 v[4:5], v[4:5], v[184:185], v[224:225]
	v_pk_fma_f32 v[6:7], v[6:7], v[186:187], v[226:227]
	v_pk_fma_f32 v[20:21], v[20:21], v[184:185], v[228:229]
	v_pk_fma_f32 v[22:23], v[22:23], v[186:187], v[230:231]
	ds_read_b128 v[92:95], v232 offset:2832
	ds_read_b128 v[108:111], v232 offset:1808
	ds_read_b128 v[184:187], v232 offset:2320
	v_pk_mul_f32 v[216:217], v[96:97], v[212:213] op_sel_hi:[1,0] neg_lo:[0,1] neg_hi:[0,1]
	v_pk_mul_f32 v[218:219], v[98:99], v[212:213] op_sel_hi:[1,0] neg_lo:[0,1] neg_hi:[0,1]
	v_pk_mul_f32 v[220:221], v[96:97], v[212:213] op_sel:[0,1] op_sel_hi:[1,1] neg_lo:[0,1] neg_hi:[0,1]
	v_pk_mul_f32 v[222:223], v[98:99], v[212:213] op_sel:[0,1] op_sel_hi:[1,1] neg_lo:[0,1] neg_hi:[0,1]
	v_pk_fma_f32 v[216:217], v[112:113], v[120:121], v[216:217] op_sel_hi:[1,0,1]
	v_pk_fma_f32 v[218:219], v[114:115], v[120:121], v[218:219] op_sel_hi:[1,0,1]
	v_pk_fma_f32 v[220:221], v[112:113], v[120:121], v[220:221] op_sel:[0,1,0] op_sel_hi:[1,1,1]
	v_pk_fma_f32 v[222:223], v[114:115], v[120:121], v[222:223] op_sel:[0,1,0] op_sel_hi:[1,1,1]
	v_pk_fma_f32 v[8:9], v[8:9], v[188:189], v[216:217]
	v_pk_fma_f32 v[10:11], v[10:11], v[190:191], v[218:219]
	v_pk_fma_f32 v[24:25], v[24:25], v[188:189], v[220:221]
	v_pk_fma_f32 v[26:27], v[26:27], v[190:191], v[222:223]
	ds_read_b128 v[96:99], v232 offset:2848
	ds_read_b128 v[112:115], v232 offset:1824
	ds_read_b128 v[188:191], v232 offset:2336
	v_pk_mul_f32 v[224:225], v[100:101], v[212:213] op_sel_hi:[1,0] neg_lo:[0,1] neg_hi:[0,1]
	v_pk_mul_f32 v[226:227], v[102:103], v[212:213] op_sel_hi:[1,0] neg_lo:[0,1] neg_hi:[0,1]
	v_pk_mul_f32 v[228:229], v[100:101], v[212:213] op_sel:[0,1] op_sel_hi:[1,1] neg_lo:[0,1] neg_hi:[0,1]
	v_pk_mul_f32 v[230:231], v[102:103], v[212:213] op_sel:[0,1] op_sel_hi:[1,1] neg_lo:[0,1] neg_hi:[0,1]
	v_pk_fma_f32 v[224:225], v[116:117], v[120:121], v[224:225] op_sel_hi:[1,0,1]
	v_pk_fma_f32 v[226:227], v[118:119], v[120:121], v[226:227] op_sel_hi:[1,0,1]
	v_pk_fma_f32 v[228:229], v[116:117], v[120:121], v[228:229] op_sel:[0,1,0] op_sel_hi:[1,1,1]
	v_pk_fma_f32 v[230:231], v[118:119], v[120:121], v[230:231] op_sel:[0,1,0] op_sel_hi:[1,1,1]
	v_pk_fma_f32 v[12:13], v[12:13], v[192:193], v[224:225]
	v_pk_fma_f32 v[14:15], v[14:15], v[194:195], v[226:227]
	v_pk_fma_f32 v[28:29], v[28:29], v[192:193], v[228:229]
	v_pk_fma_f32 v[30:31], v[30:31], v[194:195], v[230:231]
	ds_read_b128 v[100:103], v232 offset:2864
	ds_read_b128 v[116:119], v232 offset:1840
	ds_read_b128 v[192:195], v232 offset:2352
	s_waitcnt lgkmcnt(13)
	v_pk_mul_f32 v[196:197], v[0:1], v[32:33]
	v_pk_mul_f32 v[200:201], v[16:17], v[32:33]
	v_pk_mul_f32 v[204:205], v[0:1], v[48:49]
	v_pk_mul_f32 v[208:209], v[16:17], v[48:49]
	v_pk_fma_f32 v[196:197], v[2:3], v[34:35], v[196:197]
	v_pk_fma_f32 v[200:201], v[18:19], v[34:35], v[200:201]
	v_pk_fma_f32 v[204:205], v[2:3], v[50:51], v[204:205]
	v_pk_fma_f32 v[208:209], v[18:19], v[50:51], v[208:209]
	ds_read_b128 v[32:35], v232 offset:4096
	ds_read_b128 v[48:51], v232 offset:1536
	v_pk_fma_f32 v[196:197], v[4:5], v[36:37], v[196:197]
	v_pk_fma_f32 v[200:201], v[20:21], v[36:37], v[200:201]
	v_pk_fma_f32 v[204:205], v[4:5], v[52:53], v[204:205]
	v_pk_fma_f32 v[208:209], v[20:21], v[52:53], v[208:209]
	v_pk_fma_f32 v[196:197], v[6:7], v[38:39], v[196:197]
	v_pk_fma_f32 v[200:201], v[22:23], v[38:39], v[200:201]
	v_pk_fma_f32 v[204:205], v[6:7], v[54:55], v[204:205]
	v_pk_fma_f32 v[208:209], v[22:23], v[54:55], v[208:209]
	ds_read_b128 v[36:39], v232 offset:4112
	ds_read_b128 v[52:55], v232 offset:1552
	v_pk_fma_f32 v[196:197], v[8:9], v[40:41], v[196:197]
	v_pk_fma_f32 v[200:201], v[24:25], v[40:41], v[200:201]
	v_pk_fma_f32 v[204:205], v[8:9], v[56:57], v[204:205]
	v_pk_fma_f32 v[208:209], v[24:25], v[56:57], v[208:209]
	v_pk_fma_f32 v[196:197], v[10:11], v[42:43], v[196:197]
	v_pk_fma_f32 v[200:201], v[26:27], v[42:43], v[200:201]
	v_pk_fma_f32 v[204:205], v[10:11], v[58:59], v[204:205]
	v_pk_fma_f32 v[208:209], v[26:27], v[58:59], v[208:209]
	ds_read_b128 v[40:43], v232 offset:4128
	ds_read_b128 v[56:59], v232 offset:1568
	v_pk_fma_f32 v[196:197], v[12:13], v[44:45], v[196:197]
	v_pk_fma_f32 v[200:201], v[28:29], v[44:45], v[200:201]
	v_pk_fma_f32 v[204:205], v[12:13], v[60:61], v[204:205]
	v_pk_fma_f32 v[208:209], v[28:29], v[60:61], v[208:209]
	v_pk_fma_f32 v[196:197], v[14:15], v[46:47], v[196:197]
	v_pk_fma_f32 v[200:201], v[30:31], v[46:47], v[200:201]
	v_pk_fma_f32 v[204:205], v[14:15], v[62:63], v[204:205]
	v_pk_fma_f32 v[208:209], v[30:31], v[62:63], v[208:209]
	ds_read_b128 v[44:47], v232 offset:4144
	ds_read_b128 v[60:63], v232 offset:1584
	v_add_f32_e32 v212, v196, v197
	v_add_f32_e32 v213, v200, v201
	v_add_f32_e32 v214, v204, v205
	v_add_f32_e32 v215, v208, v209
	v_add_f32_dpp v212, v212, v212 quad_perm:[1,0,3,2] row_mask:0xf bank_mask:0xf
	v_add_f32_dpp v213, v213, v213 quad_perm:[1,0,3,2] row_mask:0xf bank_mask:0xf
	v_add_f32_dpp v214, v214, v214 quad_perm:[1,0,3,2] row_mask:0xf bank_mask:0xf
	v_add_f32_dpp v215, v215, v215 quad_perm:[1,0,3,2] row_mask:0xf bank_mask:0xf
	v_add_f32_dpp v212, v212, v212 quad_perm:[2,3,0,1] row_mask:0xf bank_mask:0xf
	v_add_f32_dpp v213, v213, v213 quad_perm:[2,3,0,1] row_mask:0xf bank_mask:0xf
	v_add_f32_dpp v214, v214, v214 quad_perm:[2,3,0,1] row_mask:0xf bank_mask:0xf
	v_add_f32_dpp v215, v215, v215 quad_perm:[2,3,0,1] row_mask:0xf bank_mask:0xf
	ds_write_b64 v234, v[214:215] offset:0
	s_waitcnt lgkmcnt(8)
	ds_read_b64 v[120:121], v233 offset:3584
	v_pk_mul_f32 v[216:217], v[88:89], v[212:213] op_sel_hi:[1,0] neg_lo:[0,1] neg_hi:[0,1]
	v_pk_mul_f32 v[218:219], v[90:91], v[212:213] op_sel_hi:[1,0] neg_lo:[0,1] neg_hi:[0,1]
	v_pk_mul_f32 v[220:221], v[88:89], v[212:213] op_sel:[0,1] op_sel_hi:[1,1] neg_lo:[0,1] neg_hi:[0,1]
	v_pk_mul_f32 v[222:223], v[90:91], v[212:213] op_sel:[0,1] op_sel_hi:[1,1] neg_lo:[0,1] neg_hi:[0,1]
	v_pk_fma_f32 v[216:217], v[104:105], v[122:123], v[216:217] op_sel_hi:[1,0,1]
	v_pk_fma_f32 v[218:219], v[106:107], v[122:123], v[218:219] op_sel_hi:[1,0,1]
	v_pk_fma_f32 v[220:221], v[104:105], v[122:123], v[220:221] op_sel:[0,1,0] op_sel_hi:[1,1,1]
	v_pk_fma_f32 v[222:223], v[106:107], v[122:123], v[222:223] op_sel:[0,1,0] op_sel_hi:[1,1,1]
	v_pk_fma_f32 v[0:1], v[0:1], v[180:181], v[216:217]
	v_pk_fma_f32 v[2:3], v[2:3], v[182:183], v[218:219]
	v_pk_fma_f32 v[16:17], v[16:17], v[180:181], v[220:221]
	v_pk_fma_f32 v[18:19], v[18:19], v[182:183], v[222:223]
	ds_read_b128 v[88:91], v232 offset:4352
	ds_read_b128 v[104:107], v232 offset:3328
	ds_read_b128 v[180:183], v232 offset:3840
	v_pk_mul_f32 v[224:225], v[92:93], v[212:213] op_sel_hi:[1,0] neg_lo:[0,1] neg_hi:[0,1]
	v_pk_mul_f32 v[226:227], v[94:95], v[212:213] op_sel_hi:[1,0] neg_lo:[0,1] neg_hi:[0,1]
	v_pk_mul_f32 v[228:229], v[92:93], v[212:213] op_sel:[0,1] op_sel_hi:[1,1] neg_lo:[0,1] neg_hi:[0,1]
	v_pk_mul_f32 v[230:231], v[94:95], v[212:213] op_sel:[0,1] op_sel_hi:[1,1] neg_lo:[0,1] neg_hi:[0,1]
	v_pk_fma_f32 v[224:225], v[108:109], v[122:123], v[224:225] op_sel_hi:[1,0,1]
	v_pk_fma_f32 v[226:227], v[110:111], v[122:123], v[226:227] op_sel_hi:[1,0,1]
	v_pk_fma_f32 v[228:229], v[108:109], v[122:123], v[228:229] op_sel:[0,1,0] op_sel_hi:[1,1,1]
	v_pk_fma_f32 v[230:231], v[110:111], v[122:123], v[230:231] op_sel:[0,1,0] op_sel_hi:[1,1,1]
	v_pk_fma_f32 v[4:5], v[4:5], v[184:185], v[224:225]
	v_pk_fma_f32 v[6:7], v[6:7], v[186:187], v[226:227]
	v_pk_fma_f32 v[20:21], v[20:21], v[184:185], v[228:229]
	v_pk_fma_f32 v[22:23], v[22:23], v[186:187], v[230:231]
	ds_read_b128 v[92:95], v232 offset:4368
	ds_read_b128 v[108:111], v232 offset:3344
	ds_read_b128 v[184:187], v232 offset:3856
	v_pk_mul_f32 v[216:217], v[96:97], v[212:213] op_sel_hi:[1,0] neg_lo:[0,1] neg_hi:[0,1]
	v_pk_mul_f32 v[218:219], v[98:99], v[212:213] op_sel_hi:[1,0] neg_lo:[0,1] neg_hi:[0,1]
	v_pk_mul_f32 v[220:221], v[96:97], v[212:213] op_sel:[0,1] op_sel_hi:[1,1] neg_lo:[0,1] neg_hi:[0,1]
	v_pk_mul_f32 v[222:223], v[98:99], v[212:213] op_sel:[0,1] op_sel_hi:[1,1] neg_lo:[0,1] neg_hi:[0,1]
	v_pk_fma_f32 v[216:217], v[112:113], v[122:123], v[216:217] op_sel_hi:[1,0,1]
	v_pk_fma_f32 v[218:219], v[114:115], v[122:123], v[218:219] op_sel_hi:[1,0,1]
	v_pk_fma_f32 v[220:221], v[112:113], v[122:123], v[220:221] op_sel:[0,1,0] op_sel_hi:[1,1,1]
	v_pk_fma_f32 v[222:223], v[114:115], v[122:123], v[222:223] op_sel:[0,1,0] op_sel_hi:[1,1,1]
	v_pk_fma_f32 v[8:9], v[8:9], v[188:189], v[216:217]
	v_pk_fma_f32 v[10:11], v[10:11], v[190:191], v[218:219]
	v_pk_fma_f32 v[24:25], v[24:25], v[188:189], v[220:221]
	v_pk_fma_f32 v[26:27], v[26:27], v[190:191], v[222:223]
	ds_read_b128 v[96:99], v232 offset:4384
	ds_read_b128 v[112:115], v232 offset:3360
	ds_read_b128 v[188:191], v232 offset:3872
	v_pk_mul_f32 v[224:225], v[100:101], v[212:213] op_sel_hi:[1,0] neg_lo:[0,1] neg_hi:[0,1]
	v_pk_mul_f32 v[226:227], v[102:103], v[212:213] op_sel_hi:[1,0] neg_lo:[0,1] neg_hi:[0,1]
	v_pk_mul_f32 v[228:229], v[100:101], v[212:213] op_sel:[0,1] op_sel_hi:[1,1] neg_lo:[0,1] neg_hi:[0,1]
	v_pk_mul_f32 v[230:231], v[102:103], v[212:213] op_sel:[0,1] op_sel_hi:[1,1] neg_lo:[0,1] neg_hi:[0,1]
	v_pk_fma_f32 v[224:225], v[116:117], v[122:123], v[224:225] op_sel_hi:[1,0,1]
	v_pk_fma_f32 v[226:227], v[118:119], v[122:123], v[226:227] op_sel_hi:[1,0,1]
	v_pk_fma_f32 v[228:229], v[116:117], v[122:123], v[228:229] op_sel:[0,1,0] op_sel_hi:[1,1,1]
	v_pk_fma_f32 v[230:231], v[118:119], v[122:123], v[230:231] op_sel:[0,1,0] op_sel_hi:[1,1,1]
	v_pk_fma_f32 v[12:13], v[12:13], v[192:193], v[224:225]
	v_pk_fma_f32 v[14:15], v[14:15], v[194:195], v[226:227]
	v_pk_fma_f32 v[28:29], v[28:29], v[192:193], v[228:229]
	v_pk_fma_f32 v[30:31], v[30:31], v[194:195], v[230:231]
	ds_read_b128 v[100:103], v232 offset:4400
	ds_read_b128 v[116:119], v232 offset:3376
	ds_read_b128 v[192:195], v232 offset:3888
	s_waitcnt lgkmcnt(13)
; #define SB __builtin_amdgcn_sched_barrier(0)
; #define CMP(G, c8) { CMP1(G, 0, 2 * (c8)) CMP1(G, 1, 2 * (c8) + 1) }
; __device__ __forceinline__ void phase_scan(const Args& a, unsigned char* lds) {
;     ...
; #pragma unroll
;                         for (int j = 0; j < 8; ++j) { c0 += S2[2 * j] * (f32x2){KA[j][0], KA[j][1]}; c1 += S2[2 * j + 1] * (f32x2){KA[j][2], KA[j][3]}; }
;                         float cs = (c0.x + c0.y) + (c1.x + c1.y);
;                         cs += dpp_f(cs, 0);
;                         const float sa = -cs;
;                         const f32x2 sa2 = {sa, sa}, v2 = {vi, vi};
;                         f32x2 y0 = {0.f, 0.f}, y1 = {0.f, 0.f};
;                         SB; LDG(G2, 2) SB; CMP(G0, 0) SB;
;                         LDG(G0, 3) SB; CMP(G1, 1) SB;
;                         CMP(G2, 2) SB;
; #pragma unroll
;                         for (int j = 0; j < 8; ++j) KA[j] = *(const f32x4*)(vs + 384 + 256 + 4 * j);
;                         SB; CMP(G0, 3) SB;
;                         float ys = (y0.x + y0.y) + (y1.x + y1.y);
;                         ys += dpp_f(ys, 0);
;                         if ((lane & 1) == 0) yb[s * 64 + srow] = ys;
	v_pk_mul_f32 v[196:197], v[0:1], v[32:33]
	v_pk_mul_f32 v[200:201], v[16:17], v[32:33]
	v_pk_mul_f32 v[204:205], v[0:1], v[48:49]
	v_pk_mul_f32 v[208:209], v[16:17], v[48:49]
	v_pk_fma_f32 v[196:197], v[2:3], v[34:35], v[196:197]
	v_pk_fma_f32 v[200:201], v[18:19], v[34:35], v[200:201]
	v_pk_fma_f32 v[204:205], v[2:3], v[50:51], v[204:205]
	v_pk_fma_f32 v[208:209], v[18:19], v[50:51], v[208:209]
	ds_read_b128 v[32:35], v232 offset:5632
	ds_read_b128 v[48:51], v232 offset:3072
	v_pk_fma_f32 v[196:197], v[4:5], v[36:37], v[196:197]
	v_pk_fma_f32 v[200:201], v[20:21], v[36:37], v[200:201]
	v_pk_fma_f32 v[204:205], v[4:5], v[52:53], v[204:205]
	v_pk_fma_f32 v[208:209], v[20:21], v[52:53], v[208:209]
	v_pk_fma_f32 v[196:197], v[6:7], v[38:39], v[196:197]
	v_pk_fma_f32 v[200:201], v[22:23], v[38:39], v[200:201]
	v_pk_fma_f32 v[204:205], v[6:7], v[54:55], v[204:205]
	v_pk_fma_f32 v[208:209], v[22:23], v[54:55], v[208:209]
	ds_read_b128 v[36:39], v232 offset:5648
	ds_read_b128 v[52:55], v232 offset:3088
	v_pk_fma_f32 v[196:197], v[8:9], v[40:41], v[196:197]
	v_pk_fma_f32 v[200:201], v[24:25], v[40:41], v[200:201]
	v_pk_fma_f32 v[204:205], v[8:9], v[56:57], v[204:205]
	v_pk_fma_f32 v[208:209], v[24:25], v[56:57], v[208:209]
	v_pk_fma_f32 v[196:197], v[10:11], v[42:43], v[196:197]
	v_pk_fma_f32 v[200:201], v[26:27], v[42:43], v[200:201]
	v_pk_fma_f32 v[204:205], v[10:11], v[58:59], v[204:205]
	v_pk_fma_f32 v[208:209], v[26:27], v[58:59], v[208:209]
	ds_read_b128 v[40:43], v232 offset:5664
	ds_read_b128 v[56:59], v232 offset:3104
	v_pk_fma_f32 v[196:197], v[12:13], v[44:45], v[196:197]
	v_pk_fma_f32 v[200:201], v[28:29], v[44:45], v[200:201]
	v_pk_fma_f32 v[204:205], v[12:13], v[60:61], v[204:205]
	v_pk_fma_f32 v[208:209], v[28:29], v[60:61], v[208:209]
	v_pk_fma_f32 v[196:197], v[14:15], v[46:47], v[196:197]
	v_pk_fma_f32 v[200:201], v[30:31], v[46:47], v[200:201]
	v_pk_fma_f32 v[204:205], v[14:15], v[62:63], v[204:205]
	v_pk_fma_f32 v[208:209], v[30:31], v[62:63], v[208:209]
	ds_read_b128 v[44:47], v232 offset:5680
	ds_read_b128 v[60:63], v232 offset:3120
	v_add_f32_e32 v212, v196, v197
	v_add_f32_e32 v213, v200, v201
	v_add_f32_e32 v214, v204, v205
	v_add_f32_e32 v215, v208, v209
	v_add_f32_dpp v212, v212, v212 quad_perm:[1,0,3,2] row_mask:0xf bank_mask:0xf
	v_add_f32_dpp v213, v213, v213 quad_perm:[1,0,3,2] row_mask:0xf bank_mask:0xf
	v_add_f32_dpp v214, v214, v214 quad_perm:[1,0,3,2] row_mask:0xf bank_mask:0xf
	v_add_f32_dpp v215, v215, v215 quad_perm:[1,0,3,2] row_mask:0xf bank_mask:0xf
	v_add_f32_dpp v212, v212, v212 quad_perm:[2,3,0,1] row_mask:0xf bank_mask:0xf
	v_add_f32_dpp v213, v213, v213 quad_perm:[2,3,0,1] row_mask:0xf bank_mask:0xf
	v_add_f32_dpp v214, v214, v214 quad_perm:[2,3,0,1] row_mask:0xf bank_mask:0xf
	v_add_f32_dpp v215, v215, v215 quad_perm:[2,3,0,1] row_mask:0xf bank_mask:0xf
	ds_write_b64 v234, v[214:215] offset:256
	s_waitcnt lgkmcnt(8)
	ds_read_b64 v[122:123], v233 offset:5120
	v_pk_mul_f32 v[216:217], v[88:89], v[212:213] op_sel_hi:[1,0] neg_lo:[0,1] neg_hi:[0,1]
	v_pk_mul_f32 v[218:219], v[90:91], v[212:213] op_sel_hi:[1,0] neg_lo:[0,1] neg_hi:[0,1]
	v_pk_mul_f32 v[220:221], v[88:89], v[212:213] op_sel:[0,1] op_sel_hi:[1,1] neg_lo:[0,1] neg_hi:[0,1]
	v_pk_mul_f32 v[222:223], v[90:91], v[212:213] op_sel:[0,1] op_sel_hi:[1,1] neg_lo:[0,1] neg_hi:[0,1]
	v_pk_fma_f32 v[216:217], v[104:105], v[120:121], v[216:217] op_sel_hi:[1,0,1]
	v_pk_fma_f32 v[218:219], v[106:107], v[120:121], v[218:219] op_sel_hi:[1,0,1]
	v_pk_fma_f32 v[220:221], v[104:105], v[120:121], v[220:221] op_sel:[0,1,0] op_sel_hi:[1,1,1]
	v_pk_fma_f32 v[222:223], v[106:107], v[120:121], v[222:223] op_sel:[0,1,0] op_sel_hi:[1,1,1]
	v_pk_fma_f32 v[0:1], v[0:1], v[180:181], v[216:217]
	v_pk_fma_f32 v[2:3], v[2:3], v[182:183], v[218:219]
	v_pk_fma_f32 v[16:17], v[16:17], v[180:181], v[220:221]
	v_pk_fma_f32 v[18:19], v[18:19], v[182:183], v[222:223]
	ds_read_b128 v[88:91], v232 offset:5888
	ds_read_b128 v[104:107], v232 offset:4864
	ds_read_b128 v[180:183], v232 offset:5376
	v_pk_mul_f32 v[224:225], v[92:93], v[212:213] op_sel_hi:[1,0] neg_lo:[0,1] neg_hi:[0,1]
	v_pk_mul_f32 v[226:227], v[94:95], v[212:213] op_sel_hi:[1,0] neg_lo:[0,1] neg_hi:[0,1]
	v_pk_mul_f32 v[228:229], v[92:93], v[212:213] op_sel:[0,1] op_sel_hi:[1,1] neg_lo:[0,1] neg_hi:[0,1]
	v_pk_mul_f32 v[230:231], v[94:95], v[212:213] op_sel:[0,1] op_sel_hi:[1,1] neg_lo:[0,1] neg_hi:[0,1]
	v_pk_fma_f32 v[224:225], v[108:109], v[120:121], v[224:225] op_sel_hi:[1,0,1]
	v_pk_fma_f32 v[226:227], v[110:111], v[120:121], v[226:227] op_sel_hi:[1,0,1]
	v_pk_fma_f32 v[228:229], v[108:109], v[120:121], v[228:229] op_sel:[0,1,0] op_sel_hi:[1,1,1]
	v_pk_fma_f32 v[230:231], v[110:111], v[120:121], v[230:231] op_sel:[0,1,0] op_sel_hi:[1,1,1]
	v_pk_fma_f32 v[4:5], v[4:5], v[184:185], v[224:225]
	v_pk_fma_f32 v[6:7], v[6:7], v[186:187], v[226:227]
	v_pk_fma_f32 v[20:21], v[20:21], v[184:185], v[228:229]
	v_pk_fma_f32 v[22:23], v[22:23], v[186:187], v[230:231]
	ds_read_b128 v[92:95], v232 offset:5904
	ds_read_b128 v[108:111], v232 offset:4880
	ds_read_b128 v[184:187], v232 offset:5392
	v_pk_mul_f32 v[216:217], v[96:97], v[212:213] op_sel_hi:[1,0] neg_lo:[0,1] neg_hi:[0,1]
	v_pk_mul_f32 v[218:219], v[98:99], v[212:213] op_sel_hi:[1,0] neg_lo:[0,1] neg_hi:[0,1]
	v_pk_mul_f32 v[220:221], v[96:97], v[212:213] op_sel:[0,1] op_sel_hi:[1,1] neg_lo:[0,1] neg_hi:[0,1]
	v_pk_mul_f32 v[222:223], v[98:99], v[212:213] op_sel:[0,1] op_sel_hi:[1,1] neg_lo:[0,1] neg_hi:[0,1]
	v_pk_fma_f32 v[216:217], v[112:113], v[120:121], v[216:217] op_sel_hi:[1,0,1]
	v_pk_fma_f32 v[218:219], v[114:115], v[120:121], v[218:219] op_sel_hi:[1,0,1]
; #define SB __builtin_amdgcn_sched_barrier(0)
; #define CMP(G, c8) { CMP1(G, 0, 2 * (c8)) CMP1(G, 1, 2 * (c8) + 1) }
; __device__ __forceinline__ void phase_scan(const Args& a, unsigned char* lds) {
;     ...
;                     f32x4 KA[8];
; #pragma unroll
;                     for (int j = 0; j < 8; ++j) KA[j] = *(const f32x4*)(vb + 256 + 4 * j);
; #pragma nounroll
;                     for (int s = 0; s < 16; ++s) {
;                         const float* vs = vb + s * 384;
;                         const float vi = vs[128 - cb + srow];
;                         f32x4 G0[8], G1[8], G2[8];
;                         LDG(G0, 0) SB;
;                         LDG(G1, 1) SB;
;                         f32x2 c0 = {0.f, 0.f}, c1 = {0.f, 0.f};
; #pragma unroll
;                         for (int j = 0; j < 8; ++j) { c0 += S2[2 * j] * (f32x2){KA[j][0], KA[j][1]}; c1 += S2[2 * j + 1] * (f32x2){KA[j][2], KA[j][3]}; }
;                         float cs = (c0.x + c0.y) + (c1.x + c1.y);
;                         cs += dpp_f(cs, 0);
;                         const float sa = -cs;
;                         const f32x2 sa2 = {sa, sa}, v2 = {vi, vi};
;                         f32x2 y0 = {0.f, 0.f}, y1 = {0.f, 0.f};
;                         SB; LDG(G2, 2) SB; CMP(G0, 0) SB;
;                         LDG(G0, 3) SB; CMP(G1, 1) SB;
;                         CMP(G2, 2) SB;
; #pragma unroll
;                         for (int j = 0; j < 8; ++j) KA[j] = *(const f32x4*)(vs + 384 + 256 + 4 * j);
;                         SB; CMP(G0, 3) SB;
;                         float ys = (y0.x + y0.y) + (y1.x + y1.y);
;                         ys += dpp_f(ys, 0);
;                         if ((lane & 1) == 0) yb[s * 64 + srow] = ys;
	v_pk_fma_f32 v[220:221], v[112:113], v[120:121], v[220:221] op_sel:[0,1,0] op_sel_hi:[1,1,1]
	v_pk_fma_f32 v[222:223], v[114:115], v[120:121], v[222:223] op_sel:[0,1,0] op_sel_hi:[1,1,1]
	v_pk_fma_f32 v[8:9], v[8:9], v[188:189], v[216:217]
	v_pk_fma_f32 v[10:11], v[10:11], v[190:191], v[218:219]
	v_pk_fma_f32 v[24:25], v[24:25], v[188:189], v[220:221]
	v_pk_fma_f32 v[26:27], v[26:27], v[190:191], v[222:223]
	ds_read_b128 v[96:99], v232 offset:5920
	ds_read_b128 v[112:115], v232 offset:4896
	ds_read_b128 v[188:191], v232 offset:5408
	v_pk_mul_f32 v[224:225], v[100:101], v[212:213] op_sel_hi:[1,0] neg_lo:[0,1] neg_hi:[0,1]
	v_pk_mul_f32 v[226:227], v[102:103], v[212:213] op_sel_hi:[1,0] neg_lo:[0,1] neg_hi:[0,1]
	v_pk_mul_f32 v[228:229], v[100:101], v[212:213] op_sel:[0,1] op_sel_hi:[1,1] neg_lo:[0,1] neg_hi:[0,1]
	v_pk_mul_f32 v[230:231], v[102:103], v[212:213] op_sel:[0,1] op_sel_hi:[1,1] neg_lo:[0,1] neg_hi:[0,1]
	v_pk_fma_f32 v[224:225], v[116:117], v[120:121], v[224:225] op_sel_hi:[1,0,1]
	v_pk_fma_f32 v[226:227], v[118:119], v[120:121], v[226:227] op_sel_hi:[1,0,1]
	v_pk_fma_f32 v[228:229], v[116:117], v[120:121], v[228:229] op_sel:[0,1,0] op_sel_hi:[1,1,1]
	v_pk_fma_f32 v[230:231], v[118:119], v[120:121], v[230:231] op_sel:[0,1,0] op_sel_hi:[1,1,1]
	v_pk_fma_f32 v[12:13], v[12:13], v[192:193], v[224:225]
	v_pk_fma_f32 v[14:15], v[14:15], v[194:195], v[226:227]
	v_pk_fma_f32 v[28:29], v[28:29], v[192:193], v[228:229]
	v_pk_fma_f32 v[30:31], v[30:31], v[194:195], v[230:231]
	ds_read_b128 v[100:103], v232 offset:5936
	ds_read_b128 v[116:119], v232 offset:4912
	ds_read_b128 v[192:195], v232 offset:5424
	s_waitcnt lgkmcnt(13)
	v_pk_mul_f32 v[196:197], v[0:1], v[32:33]
	v_pk_mul_f32 v[200:201], v[16:17], v[32:33]
	v_pk_mul_f32 v[204:205], v[0:1], v[48:49]
	v_pk_mul_f32 v[208:209], v[16:17], v[48:49]
	v_pk_fma_f32 v[196:197], v[2:3], v[34:35], v[196:197]
	v_pk_fma_f32 v[200:201], v[18:19], v[34:35], v[200:201]
	v_pk_fma_f32 v[204:205], v[2:3], v[50:51], v[204:205]
	v_pk_fma_f32 v[208:209], v[18:19], v[50:51], v[208:209]
	ds_read_b128 v[32:35], v232 offset:7168
	ds_read_b128 v[48:51], v232 offset:4608
	v_pk_fma_f32 v[196:197], v[4:5], v[36:37], v[196:197]
	v_pk_fma_f32 v[200:201], v[20:21], v[36:37], v[200:201]
	v_pk_fma_f32 v[204:205], v[4:5], v[52:53], v[204:205]
	v_pk_fma_f32 v[208:209], v[20:21], v[52:53], v[208:209]
	v_pk_fma_f32 v[196:197], v[6:7], v[38:39], v[196:197]
	v_pk_fma_f32 v[200:201], v[22:23], v[38:39], v[200:201]
	v_pk_fma_f32 v[204:205], v[6:7], v[54:55], v[204:205]
	v_pk_fma_f32 v[208:209], v[22:23], v[54:55], v[208:209]
	ds_read_b128 v[36:39], v232 offset:7184
	ds_read_b128 v[52:55], v232 offset:4624
	v_pk_fma_f32 v[196:197], v[8:9], v[40:41], v[196:197]
	v_pk_fma_f32 v[200:201], v[24:25], v[40:41], v[200:201]
	v_pk_fma_f32 v[204:205], v[8:9], v[56:57], v[204:205]
	v_pk_fma_f32 v[208:209], v[24:25], v[56:57], v[208:209]
	v_pk_fma_f32 v[196:197], v[10:11], v[42:43], v[196:197]
	v_pk_fma_f32 v[200:201], v[26:27], v[42:43], v[200:201]
	v_pk_fma_f32 v[204:205], v[10:11], v[58:59], v[204:205]
	v_pk_fma_f32 v[208:209], v[26:27], v[58:59], v[208:209]
	ds_read_b128 v[40:43], v232 offset:7200
	ds_read_b128 v[56:59], v232 offset:4640
	v_pk_fma_f32 v[196:197], v[12:13], v[44:45], v[196:197]
	v_pk_fma_f32 v[200:201], v[28:29], v[44:45], v[200:201]
	v_pk_fma_f32 v[204:205], v[12:13], v[60:61], v[204:205]
	v_pk_fma_f32 v[208:209], v[28:29], v[60:61], v[208:209]
	v_pk_fma_f32 v[196:197], v[14:15], v[46:47], v[196:197]
	v_pk_fma_f32 v[200:201], v[30:31], v[46:47], v[200:201]
	v_pk_fma_f32 v[204:205], v[14:15], v[62:63], v[204:205]
	v_pk_fma_f32 v[208:209], v[30:31], v[62:63], v[208:209]
	ds_read_b128 v[44:47], v232 offset:7216
	ds_read_b128 v[60:63], v232 offset:4656
	v_add_f32_e32 v212, v196, v197
	v_add_f32_e32 v213, v200, v201
	v_add_f32_e32 v214, v204, v205
	v_add_f32_e32 v215, v208, v209
	v_add_f32_dpp v212, v212, v212 quad_perm:[1,0,3,2] row_mask:0xf bank_mask:0xf
	v_add_f32_dpp v213, v213, v213 quad_perm:[1,0,3,2] row_mask:0xf bank_mask:0xf
	v_add_f32_dpp v214, v214, v214 quad_perm:[1,0,3,2] row_mask:0xf bank_mask:0xf
	v_add_f32_dpp v215, v215, v215 quad_perm:[1,0,3,2] row_mask:0xf bank_mask:0xf
	v_add_f32_dpp v212, v212, v212 quad_perm:[2,3,0,1] row_mask:0xf bank_mask:0xf
	v_add_f32_dpp v213, v213, v213 quad_perm:[2,3,0,1] row_mask:0xf bank_mask:0xf
	v_add_f32_dpp v214, v214, v214 quad_perm:[2,3,0,1] row_mask:0xf bank_mask:0xf
	v_add_f32_dpp v215, v215, v215 quad_perm:[2,3,0,1] row_mask:0xf bank_mask:0xf
	ds_write_b64 v234, v[214:215] offset:512
	s_waitcnt lgkmcnt(8)
; #define SB __builtin_amdgcn_sched_barrier(0)
; #define CMP(G, c8) { CMP1(G, 0, 2 * (c8)) CMP1(G, 1, 2 * (c8) + 1) }
; __device__ __forceinline__ void phase_scan(const Args& a, unsigned char* lds) {
;     ...
;                     f32x4 KA[8];
; #pragma unroll
;                     for (int j = 0; j < 8; ++j) KA[j] = *(const f32x4*)(vb + 256 + 4 * j);
; #pragma nounroll
;                     for (int s = 0; s < 16; ++s) {
;                         const float* vs = vb + s * 384;
;                         const float vi = vs[128 - cb + srow];
;                         f32x4 G0[8], G1[8], G2[8];
;                         LDG(G0, 0) SB;
;                         LDG(G1, 1) SB;
;                         f32x2 c0 = {0.f, 0.f}, c1 = {0.f, 0.f};
; #pragma unroll
;                         for (int j = 0; j < 8; ++j) { c0 += S2[2 * j] * (f32x2){KA[j][0], KA[j][1]}; c1 += S2[2 * j + 1] * (f32x2){KA[j][2], KA[j][3]}; }
;                         float cs = (c0.x + c0.y) + (c1.x + c1.y);
;                         cs += dpp_f(cs, 0);
;                         const float sa = -cs;
;                         const f32x2 sa2 = {sa, sa}, v2 = {vi, vi};
;                         f32x2 y0 = {0.f, 0.f}, y1 = {0.f, 0.f};
;                         SB; LDG(G2, 2) SB; CMP(G0, 0) SB;
;                         LDG(G0, 3) SB; CMP(G1, 1) SB;
;                         CMP(G2, 2) SB;
; #pragma unroll
;                         for (int j = 0; j < 8; ++j) KA[j] = *(const f32x4*)(vs + 384 + 256 + 4 * j);
;                         SB; CMP(G0, 3) SB;
;                         float ys = (y0.x + y0.y) + (y1.x + y1.y);
;                         ys += dpp_f(ys, 0);
;                         if ((lane & 1) == 0) yb[s * 64 + srow] = ys;
	ds_read_b64 v[120:121], v233 offset:6656
	v_pk_mul_f32 v[216:217], v[88:89], v[212:213] op_sel_hi:[1,0] neg_lo:[0,1] neg_hi:[0,1]
	v_pk_mul_f32 v[218:219], v[90:91], v[212:213] op_sel_hi:[1,0] neg_lo:[0,1] neg_hi:[0,1]
	v_pk_mul_f32 v[220:221], v[88:89], v[212:213] op_sel:[0,1] op_sel_hi:[1,1] neg_lo:[0,1] neg_hi:[0,1]
	v_pk_mul_f32 v[222:223], v[90:91], v[212:213] op_sel:[0,1] op_sel_hi:[1,1] neg_lo:[0,1] neg_hi:[0,1]
	v_pk_fma_f32 v[216:217], v[104:105], v[122:123], v[216:217] op_sel_hi:[1,0,1]
	v_pk_fma_f32 v[218:219], v[106:107], v[122:123], v[218:219] op_sel_hi:[1,0,1]
	v_pk_fma_f32 v[220:221], v[104:105], v[122:123], v[220:221] op_sel:[0,1,0] op_sel_hi:[1,1,1]
	v_pk_fma_f32 v[222:223], v[106:107], v[122:123], v[222:223] op_sel:[0,1,0] op_sel_hi:[1,1,1]
	v_pk_fma_f32 v[0:1], v[0:1], v[180:181], v[216:217]
	v_pk_fma_f32 v[2:3], v[2:3], v[182:183], v[218:219]
	v_pk_fma_f32 v[16:17], v[16:17], v[180:181], v[220:221]
	v_pk_fma_f32 v[18:19], v[18:19], v[182:183], v[222:223]
	ds_read_b128 v[88:91], v232 offset:7424
	ds_read_b128 v[104:107], v232 offset:6400
	ds_read_b128 v[180:183], v232 offset:6912
	v_pk_mul_f32 v[224:225], v[92:93], v[212:213] op_sel_hi:[1,0] neg_lo:[0,1] neg_hi:[0,1]
	v_pk_mul_f32 v[226:227], v[94:95], v[212:213] op_sel_hi:[1,0] neg_lo:[0,1] neg_hi:[0,1]
	v_pk_mul_f32 v[228:229], v[92:93], v[212:213] op_sel:[0,1] op_sel_hi:[1,1] neg_lo:[0,1] neg_hi:[0,1]
	v_pk_mul_f32 v[230:231], v[94:95], v[212:213] op_sel:[0,1] op_sel_hi:[1,1] neg_lo:[0,1] neg_hi:[0,1]
	v_pk_fma_f32 v[224:225], v[108:109], v[122:123], v[224:225] op_sel_hi:[1,0,1]
	v_pk_fma_f32 v[226:227], v[110:111], v[122:123], v[226:227] op_sel_hi:[1,0,1]
	v_pk_fma_f32 v[228:229], v[108:109], v[122:123], v[228:229] op_sel:[0,1,0] op_sel_hi:[1,1,1]
	v_pk_fma_f32 v[230:231], v[110:111], v[122:123], v[230:231] op_sel:[0,1,0] op_sel_hi:[1,1,1]
	v_pk_fma_f32 v[4:5], v[4:5], v[184:185], v[224:225]
	v_pk_fma_f32 v[6:7], v[6:7], v[186:187], v[226:227]
	v_pk_fma_f32 v[20:21], v[20:21], v[184:185], v[228:229]
	v_pk_fma_f32 v[22:23], v[22:23], v[186:187], v[230:231]
	ds_read_b128 v[92:95], v232 offset:7440
	ds_read_b128 v[108:111], v232 offset:6416
	ds_read_b128 v[184:187], v232 offset:6928
	v_pk_mul_f32 v[216:217], v[96:97], v[212:213] op_sel_hi:[1,0] neg_lo:[0,1] neg_hi:[0,1]
	v_pk_mul_f32 v[218:219], v[98:99], v[212:213] op_sel_hi:[1,0] neg_lo:[0,1] neg_hi:[0,1]
	v_pk_mul_f32 v[220:221], v[96:97], v[212:213] op_sel:[0,1] op_sel_hi:[1,1] neg_lo:[0,1] neg_hi:[0,1]
	v_pk_mul_f32 v[222:223], v[98:99], v[212:213] op_sel:[0,1] op_sel_hi:[1,1] neg_lo:[0,1] neg_hi:[0,1]
	v_pk_fma_f32 v[216:217], v[112:113], v[122:123], v[216:217] op_sel_hi:[1,0,1]
	v_pk_fma_f32 v[218:219], v[114:115], v[122:123], v[218:219] op_sel_hi:[1,0,1]
	v_pk_fma_f32 v[220:221], v[112:113], v[122:123], v[220:221] op_sel:[0,1,0] op_sel_hi:[1,1,1]
	v_pk_fma_f32 v[222:223], v[114:115], v[122:123], v[222:223] op_sel:[0,1,0] op_sel_hi:[1,1,1]
	v_pk_fma_f32 v[8:9], v[8:9], v[188:189], v[216:217]
	v_pk_fma_f32 v[10:11], v[10:11], v[190:191], v[218:219]
	v_pk_fma_f32 v[24:25], v[24:25], v[188:189], v[220:221]
	v_pk_fma_f32 v[26:27], v[26:27], v[190:191], v[222:223]
	ds_read_b128 v[96:99], v232 offset:7456
	ds_read_b128 v[112:115], v232 offset:6432
	ds_read_b128 v[188:191], v232 offset:6944
	v_pk_mul_f32 v[224:225], v[100:101], v[212:213] op_sel_hi:[1,0] neg_lo:[0,1] neg_hi:[0,1]
	v_pk_mul_f32 v[226:227], v[102:103], v[212:213] op_sel_hi:[1,0] neg_lo:[0,1] neg_hi:[0,1]
	v_pk_mul_f32 v[228:229], v[100:101], v[212:213] op_sel:[0,1] op_sel_hi:[1,1] neg_lo:[0,1] neg_hi:[0,1]
	v_pk_mul_f32 v[230:231], v[102:103], v[212:213] op_sel:[0,1] op_sel_hi:[1,1] neg_lo:[0,1] neg_hi:[0,1]
	v_pk_fma_f32 v[224:225], v[116:117], v[122:123], v[224:225] op_sel_hi:[1,0,1]
	v_pk_fma_f32 v[226:227], v[118:119], v[122:123], v[226:227] op_sel_hi:[1,0,1]
	v_pk_fma_f32 v[228:229], v[116:117], v[122:123], v[228:229] op_sel:[0,1,0] op_sel_hi:[1,1,1]
	v_pk_fma_f32 v[230:231], v[118:119], v[122:123], v[230:231] op_sel:[0,1,0] op_sel_hi:[1,1,1]
	v_pk_fma_f32 v[12:13], v[12:13], v[192:193], v[224:225]
	v_pk_fma_f32 v[14:15], v[14:15], v[194:195], v[226:227]
	v_pk_fma_f32 v[28:29], v[28:29], v[192:193], v[228:229]
	v_pk_fma_f32 v[30:31], v[30:31], v[194:195], v[230:231]
	ds_read_b128 v[100:103], v232 offset:7472
	ds_read_b128 v[116:119], v232 offset:6448
	ds_read_b128 v[192:195], v232 offset:6960
	s_waitcnt lgkmcnt(13)
; #define SB __builtin_amdgcn_sched_barrier(0)
; #define CMP(G, c8) { CMP1(G, 0, 2 * (c8)) CMP1(G, 1, 2 * (c8) + 1) }
; __device__ __forceinline__ void phase_scan(const Args& a, unsigned char* lds) {
;     ...
;                     f32x4 KA[8];
; #pragma unroll
;                     for (int j = 0; j < 8; ++j) KA[j] = *(const f32x4*)(vb + 256 + 4 * j);
; #pragma nounroll
;                     for (int s = 0; s < 16; ++s) {
;                         const float* vs = vb + s * 384;
;                         const float vi = vs[128 - cb + srow];
;                         f32x4 G0[8], G1[8], G2[8];
;                         LDG(G0, 0) SB;
;                         LDG(G1, 1) SB;
;                         f32x2 c0 = {0.f, 0.f}, c1 = {0.f, 0.f};
; #pragma unroll
;                         for (int j = 0; j < 8; ++j) { c0 += S2[2 * j] * (f32x2){KA[j][0], KA[j][1]}; c1 += S2[2 * j + 1] * (f32x2){KA[j][2], KA[j][3]}; }
;                         float cs = (c0.x + c0.y) + (c1.x + c1.y);
;                         cs += dpp_f(cs, 0);
;                         const float sa = -cs;
;                         const f32x2 sa2 = {sa, sa}, v2 = {vi, vi};
;                         f32x2 y0 = {0.f, 0.f}, y1 = {0.f, 0.f};
;                         SB; LDG(G2, 2) SB; CMP(G0, 0) SB;
;                         LDG(G0, 3) SB; CMP(G1, 1) SB;
;                         CMP(G2, 2) SB;
; #pragma unroll
;                         for (int j = 0; j < 8; ++j) KA[j] = *(const f32x4*)(vs + 384 + 256 + 4 * j);
;                         SB; CMP(G0, 3) SB;
;                         float ys = (y0.x + y0.y) + (y1.x + y1.y);
;                         ys += dpp_f(ys, 0);
;                         if ((lane & 1) == 0) yb[s * 64 + srow] = ys;
	v_pk_mul_f32 v[196:197], v[0:1], v[32:33]
	v_pk_mul_f32 v[200:201], v[16:17], v[32:33]
	v_pk_mul_f32 v[204:205], v[0:1], v[48:49]
	v_pk_mul_f32 v[208:209], v[16:17], v[48:49]
	v_pk_fma_f32 v[196:197], v[2:3], v[34:35], v[196:197]
	v_pk_fma_f32 v[200:201], v[18:19], v[34:35], v[200:201]
	v_pk_fma_f32 v[204:205], v[2:3], v[50:51], v[204:205]
	v_pk_fma_f32 v[208:209], v[18:19], v[50:51], v[208:209]
	ds_read_b128 v[32:35], v232 offset:8704
	ds_read_b128 v[48:51], v232 offset:6144
	v_pk_fma_f32 v[196:197], v[4:5], v[36:37], v[196:197]
	v_pk_fma_f32 v[200:201], v[20:21], v[36:37], v[200:201]
	v_pk_fma_f32 v[204:205], v[4:5], v[52:53], v[204:205]
	v_pk_fma_f32 v[208:209], v[20:21], v[52:53], v[208:209]
	v_pk_fma_f32 v[196:197], v[6:7], v[38:39], v[196:197]
	v_pk_fma_f32 v[200:201], v[22:23], v[38:39], v[200:201]
	v_pk_fma_f32 v[204:205], v[6:7], v[54:55], v[204:205]
	v_pk_fma_f32 v[208:209], v[22:23], v[54:55], v[208:209]
	ds_read_b128 v[36:39], v232 offset:8720
	ds_read_b128 v[52:55], v232 offset:6160
	v_pk_fma_f32 v[196:197], v[8:9], v[40:41], v[196:197]
	v_pk_fma_f32 v[200:201], v[24:25], v[40:41], v[200:201]
	v_pk_fma_f32 v[204:205], v[8:9], v[56:57], v[204:205]
	v_pk_fma_f32 v[208:209], v[24:25], v[56:57], v[208:209]
	v_pk_fma_f32 v[196:197], v[10:11], v[42:43], v[196:197]
	v_pk_fma_f32 v[200:201], v[26:27], v[42:43], v[200:201]
	v_pk_fma_f32 v[204:205], v[10:11], v[58:59], v[204:205]
	v_pk_fma_f32 v[208:209], v[26:27], v[58:59], v[208:209]
	ds_read_b128 v[40:43], v232 offset:8736
	ds_read_b128 v[56:59], v232 offset:6176
	v_pk_fma_f32 v[196:197], v[12:13], v[44:45], v[196:197]
	v_pk_fma_f32 v[200:201], v[28:29], v[44:45], v[200:201]
	v_pk_fma_f32 v[204:205], v[12:13], v[60:61], v[204:205]
	v_pk_fma_f32 v[208:209], v[28:29], v[60:61], v[208:209]
	v_pk_fma_f32 v[196:197], v[14:15], v[46:47], v[196:197]
	v_pk_fma_f32 v[200:201], v[30:31], v[46:47], v[200:201]
	v_pk_fma_f32 v[204:205], v[14:15], v[62:63], v[204:205]
	v_pk_fma_f32 v[208:209], v[30:31], v[62:63], v[208:209]
	ds_read_b128 v[44:47], v232 offset:8752
	ds_read_b128 v[60:63], v232 offset:6192
	v_add_f32_e32 v212, v196, v197
	v_add_f32_e32 v213, v200, v201
	v_add_f32_e32 v214, v204, v205
	v_add_f32_e32 v215, v208, v209
	v_add_f32_dpp v212, v212, v212 quad_perm:[1,0,3,2] row_mask:0xf bank_mask:0xf
	v_add_f32_dpp v213, v213, v213 quad_perm:[1,0,3,2] row_mask:0xf bank_mask:0xf
	v_add_f32_dpp v214, v214, v214 quad_perm:[1,0,3,2] row_mask:0xf bank_mask:0xf
	v_add_f32_dpp v215, v215, v215 quad_perm:[1,0,3,2] row_mask:0xf bank_mask:0xf
	v_add_f32_dpp v212, v212, v212 quad_perm:[2,3,0,1] row_mask:0xf bank_mask:0xf
	v_add_f32_dpp v213, v213, v213 quad_perm:[2,3,0,1] row_mask:0xf bank_mask:0xf
	v_add_f32_dpp v214, v214, v214 quad_perm:[2,3,0,1] row_mask:0xf bank_mask:0xf
	v_add_f32_dpp v215, v215, v215 quad_perm:[2,3,0,1] row_mask:0xf bank_mask:0xf
	ds_write_b64 v234, v[214:215] offset:768
	s_waitcnt lgkmcnt(8)
	ds_read_b64 v[122:123], v233 offset:8192
	v_pk_mul_f32 v[216:217], v[88:89], v[212:213] op_sel_hi:[1,0] neg_lo:[0,1] neg_hi:[0,1]
	v_pk_mul_f32 v[218:219], v[90:91], v[212:213] op_sel_hi:[1,0] neg_lo:[0,1] neg_hi:[0,1]
	v_pk_mul_f32 v[220:221], v[88:89], v[212:213] op_sel:[0,1] op_sel_hi:[1,1] neg_lo:[0,1] neg_hi:[0,1]
	v_pk_mul_f32 v[222:223], v[90:91], v[212:213] op_sel:[0,1] op_sel_hi:[1,1] neg_lo:[0,1] neg_hi:[0,1]
	v_pk_fma_f32 v[216:217], v[104:105], v[120:121], v[216:217] op_sel_hi:[1,0,1]
	v_pk_fma_f32 v[218:219], v[106:107], v[120:121], v[218:219] op_sel_hi:[1,0,1]
	v_pk_fma_f32 v[220:221], v[104:105], v[120:121], v[220:221] op_sel:[0,1,0] op_sel_hi:[1,1,1]
	v_pk_fma_f32 v[222:223], v[106:107], v[120:121], v[222:223] op_sel:[0,1,0] op_sel_hi:[1,1,1]
	v_pk_fma_f32 v[0:1], v[0:1], v[180:181], v[216:217]
	v_pk_fma_f32 v[2:3], v[2:3], v[182:183], v[218:219]
	v_pk_fma_f32 v[16:17], v[16:17], v[180:181], v[220:221]
	v_pk_fma_f32 v[18:19], v[18:19], v[182:183], v[222:223]
	ds_read_b128 v[88:91], v232 offset:8960
	ds_read_b128 v[104:107], v232 offset:7936
	ds_read_b128 v[180:183], v232 offset:8448
	v_pk_mul_f32 v[224:225], v[92:93], v[212:213] op_sel_hi:[1,0] neg_lo:[0,1] neg_hi:[0,1]
	v_pk_mul_f32 v[226:227], v[94:95], v[212:213] op_sel_hi:[1,0] neg_lo:[0,1] neg_hi:[0,1]
	v_pk_mul_f32 v[228:229], v[92:93], v[212:213] op_sel:[0,1] op_sel_hi:[1,1] neg_lo:[0,1] neg_hi:[0,1]
	v_pk_mul_f32 v[230:231], v[94:95], v[212:213] op_sel:[0,1] op_sel_hi:[1,1] neg_lo:[0,1] neg_hi:[0,1]
	v_pk_fma_f32 v[224:225], v[108:109], v[120:121], v[224:225] op_sel_hi:[1,0,1]
	v_pk_fma_f32 v[226:227], v[110:111], v[120:121], v[226:227] op_sel_hi:[1,0,1]
	v_pk_fma_f32 v[228:229], v[108:109], v[120:121], v[228:229] op_sel:[0,1,0] op_sel_hi:[1,1,1]
	v_pk_fma_f32 v[230:231], v[110:111], v[120:121], v[230:231] op_sel:[0,1,0] op_sel_hi:[1,1,1]
	v_pk_fma_f32 v[4:5], v[4:5], v[184:185], v[224:225]
	v_pk_fma_f32 v[6:7], v[6:7], v[186:187], v[226:227]
	v_pk_fma_f32 v[20:21], v[20:21], v[184:185], v[228:229]
	v_pk_fma_f32 v[22:23], v[22:23], v[186:187], v[230:231]
	ds_read_b128 v[92:95], v232 offset:8976
	ds_read_b128 v[108:111], v232 offset:7952
	ds_read_b128 v[184:187], v232 offset:8464
	v_pk_mul_f32 v[216:217], v[96:97], v[212:213] op_sel_hi:[1,0] neg_lo:[0,1] neg_hi:[0,1]
	v_pk_mul_f32 v[218:219], v[98:99], v[212:213] op_sel_hi:[1,0] neg_lo:[0,1] neg_hi:[0,1]
	v_pk_mul_f32 v[220:221], v[96:97], v[212:213] op_sel:[0,1] op_sel_hi:[1,1] neg_lo:[0,1] neg_hi:[0,1]
	v_pk_mul_f32 v[222:223], v[98:99], v[212:213] op_sel:[0,1] op_sel_hi:[1,1] neg_lo:[0,1] neg_hi:[0,1]
	v_pk_fma_f32 v[216:217], v[112:113], v[120:121], v[216:217] op_sel_hi:[1,0,1]
	v_pk_fma_f32 v[218:219], v[114:115], v[120:121], v[218:219] op_sel_hi:[1,0,1]
; #define SB __builtin_amdgcn_sched_barrier(0)
; #define CMP(G, c8) { CMP1(G, 0, 2 * (c8)) CMP1(G, 1, 2 * (c8) + 1) }
; __device__ __forceinline__ void phase_scan(const Args& a, unsigned char* lds) {
;     ...
;                     f32x4 KA[8];
; #pragma unroll
;                     for (int j = 0; j < 8; ++j) KA[j] = *(const f32x4*)(vb + 256 + 4 * j);
; #pragma nounroll
;                     for (int s = 0; s < 16; ++s) {
;                         const float* vs = vb + s * 384;
;                         const float vi = vs[128 - cb + srow];
;                         f32x4 G0[8], G1[8], G2[8];
;                         LDG(G0, 0) SB;
;                         LDG(G1, 1) SB;
;                         f32x2 c0 = {0.f, 0.f}, c1 = {0.f, 0.f};
; #pragma unroll
;                         for (int j = 0; j < 8; ++j) { c0 += S2[2 * j] * (f32x2){KA[j][0], KA[j][1]}; c1 += S2[2 * j + 1] * (f32x2){KA[j][2], KA[j][3]}; }
;                         float cs = (c0.x + c0.y) + (c1.x + c1.y);
;                         cs += dpp_f(cs, 0);
;                         const float sa = -cs;
;                         const f32x2 sa2 = {sa, sa}, v2 = {vi, vi};
;                         f32x2 y0 = {0.f, 0.f}, y1 = {0.f, 0.f};
;                         SB; LDG(G2, 2) SB; CMP(G0, 0) SB;
;                         LDG(G0, 3) SB; CMP(G1, 1) SB;
;                         CMP(G2, 2) SB;
; #pragma unroll
;                         for (int j = 0; j < 8; ++j) KA[j] = *(const f32x4*)(vs + 384 + 256 + 4 * j);
;                         SB; CMP(G0, 3) SB;
;                         float ys = (y0.x + y0.y) + (y1.x + y1.y);
;                         ys += dpp_f(ys, 0);
;                         if ((lane & 1) == 0) yb[s * 64 + srow] = ys;
	v_pk_fma_f32 v[220:221], v[112:113], v[120:121], v[220:221] op_sel:[0,1,0] op_sel_hi:[1,1,1]
	v_pk_fma_f32 v[222:223], v[114:115], v[120:121], v[222:223] op_sel:[0,1,0] op_sel_hi:[1,1,1]
	v_pk_fma_f32 v[8:9], v[8:9], v[188:189], v[216:217]
	v_pk_fma_f32 v[10:11], v[10:11], v[190:191], v[218:219]
	v_pk_fma_f32 v[24:25], v[24:25], v[188:189], v[220:221]
	v_pk_fma_f32 v[26:27], v[26:27], v[190:191], v[222:223]
	ds_read_b128 v[96:99], v232 offset:8992
	ds_read_b128 v[112:115], v232 offset:7968
	ds_read_b128 v[188:191], v232 offset:8480
	v_pk_mul_f32 v[224:225], v[100:101], v[212:213] op_sel_hi:[1,0] neg_lo:[0,1] neg_hi:[0,1]
	v_pk_mul_f32 v[226:227], v[102:103], v[212:213] op_sel_hi:[1,0] neg_lo:[0,1] neg_hi:[0,1]
	v_pk_mul_f32 v[228:229], v[100:101], v[212:213] op_sel:[0,1] op_sel_hi:[1,1] neg_lo:[0,1] neg_hi:[0,1]
	v_pk_mul_f32 v[230:231], v[102:103], v[212:213] op_sel:[0,1] op_sel_hi:[1,1] neg_lo:[0,1] neg_hi:[0,1]
	v_pk_fma_f32 v[224:225], v[116:117], v[120:121], v[224:225] op_sel_hi:[1,0,1]
	v_pk_fma_f32 v[226:227], v[118:119], v[120:121], v[226:227] op_sel_hi:[1,0,1]
	v_pk_fma_f32 v[228:229], v[116:117], v[120:121], v[228:229] op_sel:[0,1,0] op_sel_hi:[1,1,1]
	v_pk_fma_f32 v[230:231], v[118:119], v[120:121], v[230:231] op_sel:[0,1,0] op_sel_hi:[1,1,1]
	v_pk_fma_f32 v[12:13], v[12:13], v[192:193], v[224:225]
	v_pk_fma_f32 v[14:15], v[14:15], v[194:195], v[226:227]
	v_pk_fma_f32 v[28:29], v[28:29], v[192:193], v[228:229]
	v_pk_fma_f32 v[30:31], v[30:31], v[194:195], v[230:231]
	ds_read_b128 v[100:103], v232 offset:9008
	ds_read_b128 v[116:119], v232 offset:7984
	ds_read_b128 v[192:195], v232 offset:8496
	s_waitcnt lgkmcnt(13)
	v_pk_mul_f32 v[196:197], v[0:1], v[32:33]
	v_pk_mul_f32 v[200:201], v[16:17], v[32:33]
	v_pk_mul_f32 v[204:205], v[0:1], v[48:49]
	v_pk_mul_f32 v[208:209], v[16:17], v[48:49]
	v_pk_fma_f32 v[196:197], v[2:3], v[34:35], v[196:197]
	v_pk_fma_f32 v[200:201], v[18:19], v[34:35], v[200:201]
	v_pk_fma_f32 v[204:205], v[2:3], v[50:51], v[204:205]
	v_pk_fma_f32 v[208:209], v[18:19], v[50:51], v[208:209]
	ds_read_b128 v[32:35], v232 offset:10240
	ds_read_b128 v[48:51], v232 offset:7680
	v_pk_fma_f32 v[196:197], v[4:5], v[36:37], v[196:197]
	v_pk_fma_f32 v[200:201], v[20:21], v[36:37], v[200:201]
	v_pk_fma_f32 v[204:205], v[4:5], v[52:53], v[204:205]
	v_pk_fma_f32 v[208:209], v[20:21], v[52:53], v[208:209]
	v_pk_fma_f32 v[196:197], v[6:7], v[38:39], v[196:197]
	v_pk_fma_f32 v[200:201], v[22:23], v[38:39], v[200:201]
	v_pk_fma_f32 v[204:205], v[6:7], v[54:55], v[204:205]
	v_pk_fma_f32 v[208:209], v[22:23], v[54:55], v[208:209]
	ds_read_b128 v[36:39], v232 offset:10256
	ds_read_b128 v[52:55], v232 offset:7696
	v_pk_fma_f32 v[196:197], v[8:9], v[40:41], v[196:197]
	v_pk_fma_f32 v[200:201], v[24:25], v[40:41], v[200:201]
	v_pk_fma_f32 v[204:205], v[8:9], v[56:57], v[204:205]
	v_pk_fma_f32 v[208:209], v[24:25], v[56:57], v[208:209]
	v_pk_fma_f32 v[196:197], v[10:11], v[42:43], v[196:197]
	v_pk_fma_f32 v[200:201], v[26:27], v[42:43], v[200:201]
	v_pk_fma_f32 v[204:205], v[10:11], v[58:59], v[204:205]
	v_pk_fma_f32 v[208:209], v[26:27], v[58:59], v[208:209]
	ds_read_b128 v[40:43], v232 offset:10272
	ds_read_b128 v[56:59], v232 offset:7712
	v_pk_fma_f32 v[196:197], v[12:13], v[44:45], v[196:197]
	v_pk_fma_f32 v[200:201], v[28:29], v[44:45], v[200:201]
	v_pk_fma_f32 v[204:205], v[12:13], v[60:61], v[204:205]
	v_pk_fma_f32 v[208:209], v[28:29], v[60:61], v[208:209]
	v_pk_fma_f32 v[196:197], v[14:15], v[46:47], v[196:197]
	v_pk_fma_f32 v[200:201], v[30:31], v[46:47], v[200:201]
	v_pk_fma_f32 v[204:205], v[14:15], v[62:63], v[204:205]
	v_pk_fma_f32 v[208:209], v[30:31], v[62:63], v[208:209]
	ds_read_b128 v[44:47], v232 offset:10288
	ds_read_b128 v[60:63], v232 offset:7728
	v_add_f32_e32 v212, v196, v197
	v_add_f32_e32 v213, v200, v201
	v_add_f32_e32 v214, v204, v205
	v_add_f32_e32 v215, v208, v209
	v_add_f32_dpp v212, v212, v212 quad_perm:[1,0,3,2] row_mask:0xf bank_mask:0xf
	v_add_f32_dpp v213, v213, v213 quad_perm:[1,0,3,2] row_mask:0xf bank_mask:0xf
	v_add_f32_dpp v214, v214, v214 quad_perm:[1,0,3,2] row_mask:0xf bank_mask:0xf
	v_add_f32_dpp v215, v215, v215 quad_perm:[1,0,3,2] row_mask:0xf bank_mask:0xf
	v_add_f32_dpp v212, v212, v212 quad_perm:[2,3,0,1] row_mask:0xf bank_mask:0xf
	v_add_f32_dpp v213, v213, v213 quad_perm:[2,3,0,1] row_mask:0xf bank_mask:0xf
	v_add_f32_dpp v214, v214, v214 quad_perm:[2,3,0,1] row_mask:0xf bank_mask:0xf
	v_add_f32_dpp v215, v215, v215 quad_perm:[2,3,0,1] row_mask:0xf bank_mask:0xf
	ds_write_b64 v234, v[214:215] offset:1024
	s_waitcnt lgkmcnt(8)
; #define SB __builtin_amdgcn_sched_barrier(0)
; #define CMP(G, c8) { CMP1(G, 0, 2 * (c8)) CMP1(G, 1, 2 * (c8) + 1) }
; __device__ __forceinline__ void phase_scan(const Args& a, unsigned char* lds) {
;     ...
;                     f32x4 KA[8];
; #pragma unroll
;                     for (int j = 0; j < 8; ++j) KA[j] = *(const f32x4*)(vb + 256 + 4 * j);
; #pragma nounroll
;                     for (int s = 0; s < 16; ++s) {
;                         const float* vs = vb + s * 384;
;                         const float vi = vs[128 - cb + srow];
;                         f32x4 G0[8], G1[8], G2[8];
;                         LDG(G0, 0) SB;
;                         LDG(G1, 1) SB;
;                         f32x2 c0 = {0.f, 0.f}, c1 = {0.f, 0.f};
; #pragma unroll
;                         for (int j = 0; j < 8; ++j) { c0 += S2[2 * j] * (f32x2){KA[j][0], KA[j][1]}; c1 += S2[2 * j + 1] * (f32x2){KA[j][2], KA[j][3]}; }
;                         float cs = (c0.x + c0.y) + (c1.x + c1.y);
;                         cs += dpp_f(cs, 0);
;                         const float sa = -cs;
;                         const f32x2 sa2 = {sa, sa}, v2 = {vi, vi};
;                         f32x2 y0 = {0.f, 0.f}, y1 = {0.f, 0.f};
;                         SB; LDG(G2, 2) SB; CMP(G0, 0) SB;
;                         LDG(G0, 3) SB; CMP(G1, 1) SB;
;                         CMP(G2, 2) SB;
; #pragma unroll
;                         for (int j = 0; j < 8; ++j) KA[j] = *(const f32x4*)(vs + 384 + 256 + 4 * j);
;                         SB; CMP(G0, 3) SB;
;                         float ys = (y0.x + y0.y) + (y1.x + y1.y);
;                         ys += dpp_f(ys, 0);
;                         if ((lane & 1) == 0) yb[s * 64 + srow] = ys;
	ds_read_b64 v[120:121], v233 offset:9728
	v_pk_mul_f32 v[216:217], v[88:89], v[212:213] op_sel_hi:[1,0] neg_lo:[0,1] neg_hi:[0,1]
	v_pk_mul_f32 v[218:219], v[90:91], v[212:213] op_sel_hi:[1,0] neg_lo:[0,1] neg_hi:[0,1]
	v_pk_mul_f32 v[220:221], v[88:89], v[212:213] op_sel:[0,1] op_sel_hi:[1,1] neg_lo:[0,1] neg_hi:[0,1]
	v_pk_mul_f32 v[222:223], v[90:91], v[212:213] op_sel:[0,1] op_sel_hi:[1,1] neg_lo:[0,1] neg_hi:[0,1]
	v_pk_fma_f32 v[216:217], v[104:105], v[122:123], v[216:217] op_sel_hi:[1,0,1]
	v_pk_fma_f32 v[218:219], v[106:107], v[122:123], v[218:219] op_sel_hi:[1,0,1]
	v_pk_fma_f32 v[220:221], v[104:105], v[122:123], v[220:221] op_sel:[0,1,0] op_sel_hi:[1,1,1]
	v_pk_fma_f32 v[222:223], v[106:107], v[122:123], v[222:223] op_sel:[0,1,0] op_sel_hi:[1,1,1]
	v_pk_fma_f32 v[0:1], v[0:1], v[180:181], v[216:217]
	v_pk_fma_f32 v[2:3], v[2:3], v[182:183], v[218:219]
	v_pk_fma_f32 v[16:17], v[16:17], v[180:181], v[220:221]
	v_pk_fma_f32 v[18:19], v[18:19], v[182:183], v[222:223]
	ds_read_b128 v[88:91], v232 offset:10496
	ds_read_b128 v[104:107], v232 offset:9472
	ds_read_b128 v[180:183], v232 offset:9984
	v_pk_mul_f32 v[224:225], v[92:93], v[212:213] op_sel_hi:[1,0] neg_lo:[0,1] neg_hi:[0,1]
	v_pk_mul_f32 v[226:227], v[94:95], v[212:213] op_sel_hi:[1,0] neg_lo:[0,1] neg_hi:[0,1]
	v_pk_mul_f32 v[228:229], v[92:93], v[212:213] op_sel:[0,1] op_sel_hi:[1,1] neg_lo:[0,1] neg_hi:[0,1]
	v_pk_mul_f32 v[230:231], v[94:95], v[212:213] op_sel:[0,1] op_sel_hi:[1,1] neg_lo:[0,1] neg_hi:[0,1]
	v_pk_fma_f32 v[224:225], v[108:109], v[122:123], v[224:225] op_sel_hi:[1,0,1]
	v_pk_fma_f32 v[226:227], v[110:111], v[122:123], v[226:227] op_sel_hi:[1,0,1]
	v_pk_fma_f32 v[228:229], v[108:109], v[122:123], v[228:229] op_sel:[0,1,0] op_sel_hi:[1,1,1]
	v_pk_fma_f32 v[230:231], v[110:111], v[122:123], v[230:231] op_sel:[0,1,0] op_sel_hi:[1,1,1]
	v_pk_fma_f32 v[4:5], v[4:5], v[184:185], v[224:225]
	v_pk_fma_f32 v[6:7], v[6:7], v[186:187], v[226:227]
	v_pk_fma_f32 v[20:21], v[20:21], v[184:185], v[228:229]
	v_pk_fma_f32 v[22:23], v[22:23], v[186:187], v[230:231]
	ds_read_b128 v[92:95], v232 offset:10512
	ds_read_b128 v[108:111], v232 offset:9488
	ds_read_b128 v[184:187], v232 offset:10000
	v_pk_mul_f32 v[216:217], v[96:97], v[212:213] op_sel_hi:[1,0] neg_lo:[0,1] neg_hi:[0,1]
	v_pk_mul_f32 v[218:219], v[98:99], v[212:213] op_sel_hi:[1,0] neg_lo:[0,1] neg_hi:[0,1]
	v_pk_mul_f32 v[220:221], v[96:97], v[212:213] op_sel:[0,1] op_sel_hi:[1,1] neg_lo:[0,1] neg_hi:[0,1]
	v_pk_mul_f32 v[222:223], v[98:99], v[212:213] op_sel:[0,1] op_sel_hi:[1,1] neg_lo:[0,1] neg_hi:[0,1]
	v_pk_fma_f32 v[216:217], v[112:113], v[122:123], v[216:217] op_sel_hi:[1,0,1]
	v_pk_fma_f32 v[218:219], v[114:115], v[122:123], v[218:219] op_sel_hi:[1,0,1]
	v_pk_fma_f32 v[220:221], v[112:113], v[122:123], v[220:221] op_sel:[0,1,0] op_sel_hi:[1,1,1]
	v_pk_fma_f32 v[222:223], v[114:115], v[122:123], v[222:223] op_sel:[0,1,0] op_sel_hi:[1,1,1]
	v_pk_fma_f32 v[8:9], v[8:9], v[188:189], v[216:217]
	v_pk_fma_f32 v[10:11], v[10:11], v[190:191], v[218:219]
	v_pk_fma_f32 v[24:25], v[24:25], v[188:189], v[220:221]
	v_pk_fma_f32 v[26:27], v[26:27], v[190:191], v[222:223]
	ds_read_b128 v[96:99], v232 offset:10528
	ds_read_b128 v[112:115], v232 offset:9504
	ds_read_b128 v[188:191], v232 offset:10016
	v_pk_mul_f32 v[224:225], v[100:101], v[212:213] op_sel_hi:[1,0] neg_lo:[0,1] neg_hi:[0,1]
	v_pk_mul_f32 v[226:227], v[102:103], v[212:213] op_sel_hi:[1,0] neg_lo:[0,1] neg_hi:[0,1]
	v_pk_mul_f32 v[228:229], v[100:101], v[212:213] op_sel:[0,1] op_sel_hi:[1,1] neg_lo:[0,1] neg_hi:[0,1]
	v_pk_mul_f32 v[230:231], v[102:103], v[212:213] op_sel:[0,1] op_sel_hi:[1,1] neg_lo:[0,1] neg_hi:[0,1]
	v_pk_fma_f32 v[224:225], v[116:117], v[122:123], v[224:225] op_sel_hi:[1,0,1]
	v_pk_fma_f32 v[226:227], v[118:119], v[122:123], v[226:227] op_sel_hi:[1,0,1]
	v_pk_fma_f32 v[228:229], v[116:117], v[122:123], v[228:229] op_sel:[0,1,0] op_sel_hi:[1,1,1]
	v_pk_fma_f32 v[230:231], v[118:119], v[122:123], v[230:231] op_sel:[0,1,0] op_sel_hi:[1,1,1]
	v_pk_fma_f32 v[12:13], v[12:13], v[192:193], v[224:225]
	v_pk_fma_f32 v[14:15], v[14:15], v[194:195], v[226:227]
	v_pk_fma_f32 v[28:29], v[28:29], v[192:193], v[228:229]
	v_pk_fma_f32 v[30:31], v[30:31], v[194:195], v[230:231]
	ds_read_b128 v[100:103], v232 offset:10544
	ds_read_b128 v[116:119], v232 offset:9520
	ds_read_b128 v[192:195], v232 offset:10032
	s_waitcnt lgkmcnt(13)
; #define SB __builtin_amdgcn_sched_barrier(0)
; #define CMP(G, c8) { CMP1(G, 0, 2 * (c8)) CMP1(G, 1, 2 * (c8) + 1) }
; __device__ __forceinline__ void phase_scan(const Args& a, unsigned char* lds) {
;     ...
;                     f32x4 KA[8];
; #pragma unroll
;                     for (int j = 0; j < 8; ++j) KA[j] = *(const f32x4*)(vb + 256 + 4 * j);
; #pragma nounroll
;                     for (int s = 0; s < 16; ++s) {
;                         const float* vs = vb + s * 384;
;                         const float vi = vs[128 - cb + srow];
;                         f32x4 G0[8], G1[8], G2[8];
;                         LDG(G0, 0) SB;
;                         LDG(G1, 1) SB;
;                         f32x2 c0 = {0.f, 0.f}, c1 = {0.f, 0.f};
; #pragma unroll
;                         for (int j = 0; j < 8; ++j) { c0 += S2[2 * j] * (f32x2){KA[j][0], KA[j][1]}; c1 += S2[2 * j + 1] * (f32x2){KA[j][2], KA[j][3]}; }
;                         float cs = (c0.x + c0.y) + (c1.x + c1.y);
;                         cs += dpp_f(cs, 0);
;                         const float sa = -cs;
;                         const f32x2 sa2 = {sa, sa}, v2 = {vi, vi};
;                         f32x2 y0 = {0.f, 0.f}, y1 = {0.f, 0.f};
;                         SB; LDG(G2, 2) SB; CMP(G0, 0) SB;
;                         LDG(G0, 3) SB; CMP(G1, 1) SB;
;                         CMP(G2, 2) SB;
; #pragma unroll
;                         for (int j = 0; j < 8; ++j) KA[j] = *(const f32x4*)(vs + 384 + 256 + 4 * j);
;                         SB; CMP(G0, 3) SB;
;                         float ys = (y0.x + y0.y) + (y1.x + y1.y);
;                         ys += dpp_f(ys, 0);
;                         if ((lane & 1) == 0) yb[s * 64 + srow] = ys;
	v_pk_mul_f32 v[196:197], v[0:1], v[32:33]
	v_pk_mul_f32 v[200:201], v[16:17], v[32:33]
	v_pk_mul_f32 v[204:205], v[0:1], v[48:49]
	v_pk_mul_f32 v[208:209], v[16:17], v[48:49]
	v_pk_fma_f32 v[196:197], v[2:3], v[34:35], v[196:197]
	v_pk_fma_f32 v[200:201], v[18:19], v[34:35], v[200:201]
	v_pk_fma_f32 v[204:205], v[2:3], v[50:51], v[204:205]
	v_pk_fma_f32 v[208:209], v[18:19], v[50:51], v[208:209]
	ds_read_b128 v[32:35], v232 offset:11776
	ds_read_b128 v[48:51], v232 offset:9216
	v_pk_fma_f32 v[196:197], v[4:5], v[36:37], v[196:197]
	v_pk_fma_f32 v[200:201], v[20:21], v[36:37], v[200:201]
	v_pk_fma_f32 v[204:205], v[4:5], v[52:53], v[204:205]
	v_pk_fma_f32 v[208:209], v[20:21], v[52:53], v[208:209]
	v_pk_fma_f32 v[196:197], v[6:7], v[38:39], v[196:197]
	v_pk_fma_f32 v[200:201], v[22:23], v[38:39], v[200:201]
	v_pk_fma_f32 v[204:205], v[6:7], v[54:55], v[204:205]
	v_pk_fma_f32 v[208:209], v[22:23], v[54:55], v[208:209]
	ds_read_b128 v[36:39], v232 offset:11792
	ds_read_b128 v[52:55], v232 offset:9232
	v_pk_fma_f32 v[196:197], v[8:9], v[40:41], v[196:197]
	v_pk_fma_f32 v[200:201], v[24:25], v[40:41], v[200:201]
	v_pk_fma_f32 v[204:205], v[8:9], v[56:57], v[204:205]
	v_pk_fma_f32 v[208:209], v[24:25], v[56:57], v[208:209]
	v_pk_fma_f32 v[196:197], v[10:11], v[42:43], v[196:197]
	v_pk_fma_f32 v[200:201], v[26:27], v[42:43], v[200:201]
	v_pk_fma_f32 v[204:205], v[10:11], v[58:59], v[204:205]
	v_pk_fma_f32 v[208:209], v[26:27], v[58:59], v[208:209]
	ds_read_b128 v[40:43], v232 offset:11808
	ds_read_b128 v[56:59], v232 offset:9248
	v_pk_fma_f32 v[196:197], v[12:13], v[44:45], v[196:197]
	v_pk_fma_f32 v[200:201], v[28:29], v[44:45], v[200:201]
	v_pk_fma_f32 v[204:205], v[12:13], v[60:61], v[204:205]
	v_pk_fma_f32 v[208:209], v[28:29], v[60:61], v[208:209]
	v_pk_fma_f32 v[196:197], v[14:15], v[46:47], v[196:197]
	v_pk_fma_f32 v[200:201], v[30:31], v[46:47], v[200:201]
	v_pk_fma_f32 v[204:205], v[14:15], v[62:63], v[204:205]
	v_pk_fma_f32 v[208:209], v[30:31], v[62:63], v[208:209]
	ds_read_b128 v[44:47], v232 offset:11824
	ds_read_b128 v[60:63], v232 offset:9264
	v_add_f32_e32 v212, v196, v197
	v_add_f32_e32 v213, v200, v201
	v_add_f32_e32 v214, v204, v205
	v_add_f32_e32 v215, v208, v209
	v_add_f32_dpp v212, v212, v212 quad_perm:[1,0,3,2] row_mask:0xf bank_mask:0xf
	v_add_f32_dpp v213, v213, v213 quad_perm:[1,0,3,2] row_mask:0xf bank_mask:0xf
	v_add_f32_dpp v214, v214, v214 quad_perm:[1,0,3,2] row_mask:0xf bank_mask:0xf
	v_add_f32_dpp v215, v215, v215 quad_perm:[1,0,3,2] row_mask:0xf bank_mask:0xf
	v_add_f32_dpp v212, v212, v212 quad_perm:[2,3,0,1] row_mask:0xf bank_mask:0xf
	v_add_f32_dpp v213, v213, v213 quad_perm:[2,3,0,1] row_mask:0xf bank_mask:0xf
	v_add_f32_dpp v214, v214, v214 quad_perm:[2,3,0,1] row_mask:0xf bank_mask:0xf
	v_add_f32_dpp v215, v215, v215 quad_perm:[2,3,0,1] row_mask:0xf bank_mask:0xf
	ds_write_b64 v234, v[214:215] offset:1280
	s_waitcnt lgkmcnt(8)
	ds_read_b64 v[122:123], v233 offset:11264
	v_pk_mul_f32 v[216:217], v[88:89], v[212:213] op_sel_hi:[1,0] neg_lo:[0,1] neg_hi:[0,1]
	v_pk_mul_f32 v[218:219], v[90:91], v[212:213] op_sel_hi:[1,0] neg_lo:[0,1] neg_hi:[0,1]
	v_pk_mul_f32 v[220:221], v[88:89], v[212:213] op_sel:[0,1] op_sel_hi:[1,1] neg_lo:[0,1] neg_hi:[0,1]
	v_pk_mul_f32 v[222:223], v[90:91], v[212:213] op_sel:[0,1] op_sel_hi:[1,1] neg_lo:[0,1] neg_hi:[0,1]
	v_pk_fma_f32 v[216:217], v[104:105], v[120:121], v[216:217] op_sel_hi:[1,0,1]
	v_pk_fma_f32 v[218:219], v[106:107], v[120:121], v[218:219] op_sel_hi:[1,0,1]
	v_pk_fma_f32 v[220:221], v[104:105], v[120:121], v[220:221] op_sel:[0,1,0] op_sel_hi:[1,1,1]
	v_pk_fma_f32 v[222:223], v[106:107], v[120:121], v[222:223] op_sel:[0,1,0] op_sel_hi:[1,1,1]
	v_pk_fma_f32 v[0:1], v[0:1], v[180:181], v[216:217]
	v_pk_fma_f32 v[2:3], v[2:3], v[182:183], v[218:219]
	v_pk_fma_f32 v[16:17], v[16:17], v[180:181], v[220:221]
	v_pk_fma_f32 v[18:19], v[18:19], v[182:183], v[222:223]
	ds_read_b128 v[88:91], v232 offset:12032
	ds_read_b128 v[104:107], v232 offset:11008
	ds_read_b128 v[180:183], v232 offset:11520
	v_pk_mul_f32 v[224:225], v[92:93], v[212:213] op_sel_hi:[1,0] neg_lo:[0,1] neg_hi:[0,1]
	v_pk_mul_f32 v[226:227], v[94:95], v[212:213] op_sel_hi:[1,0] neg_lo:[0,1] neg_hi:[0,1]
	v_pk_mul_f32 v[228:229], v[92:93], v[212:213] op_sel:[0,1] op_sel_hi:[1,1] neg_lo:[0,1] neg_hi:[0,1]
	v_pk_mul_f32 v[230:231], v[94:95], v[212:213] op_sel:[0,1] op_sel_hi:[1,1] neg_lo:[0,1] neg_hi:[0,1]
	v_pk_fma_f32 v[224:225], v[108:109], v[120:121], v[224:225] op_sel_hi:[1,0,1]
	v_pk_fma_f32 v[226:227], v[110:111], v[120:121], v[226:227] op_sel_hi:[1,0,1]
	v_pk_fma_f32 v[228:229], v[108:109], v[120:121], v[228:229] op_sel:[0,1,0] op_sel_hi:[1,1,1]
	v_pk_fma_f32 v[230:231], v[110:111], v[120:121], v[230:231] op_sel:[0,1,0] op_sel_hi:[1,1,1]
	v_pk_fma_f32 v[4:5], v[4:5], v[184:185], v[224:225]
	v_pk_fma_f32 v[6:7], v[6:7], v[186:187], v[226:227]
	v_pk_fma_f32 v[20:21], v[20:21], v[184:185], v[228:229]
	v_pk_fma_f32 v[22:23], v[22:23], v[186:187], v[230:231]
	ds_read_b128 v[92:95], v232 offset:12048
	ds_read_b128 v[108:111], v232 offset:11024
	ds_read_b128 v[184:187], v232 offset:11536
	v_pk_mul_f32 v[216:217], v[96:97], v[212:213] op_sel_hi:[1,0] neg_lo:[0,1] neg_hi:[0,1]
	v_pk_mul_f32 v[218:219], v[98:99], v[212:213] op_sel_hi:[1,0] neg_lo:[0,1] neg_hi:[0,1]
	v_pk_mul_f32 v[220:221], v[96:97], v[212:213] op_sel:[0,1] op_sel_hi:[1,1] neg_lo:[0,1] neg_hi:[0,1]
	v_pk_mul_f32 v[222:223], v[98:99], v[212:213] op_sel:[0,1] op_sel_hi:[1,1] neg_lo:[0,1] neg_hi:[0,1]
	v_pk_fma_f32 v[216:217], v[112:113], v[120:121], v[216:217] op_sel_hi:[1,0,1]
	v_pk_fma_f32 v[218:219], v[114:115], v[120:121], v[218:219] op_sel_hi:[1,0,1]
; #define SB __builtin_amdgcn_sched_barrier(0)
; #define CMP(G, c8) { CMP1(G, 0, 2 * (c8)) CMP1(G, 1, 2 * (c8) + 1) }
; __device__ __forceinline__ void phase_scan(const Args& a, unsigned char* lds) {
;     ...
;                     f32x4 KA[8];
; #pragma unroll
;                     for (int j = 0; j < 8; ++j) KA[j] = *(const f32x4*)(vb + 256 + 4 * j);
; #pragma nounroll
;                     for (int s = 0; s < 16; ++s) {
;                         const float* vs = vb + s * 384;
;                         const float vi = vs[128 - cb + srow];
;                         f32x4 G0[8], G1[8], G2[8];
;                         LDG(G0, 0) SB;
;                         LDG(G1, 1) SB;
;                         f32x2 c0 = {0.f, 0.f}, c1 = {0.f, 0.f};
; #pragma unroll
;                         for (int j = 0; j < 8; ++j) { c0 += S2[2 * j] * (f32x2){KA[j][0], KA[j][1]}; c1 += S2[2 * j + 1] * (f32x2){KA[j][2], KA[j][3]}; }
;                         float cs = (c0.x + c0.y) + (c1.x + c1.y);
;                         cs += dpp_f(cs, 0);
;                         const float sa = -cs;
;                         const f32x2 sa2 = {sa, sa}, v2 = {vi, vi};
;                         f32x2 y0 = {0.f, 0.f}, y1 = {0.f, 0.f};
;                         SB; LDG(G2, 2) SB; CMP(G0, 0) SB;
;                         LDG(G0, 3) SB; CMP(G1, 1) SB;
;                         CMP(G2, 2) SB;
; #pragma unroll
;                         for (int j = 0; j < 8; ++j) KA[j] = *(const f32x4*)(vs + 384 + 256 + 4 * j);
;                         SB; CMP(G0, 3) SB;
;                         float ys = (y0.x + y0.y) + (y1.x + y1.y);
;                         ys += dpp_f(ys, 0);
;                         if ((lane & 1) == 0) yb[s * 64 + srow] = ys;
	v_pk_fma_f32 v[220:221], v[112:113], v[120:121], v[220:221] op_sel:[0,1,0] op_sel_hi:[1,1,1]
	v_pk_fma_f32 v[222:223], v[114:115], v[120:121], v[222:223] op_sel:[0,1,0] op_sel_hi:[1,1,1]
	v_pk_fma_f32 v[8:9], v[8:9], v[188:189], v[216:217]
	v_pk_fma_f32 v[10:11], v[10:11], v[190:191], v[218:219]
	v_pk_fma_f32 v[24:25], v[24:25], v[188:189], v[220:221]
	v_pk_fma_f32 v[26:27], v[26:27], v[190:191], v[222:223]
	ds_read_b128 v[96:99], v232 offset:12064
	ds_read_b128 v[112:115], v232 offset:11040
	ds_read_b128 v[188:191], v232 offset:11552
	v_pk_mul_f32 v[224:225], v[100:101], v[212:213] op_sel_hi:[1,0] neg_lo:[0,1] neg_hi:[0,1]
	v_pk_mul_f32 v[226:227], v[102:103], v[212:213] op_sel_hi:[1,0] neg_lo:[0,1] neg_hi:[0,1]
	v_pk_mul_f32 v[228:229], v[100:101], v[212:213] op_sel:[0,1] op_sel_hi:[1,1] neg_lo:[0,1] neg_hi:[0,1]
	v_pk_mul_f32 v[230:231], v[102:103], v[212:213] op_sel:[0,1] op_sel_hi:[1,1] neg_lo:[0,1] neg_hi:[0,1]
	v_pk_fma_f32 v[224:225], v[116:117], v[120:121], v[224:225] op_sel_hi:[1,0,1]
	v_pk_fma_f32 v[226:227], v[118:119], v[120:121], v[226:227] op_sel_hi:[1,0,1]
	v_pk_fma_f32 v[228:229], v[116:117], v[120:121], v[228:229] op_sel:[0,1,0] op_sel_hi:[1,1,1]
	v_pk_fma_f32 v[230:231], v[118:119], v[120:121], v[230:231] op_sel:[0,1,0] op_sel_hi:[1,1,1]
	v_pk_fma_f32 v[12:13], v[12:13], v[192:193], v[224:225]
	v_pk_fma_f32 v[14:15], v[14:15], v[194:195], v[226:227]
	v_pk_fma_f32 v[28:29], v[28:29], v[192:193], v[228:229]
	v_pk_fma_f32 v[30:31], v[30:31], v[194:195], v[230:231]
	ds_read_b128 v[100:103], v232 offset:12080
	ds_read_b128 v[116:119], v232 offset:11056
	ds_read_b128 v[192:195], v232 offset:11568
	s_waitcnt lgkmcnt(13)
	v_pk_mul_f32 v[196:197], v[0:1], v[32:33]
	v_pk_mul_f32 v[200:201], v[16:17], v[32:33]
	v_pk_mul_f32 v[204:205], v[0:1], v[48:49]
	v_pk_mul_f32 v[208:209], v[16:17], v[48:49]
	v_pk_fma_f32 v[196:197], v[2:3], v[34:35], v[196:197]
	v_pk_fma_f32 v[200:201], v[18:19], v[34:35], v[200:201]
	v_pk_fma_f32 v[204:205], v[2:3], v[50:51], v[204:205]
	v_pk_fma_f32 v[208:209], v[18:19], v[50:51], v[208:209]
	ds_read_b128 v[32:35], v232 offset:13312
	ds_read_b128 v[48:51], v232 offset:10752
	v_pk_fma_f32 v[196:197], v[4:5], v[36:37], v[196:197]
	v_pk_fma_f32 v[200:201], v[20:21], v[36:37], v[200:201]
	v_pk_fma_f32 v[204:205], v[4:5], v[52:53], v[204:205]
	v_pk_fma_f32 v[208:209], v[20:21], v[52:53], v[208:209]
	v_pk_fma_f32 v[196:197], v[6:7], v[38:39], v[196:197]
	v_pk_fma_f32 v[200:201], v[22:23], v[38:39], v[200:201]
	v_pk_fma_f32 v[204:205], v[6:7], v[54:55], v[204:205]
	v_pk_fma_f32 v[208:209], v[22:23], v[54:55], v[208:209]
	ds_read_b128 v[36:39], v232 offset:13328
	ds_read_b128 v[52:55], v232 offset:10768
	v_pk_fma_f32 v[196:197], v[8:9], v[40:41], v[196:197]
	v_pk_fma_f32 v[200:201], v[24:25], v[40:41], v[200:201]
	v_pk_fma_f32 v[204:205], v[8:9], v[56:57], v[204:205]
	v_pk_fma_f32 v[208:209], v[24:25], v[56:57], v[208:209]
	v_pk_fma_f32 v[196:197], v[10:11], v[42:43], v[196:197]
	v_pk_fma_f32 v[200:201], v[26:27], v[42:43], v[200:201]
	v_pk_fma_f32 v[204:205], v[10:11], v[58:59], v[204:205]
	v_pk_fma_f32 v[208:209], v[26:27], v[58:59], v[208:209]
	ds_read_b128 v[40:43], v232 offset:13344
	ds_read_b128 v[56:59], v232 offset:10784
	v_pk_fma_f32 v[196:197], v[12:13], v[44:45], v[196:197]
	v_pk_fma_f32 v[200:201], v[28:29], v[44:45], v[200:201]
	v_pk_fma_f32 v[204:205], v[12:13], v[60:61], v[204:205]
	v_pk_fma_f32 v[208:209], v[28:29], v[60:61], v[208:209]
	v_pk_fma_f32 v[196:197], v[14:15], v[46:47], v[196:197]
	v_pk_fma_f32 v[200:201], v[30:31], v[46:47], v[200:201]
	v_pk_fma_f32 v[204:205], v[14:15], v[62:63], v[204:205]
	v_pk_fma_f32 v[208:209], v[30:31], v[62:63], v[208:209]
	ds_read_b128 v[44:47], v232 offset:13360
	ds_read_b128 v[60:63], v232 offset:10800
	v_add_f32_e32 v212, v196, v197
	v_add_f32_e32 v213, v200, v201
	v_add_f32_e32 v214, v204, v205
	v_add_f32_e32 v215, v208, v209
	v_add_f32_dpp v212, v212, v212 quad_perm:[1,0,3,2] row_mask:0xf bank_mask:0xf
	v_add_f32_dpp v213, v213, v213 quad_perm:[1,0,3,2] row_mask:0xf bank_mask:0xf
	v_add_f32_dpp v214, v214, v214 quad_perm:[1,0,3,2] row_mask:0xf bank_mask:0xf
	v_add_f32_dpp v215, v215, v215 quad_perm:[1,0,3,2] row_mask:0xf bank_mask:0xf
	v_add_f32_dpp v212, v212, v212 quad_perm:[2,3,0,1] row_mask:0xf bank_mask:0xf
	v_add_f32_dpp v213, v213, v213 quad_perm:[2,3,0,1] row_mask:0xf bank_mask:0xf
	v_add_f32_dpp v214, v214, v214 quad_perm:[2,3,0,1] row_mask:0xf bank_mask:0xf
	v_add_f32_dpp v215, v215, v215 quad_perm:[2,3,0,1] row_mask:0xf bank_mask:0xf
	ds_write_b64 v234, v[214:215] offset:1536
	s_waitcnt lgkmcnt(8)
; #define SB __builtin_amdgcn_sched_barrier(0)
; #define CMP(G, c8) { CMP1(G, 0, 2 * (c8)) CMP1(G, 1, 2 * (c8) + 1) }
; __device__ __forceinline__ void phase_scan(const Args& a, unsigned char* lds) {
;     ...
;                     f32x4 KA[8];
; #pragma unroll
;                     for (int j = 0; j < 8; ++j) KA[j] = *(const f32x4*)(vb + 256 + 4 * j);
; #pragma nounroll
;                     for (int s = 0; s < 16; ++s) {
;                         const float* vs = vb + s * 384;
;                         const float vi = vs[128 - cb + srow];
;                         f32x4 G0[8], G1[8], G2[8];
;                         LDG(G0, 0) SB;
;                         LDG(G1, 1) SB;
;                         f32x2 c0 = {0.f, 0.f}, c1 = {0.f, 0.f};
; #pragma unroll
;                         for (int j = 0; j < 8; ++j) { c0 += S2[2 * j] * (f32x2){KA[j][0], KA[j][1]}; c1 += S2[2 * j + 1] * (f32x2){KA[j][2], KA[j][3]}; }
;                         float cs = (c0.x + c0.y) + (c1.x + c1.y);
;                         cs += dpp_f(cs, 0);
;                         const float sa = -cs;
;                         const f32x2 sa2 = {sa, sa}, v2 = {vi, vi};
;                         f32x2 y0 = {0.f, 0.f}, y1 = {0.f, 0.f};
;                         SB; LDG(G2, 2) SB; CMP(G0, 0) SB;
;                         LDG(G0, 3) SB; CMP(G1, 1) SB;
;                         CMP(G2, 2) SB;
; #pragma unroll
;                         for (int j = 0; j < 8; ++j) KA[j] = *(const f32x4*)(vs + 384 + 256 + 4 * j);
;                         SB; CMP(G0, 3) SB;
;                         float ys = (y0.x + y0.y) + (y1.x + y1.y);
;                         ys += dpp_f(ys, 0);
;                         if ((lane & 1) == 0) yb[s * 64 + srow] = ys;
	ds_read_b64 v[120:121], v233 offset:12800
	v_pk_mul_f32 v[216:217], v[88:89], v[212:213] op_sel_hi:[1,0] neg_lo:[0,1] neg_hi:[0,1]
	v_pk_mul_f32 v[218:219], v[90:91], v[212:213] op_sel_hi:[1,0] neg_lo:[0,1] neg_hi:[0,1]
	v_pk_mul_f32 v[220:221], v[88:89], v[212:213] op_sel:[0,1] op_sel_hi:[1,1] neg_lo:[0,1] neg_hi:[0,1]
	v_pk_mul_f32 v[222:223], v[90:91], v[212:213] op_sel:[0,1] op_sel_hi:[1,1] neg_lo:[0,1] neg_hi:[0,1]
	v_pk_fma_f32 v[216:217], v[104:105], v[122:123], v[216:217] op_sel_hi:[1,0,1]
	v_pk_fma_f32 v[218:219], v[106:107], v[122:123], v[218:219] op_sel_hi:[1,0,1]
	v_pk_fma_f32 v[220:221], v[104:105], v[122:123], v[220:221] op_sel:[0,1,0] op_sel_hi:[1,1,1]
	v_pk_fma_f32 v[222:223], v[106:107], v[122:123], v[222:223] op_sel:[0,1,0] op_sel_hi:[1,1,1]
	v_pk_fma_f32 v[0:1], v[0:1], v[180:181], v[216:217]
	v_pk_fma_f32 v[2:3], v[2:3], v[182:183], v[218:219]
	v_pk_fma_f32 v[16:17], v[16:17], v[180:181], v[220:221]
	v_pk_fma_f32 v[18:19], v[18:19], v[182:183], v[222:223]
	ds_read_b128 v[88:91], v232 offset:13568
	ds_read_b128 v[104:107], v232 offset:12544
	ds_read_b128 v[180:183], v232 offset:13056
	v_pk_mul_f32 v[224:225], v[92:93], v[212:213] op_sel_hi:[1,0] neg_lo:[0,1] neg_hi:[0,1]
	v_pk_mul_f32 v[226:227], v[94:95], v[212:213] op_sel_hi:[1,0] neg_lo:[0,1] neg_hi:[0,1]
	v_pk_mul_f32 v[228:229], v[92:93], v[212:213] op_sel:[0,1] op_sel_hi:[1,1] neg_lo:[0,1] neg_hi:[0,1]
	v_pk_mul_f32 v[230:231], v[94:95], v[212:213] op_sel:[0,1] op_sel_hi:[1,1] neg_lo:[0,1] neg_hi:[0,1]
	v_pk_fma_f32 v[224:225], v[108:109], v[122:123], v[224:225] op_sel_hi:[1,0,1]
	v_pk_fma_f32 v[226:227], v[110:111], v[122:123], v[226:227] op_sel_hi:[1,0,1]
	v_pk_fma_f32 v[228:229], v[108:109], v[122:123], v[228:229] op_sel:[0,1,0] op_sel_hi:[1,1,1]
	v_pk_fma_f32 v[230:231], v[110:111], v[122:123], v[230:231] op_sel:[0,1,0] op_sel_hi:[1,1,1]
	v_pk_fma_f32 v[4:5], v[4:5], v[184:185], v[224:225]
	v_pk_fma_f32 v[6:7], v[6:7], v[186:187], v[226:227]
	v_pk_fma_f32 v[20:21], v[20:21], v[184:185], v[228:229]
	v_pk_fma_f32 v[22:23], v[22:23], v[186:187], v[230:231]
	ds_read_b128 v[92:95], v232 offset:13584
	ds_read_b128 v[108:111], v232 offset:12560
	ds_read_b128 v[184:187], v232 offset:13072
	v_pk_mul_f32 v[216:217], v[96:97], v[212:213] op_sel_hi:[1,0] neg_lo:[0,1] neg_hi:[0,1]
	v_pk_mul_f32 v[218:219], v[98:99], v[212:213] op_sel_hi:[1,0] neg_lo:[0,1] neg_hi:[0,1]
	v_pk_mul_f32 v[220:221], v[96:97], v[212:213] op_sel:[0,1] op_sel_hi:[1,1] neg_lo:[0,1] neg_hi:[0,1]
	v_pk_mul_f32 v[222:223], v[98:99], v[212:213] op_sel:[0,1] op_sel_hi:[1,1] neg_lo:[0,1] neg_hi:[0,1]
	v_pk_fma_f32 v[216:217], v[112:113], v[122:123], v[216:217] op_sel_hi:[1,0,1]
	v_pk_fma_f32 v[218:219], v[114:115], v[122:123], v[218:219] op_sel_hi:[1,0,1]
	v_pk_fma_f32 v[220:221], v[112:113], v[122:123], v[220:221] op_sel:[0,1,0] op_sel_hi:[1,1,1]
	v_pk_fma_f32 v[222:223], v[114:115], v[122:123], v[222:223] op_sel:[0,1,0] op_sel_hi:[1,1,1]
	v_pk_fma_f32 v[8:9], v[8:9], v[188:189], v[216:217]
	v_pk_fma_f32 v[10:11], v[10:11], v[190:191], v[218:219]
	v_pk_fma_f32 v[24:25], v[24:25], v[188:189], v[220:221]
	v_pk_fma_f32 v[26:27], v[26:27], v[190:191], v[222:223]
	ds_read_b128 v[96:99], v232 offset:13600
	ds_read_b128 v[112:115], v232 offset:12576
	ds_read_b128 v[188:191], v232 offset:13088
	v_pk_mul_f32 v[224:225], v[100:101], v[212:213] op_sel_hi:[1,0] neg_lo:[0,1] neg_hi:[0,1]
	v_pk_mul_f32 v[226:227], v[102:103], v[212:213] op_sel_hi:[1,0] neg_lo:[0,1] neg_hi:[0,1]
	v_pk_mul_f32 v[228:229], v[100:101], v[212:213] op_sel:[0,1] op_sel_hi:[1,1] neg_lo:[0,1] neg_hi:[0,1]
	v_pk_mul_f32 v[230:231], v[102:103], v[212:213] op_sel:[0,1] op_sel_hi:[1,1] neg_lo:[0,1] neg_hi:[0,1]
	v_pk_fma_f32 v[224:225], v[116:117], v[122:123], v[224:225] op_sel_hi:[1,0,1]
	v_pk_fma_f32 v[226:227], v[118:119], v[122:123], v[226:227] op_sel_hi:[1,0,1]
	v_pk_fma_f32 v[228:229], v[116:117], v[122:123], v[228:229] op_sel:[0,1,0] op_sel_hi:[1,1,1]
	v_pk_fma_f32 v[230:231], v[118:119], v[122:123], v[230:231] op_sel:[0,1,0] op_sel_hi:[1,1,1]
	v_pk_fma_f32 v[12:13], v[12:13], v[192:193], v[224:225]
	v_pk_fma_f32 v[14:15], v[14:15], v[194:195], v[226:227]
	v_pk_fma_f32 v[28:29], v[28:29], v[192:193], v[228:229]
	v_pk_fma_f32 v[30:31], v[30:31], v[194:195], v[230:231]
	ds_read_b128 v[100:103], v232 offset:13616
	ds_read_b128 v[116:119], v232 offset:12592
	ds_read_b128 v[192:195], v232 offset:13104
	s_waitcnt lgkmcnt(13)
; #define SB __builtin_amdgcn_sched_barrier(0)
; #define CMP(G, c8) { CMP1(G, 0, 2 * (c8)) CMP1(G, 1, 2 * (c8) + 1) }
; __device__ __forceinline__ void phase_scan(const Args& a, unsigned char* lds) {
;     ...
;                     f32x4 KA[8];
; #pragma unroll
;                     for (int j = 0; j < 8; ++j) KA[j] = *(const f32x4*)(vb + 256 + 4 * j);
; #pragma nounroll
;                     for (int s = 0; s < 16; ++s) {
;                         const float* vs = vb + s * 384;
;                         const float vi = vs[128 - cb + srow];
;                         f32x4 G0[8], G1[8], G2[8];
;                         LDG(G0, 0) SB;
;                         LDG(G1, 1) SB;
;                         f32x2 c0 = {0.f, 0.f}, c1 = {0.f, 0.f};
; #pragma unroll
;                         for (int j = 0; j < 8; ++j) { c0 += S2[2 * j] * (f32x2){KA[j][0], KA[j][1]}; c1 += S2[2 * j + 1] * (f32x2){KA[j][2], KA[j][3]}; }
;                         float cs = (c0.x + c0.y) + (c1.x + c1.y);
;                         cs += dpp_f(cs, 0);
;                         const float sa = -cs;
;                         const f32x2 sa2 = {sa, sa}, v2 = {vi, vi};
;                         f32x2 y0 = {0.f, 0.f}, y1 = {0.f, 0.f};
;                         SB; LDG(G2, 2) SB; CMP(G0, 0) SB;
;                         LDG(G0, 3) SB; CMP(G1, 1) SB;
;                         CMP(G2, 2) SB;
; #pragma unroll
;                         for (int j = 0; j < 8; ++j) KA[j] = *(const f32x4*)(vs + 384 + 256 + 4 * j);
;                         SB; CMP(G0, 3) SB;
;                         float ys = (y0.x + y0.y) + (y1.x + y1.y);
;                         ys += dpp_f(ys, 0);
;                         if ((lane & 1) == 0) yb[s * 64 + srow] = ys;
	v_pk_mul_f32 v[196:197], v[0:1], v[32:33]
	v_pk_mul_f32 v[200:201], v[16:17], v[32:33]
	v_pk_mul_f32 v[204:205], v[0:1], v[48:49]
	v_pk_mul_f32 v[208:209], v[16:17], v[48:49]
	v_pk_fma_f32 v[196:197], v[2:3], v[34:35], v[196:197]
	v_pk_fma_f32 v[200:201], v[18:19], v[34:35], v[200:201]
	v_pk_fma_f32 v[204:205], v[2:3], v[50:51], v[204:205]
	v_pk_fma_f32 v[208:209], v[18:19], v[50:51], v[208:209]
	ds_read_b128 v[32:35], v232 offset:14848
	ds_read_b128 v[48:51], v232 offset:12288
	v_pk_fma_f32 v[196:197], v[4:5], v[36:37], v[196:197]
	v_pk_fma_f32 v[200:201], v[20:21], v[36:37], v[200:201]
	v_pk_fma_f32 v[204:205], v[4:5], v[52:53], v[204:205]
	v_pk_fma_f32 v[208:209], v[20:21], v[52:53], v[208:209]
	v_pk_fma_f32 v[196:197], v[6:7], v[38:39], v[196:197]
	v_pk_fma_f32 v[200:201], v[22:23], v[38:39], v[200:201]
	v_pk_fma_f32 v[204:205], v[6:7], v[54:55], v[204:205]
	v_pk_fma_f32 v[208:209], v[22:23], v[54:55], v[208:209]
	ds_read_b128 v[36:39], v232 offset:14864
	ds_read_b128 v[52:55], v232 offset:12304
	v_pk_fma_f32 v[196:197], v[8:9], v[40:41], v[196:197]
	v_pk_fma_f32 v[200:201], v[24:25], v[40:41], v[200:201]
	v_pk_fma_f32 v[204:205], v[8:9], v[56:57], v[204:205]
	v_pk_fma_f32 v[208:209], v[24:25], v[56:57], v[208:209]
	v_pk_fma_f32 v[196:197], v[10:11], v[42:43], v[196:197]
	v_pk_fma_f32 v[200:201], v[26:27], v[42:43], v[200:201]
	v_pk_fma_f32 v[204:205], v[10:11], v[58:59], v[204:205]
	v_pk_fma_f32 v[208:209], v[26:27], v[58:59], v[208:209]
	ds_read_b128 v[40:43], v232 offset:14880
	ds_read_b128 v[56:59], v232 offset:12320
	v_pk_fma_f32 v[196:197], v[12:13], v[44:45], v[196:197]
	v_pk_fma_f32 v[200:201], v[28:29], v[44:45], v[200:201]
	v_pk_fma_f32 v[204:205], v[12:13], v[60:61], v[204:205]
	v_pk_fma_f32 v[208:209], v[28:29], v[60:61], v[208:209]
	v_pk_fma_f32 v[196:197], v[14:15], v[46:47], v[196:197]
	v_pk_fma_f32 v[200:201], v[30:31], v[46:47], v[200:201]
	v_pk_fma_f32 v[204:205], v[14:15], v[62:63], v[204:205]
	v_pk_fma_f32 v[208:209], v[30:31], v[62:63], v[208:209]
	ds_read_b128 v[44:47], v232 offset:14896
	ds_read_b128 v[60:63], v232 offset:12336
	v_add_f32_e32 v212, v196, v197
	v_add_f32_e32 v213, v200, v201
	v_add_f32_e32 v214, v204, v205
	v_add_f32_e32 v215, v208, v209
	v_add_f32_dpp v212, v212, v212 quad_perm:[1,0,3,2] row_mask:0xf bank_mask:0xf
	v_add_f32_dpp v213, v213, v213 quad_perm:[1,0,3,2] row_mask:0xf bank_mask:0xf
	v_add_f32_dpp v214, v214, v214 quad_perm:[1,0,3,2] row_mask:0xf bank_mask:0xf
	v_add_f32_dpp v215, v215, v215 quad_perm:[1,0,3,2] row_mask:0xf bank_mask:0xf
	v_add_f32_dpp v212, v212, v212 quad_perm:[2,3,0,1] row_mask:0xf bank_mask:0xf
	v_add_f32_dpp v213, v213, v213 quad_perm:[2,3,0,1] row_mask:0xf bank_mask:0xf
	v_add_f32_dpp v214, v214, v214 quad_perm:[2,3,0,1] row_mask:0xf bank_mask:0xf
	v_add_f32_dpp v215, v215, v215 quad_perm:[2,3,0,1] row_mask:0xf bank_mask:0xf
	ds_write_b64 v234, v[214:215] offset:1792
	s_waitcnt lgkmcnt(8)
	ds_read_b64 v[122:123], v233 offset:14336
	v_pk_mul_f32 v[216:217], v[88:89], v[212:213] op_sel_hi:[1,0] neg_lo:[0,1] neg_hi:[0,1]
	v_pk_mul_f32 v[218:219], v[90:91], v[212:213] op_sel_hi:[1,0] neg_lo:[0,1] neg_hi:[0,1]
	v_pk_mul_f32 v[220:221], v[88:89], v[212:213] op_sel:[0,1] op_sel_hi:[1,1] neg_lo:[0,1] neg_hi:[0,1]
	v_pk_mul_f32 v[222:223], v[90:91], v[212:213] op_sel:[0,1] op_sel_hi:[1,1] neg_lo:[0,1] neg_hi:[0,1]
	v_pk_fma_f32 v[216:217], v[104:105], v[120:121], v[216:217] op_sel_hi:[1,0,1]
	v_pk_fma_f32 v[218:219], v[106:107], v[120:121], v[218:219] op_sel_hi:[1,0,1]
	v_pk_fma_f32 v[220:221], v[104:105], v[120:121], v[220:221] op_sel:[0,1,0] op_sel_hi:[1,1,1]
	v_pk_fma_f32 v[222:223], v[106:107], v[120:121], v[222:223] op_sel:[0,1,0] op_sel_hi:[1,1,1]
	v_pk_fma_f32 v[0:1], v[0:1], v[180:181], v[216:217]
	v_pk_fma_f32 v[2:3], v[2:3], v[182:183], v[218:219]
	v_pk_fma_f32 v[16:17], v[16:17], v[180:181], v[220:221]
	v_pk_fma_f32 v[18:19], v[18:19], v[182:183], v[222:223]
	ds_read_b128 v[88:91], v232 offset:15104
	ds_read_b128 v[104:107], v232 offset:14080
	ds_read_b128 v[180:183], v232 offset:14592
	v_pk_mul_f32 v[224:225], v[92:93], v[212:213] op_sel_hi:[1,0] neg_lo:[0,1] neg_hi:[0,1]
	v_pk_mul_f32 v[226:227], v[94:95], v[212:213] op_sel_hi:[1,0] neg_lo:[0,1] neg_hi:[0,1]
	v_pk_mul_f32 v[228:229], v[92:93], v[212:213] op_sel:[0,1] op_sel_hi:[1,1] neg_lo:[0,1] neg_hi:[0,1]
	v_pk_mul_f32 v[230:231], v[94:95], v[212:213] op_sel:[0,1] op_sel_hi:[1,1] neg_lo:[0,1] neg_hi:[0,1]
	v_pk_fma_f32 v[224:225], v[108:109], v[120:121], v[224:225] op_sel_hi:[1,0,1]
	v_pk_fma_f32 v[226:227], v[110:111], v[120:121], v[226:227] op_sel_hi:[1,0,1]
	v_pk_fma_f32 v[228:229], v[108:109], v[120:121], v[228:229] op_sel:[0,1,0] op_sel_hi:[1,1,1]
	v_pk_fma_f32 v[230:231], v[110:111], v[120:121], v[230:231] op_sel:[0,1,0] op_sel_hi:[1,1,1]
	v_pk_fma_f32 v[4:5], v[4:5], v[184:185], v[224:225]
	v_pk_fma_f32 v[6:7], v[6:7], v[186:187], v[226:227]
	v_pk_fma_f32 v[20:21], v[20:21], v[184:185], v[228:229]
	v_pk_fma_f32 v[22:23], v[22:23], v[186:187], v[230:231]
	ds_read_b128 v[92:95], v232 offset:15120
	ds_read_b128 v[108:111], v232 offset:14096
	ds_read_b128 v[184:187], v232 offset:14608
	v_pk_mul_f32 v[216:217], v[96:97], v[212:213] op_sel_hi:[1,0] neg_lo:[0,1] neg_hi:[0,1]
	v_pk_mul_f32 v[218:219], v[98:99], v[212:213] op_sel_hi:[1,0] neg_lo:[0,1] neg_hi:[0,1]
	v_pk_mul_f32 v[220:221], v[96:97], v[212:213] op_sel:[0,1] op_sel_hi:[1,1] neg_lo:[0,1] neg_hi:[0,1]
	v_pk_mul_f32 v[222:223], v[98:99], v[212:213] op_sel:[0,1] op_sel_hi:[1,1] neg_lo:[0,1] neg_hi:[0,1]
	v_pk_fma_f32 v[216:217], v[112:113], v[120:121], v[216:217] op_sel_hi:[1,0,1]
	v_pk_fma_f32 v[218:219], v[114:115], v[120:121], v[218:219] op_sel_hi:[1,0,1]
; #define SB __builtin_amdgcn_sched_barrier(0)
; #define CMP(G, c8) { CMP1(G, 0, 2 * (c8)) CMP1(G, 1, 2 * (c8) + 1) }
; __device__ __forceinline__ void phase_scan(const Args& a, unsigned char* lds) {
;     ...
;                     f32x4 KA[8];
; #pragma unroll
;                     for (int j = 0; j < 8; ++j) KA[j] = *(const f32x4*)(vb + 256 + 4 * j);
; #pragma nounroll
;                     for (int s = 0; s < 16; ++s) {
;                         const float* vs = vb + s * 384;
;                         const float vi = vs[128 - cb + srow];
;                         f32x4 G0[8], G1[8], G2[8];
;                         LDG(G0, 0) SB;
;                         LDG(G1, 1) SB;
;                         f32x2 c0 = {0.f, 0.f}, c1 = {0.f, 0.f};
; #pragma unroll
;                         for (int j = 0; j < 8; ++j) { c0 += S2[2 * j] * (f32x2){KA[j][0], KA[j][1]}; c1 += S2[2 * j + 1] * (f32x2){KA[j][2], KA[j][3]}; }
;                         float cs = (c0.x + c0.y) + (c1.x + c1.y);
;                         cs += dpp_f(cs, 0);
;                         const float sa = -cs;
;                         const f32x2 sa2 = {sa, sa}, v2 = {vi, vi};
;                         f32x2 y0 = {0.f, 0.f}, y1 = {0.f, 0.f};
;                         SB; LDG(G2, 2) SB; CMP(G0, 0) SB;
;                         LDG(G0, 3) SB; CMP(G1, 1) SB;
;                         CMP(G2, 2) SB;
; #pragma unroll
;                         for (int j = 0; j < 8; ++j) KA[j] = *(const f32x4*)(vs + 384 + 256 + 4 * j);
;                         SB; CMP(G0, 3) SB;
;                         float ys = (y0.x + y0.y) + (y1.x + y1.y);
;                         ys += dpp_f(ys, 0);
;                         if ((lane & 1) == 0) yb[s * 64 + srow] = ys;
	v_pk_fma_f32 v[220:221], v[112:113], v[120:121], v[220:221] op_sel:[0,1,0] op_sel_hi:[1,1,1]
	v_pk_fma_f32 v[222:223], v[114:115], v[120:121], v[222:223] op_sel:[0,1,0] op_sel_hi:[1,1,1]
	v_pk_fma_f32 v[8:9], v[8:9], v[188:189], v[216:217]
	v_pk_fma_f32 v[10:11], v[10:11], v[190:191], v[218:219]
	v_pk_fma_f32 v[24:25], v[24:25], v[188:189], v[220:221]
	v_pk_fma_f32 v[26:27], v[26:27], v[190:191], v[222:223]
	ds_read_b128 v[96:99], v232 offset:15136
	ds_read_b128 v[112:115], v232 offset:14112
	ds_read_b128 v[188:191], v232 offset:14624
	v_pk_mul_f32 v[224:225], v[100:101], v[212:213] op_sel_hi:[1,0] neg_lo:[0,1] neg_hi:[0,1]
	v_pk_mul_f32 v[226:227], v[102:103], v[212:213] op_sel_hi:[1,0] neg_lo:[0,1] neg_hi:[0,1]
	v_pk_mul_f32 v[228:229], v[100:101], v[212:213] op_sel:[0,1] op_sel_hi:[1,1] neg_lo:[0,1] neg_hi:[0,1]
	v_pk_mul_f32 v[230:231], v[102:103], v[212:213] op_sel:[0,1] op_sel_hi:[1,1] neg_lo:[0,1] neg_hi:[0,1]
	v_pk_fma_f32 v[224:225], v[116:117], v[120:121], v[224:225] op_sel_hi:[1,0,1]
	v_pk_fma_f32 v[226:227], v[118:119], v[120:121], v[226:227] op_sel_hi:[1,0,1]
	v_pk_fma_f32 v[228:229], v[116:117], v[120:121], v[228:229] op_sel:[0,1,0] op_sel_hi:[1,1,1]
	v_pk_fma_f32 v[230:231], v[118:119], v[120:121], v[230:231] op_sel:[0,1,0] op_sel_hi:[1,1,1]
	v_pk_fma_f32 v[12:13], v[12:13], v[192:193], v[224:225]
	v_pk_fma_f32 v[14:15], v[14:15], v[194:195], v[226:227]
	v_pk_fma_f32 v[28:29], v[28:29], v[192:193], v[228:229]
	v_pk_fma_f32 v[30:31], v[30:31], v[194:195], v[230:231]
	ds_read_b128 v[100:103], v232 offset:15152
	ds_read_b128 v[116:119], v232 offset:14128
	ds_read_b128 v[192:195], v232 offset:14640
	s_waitcnt lgkmcnt(13)
	v_pk_mul_f32 v[196:197], v[0:1], v[32:33]
	v_pk_mul_f32 v[200:201], v[16:17], v[32:33]
	v_pk_mul_f32 v[204:205], v[0:1], v[48:49]
	v_pk_mul_f32 v[208:209], v[16:17], v[48:49]
	v_pk_fma_f32 v[196:197], v[2:3], v[34:35], v[196:197]
	v_pk_fma_f32 v[200:201], v[18:19], v[34:35], v[200:201]
	v_pk_fma_f32 v[204:205], v[2:3], v[50:51], v[204:205]
	v_pk_fma_f32 v[208:209], v[18:19], v[50:51], v[208:209]
	ds_read_b128 v[32:35], v232 offset:16384
	ds_read_b128 v[48:51], v232 offset:13824
	v_pk_fma_f32 v[196:197], v[4:5], v[36:37], v[196:197]
	v_pk_fma_f32 v[200:201], v[20:21], v[36:37], v[200:201]
	v_pk_fma_f32 v[204:205], v[4:5], v[52:53], v[204:205]
	v_pk_fma_f32 v[208:209], v[20:21], v[52:53], v[208:209]
	v_pk_fma_f32 v[196:197], v[6:7], v[38:39], v[196:197]
	v_pk_fma_f32 v[200:201], v[22:23], v[38:39], v[200:201]
	v_pk_fma_f32 v[204:205], v[6:7], v[54:55], v[204:205]
	v_pk_fma_f32 v[208:209], v[22:23], v[54:55], v[208:209]
	ds_read_b128 v[36:39], v232 offset:16400
	ds_read_b128 v[52:55], v232 offset:13840
	v_pk_fma_f32 v[196:197], v[8:9], v[40:41], v[196:197]
	v_pk_fma_f32 v[200:201], v[24:25], v[40:41], v[200:201]
	v_pk_fma_f32 v[204:205], v[8:9], v[56:57], v[204:205]
	v_pk_fma_f32 v[208:209], v[24:25], v[56:57], v[208:209]
	v_pk_fma_f32 v[196:197], v[10:11], v[42:43], v[196:197]
	v_pk_fma_f32 v[200:201], v[26:27], v[42:43], v[200:201]
	v_pk_fma_f32 v[204:205], v[10:11], v[58:59], v[204:205]
	v_pk_fma_f32 v[208:209], v[26:27], v[58:59], v[208:209]
	ds_read_b128 v[40:43], v232 offset:16416
	ds_read_b128 v[56:59], v232 offset:13856
	v_pk_fma_f32 v[196:197], v[12:13], v[44:45], v[196:197]
	v_pk_fma_f32 v[200:201], v[28:29], v[44:45], v[200:201]
	v_pk_fma_f32 v[204:205], v[12:13], v[60:61], v[204:205]
	v_pk_fma_f32 v[208:209], v[28:29], v[60:61], v[208:209]
	v_pk_fma_f32 v[196:197], v[14:15], v[46:47], v[196:197]
	v_pk_fma_f32 v[200:201], v[30:31], v[46:47], v[200:201]
	v_pk_fma_f32 v[204:205], v[14:15], v[62:63], v[204:205]
	v_pk_fma_f32 v[208:209], v[30:31], v[62:63], v[208:209]
	ds_read_b128 v[44:47], v232 offset:16432
	ds_read_b128 v[60:63], v232 offset:13872
	v_add_f32_e32 v212, v196, v197
	v_add_f32_e32 v213, v200, v201
	v_add_f32_e32 v214, v204, v205
	v_add_f32_e32 v215, v208, v209
	v_add_f32_dpp v212, v212, v212 quad_perm:[1,0,3,2] row_mask:0xf bank_mask:0xf
	v_add_f32_dpp v213, v213, v213 quad_perm:[1,0,3,2] row_mask:0xf bank_mask:0xf
	v_add_f32_dpp v214, v214, v214 quad_perm:[1,0,3,2] row_mask:0xf bank_mask:0xf
	v_add_f32_dpp v215, v215, v215 quad_perm:[1,0,3,2] row_mask:0xf bank_mask:0xf
	v_add_f32_dpp v212, v212, v212 quad_perm:[2,3,0,1] row_mask:0xf bank_mask:0xf
	v_add_f32_dpp v213, v213, v213 quad_perm:[2,3,0,1] row_mask:0xf bank_mask:0xf
	v_add_f32_dpp v214, v214, v214 quad_perm:[2,3,0,1] row_mask:0xf bank_mask:0xf
	v_add_f32_dpp v215, v215, v215 quad_perm:[2,3,0,1] row_mask:0xf bank_mask:0xf
	ds_write_b64 v234, v[214:215] offset:2048
	s_waitcnt lgkmcnt(8)
; #define SB __builtin_amdgcn_sched_barrier(0)
; #define CMP(G, c8) { CMP1(G, 0, 2 * (c8)) CMP1(G, 1, 2 * (c8) + 1) }
; __device__ __forceinline__ void phase_scan(const Args& a, unsigned char* lds) {
;     ...
;                     f32x4 KA[8];
; #pragma unroll
;                     for (int j = 0; j < 8; ++j) KA[j] = *(const f32x4*)(vb + 256 + 4 * j);
; #pragma nounroll
;                     for (int s = 0; s < 16; ++s) {
;                         const float* vs = vb + s * 384;
;                         const float vi = vs[128 - cb + srow];
;                         f32x4 G0[8], G1[8], G2[8];
;                         LDG(G0, 0) SB;
;                         LDG(G1, 1) SB;
;                         f32x2 c0 = {0.f, 0.f}, c1 = {0.f, 0.f};
; #pragma unroll
;                         for (int j = 0; j < 8; ++j) { c0 += S2[2 * j] * (f32x2){KA[j][0], KA[j][1]}; c1 += S2[2 * j + 1] * (f32x2){KA[j][2], KA[j][3]}; }
;                         float cs = (c0.x + c0.y) + (c1.x + c1.y);
;                         cs += dpp_f(cs, 0);
;                         const float sa = -cs;
;                         const f32x2 sa2 = {sa, sa}, v2 = {vi, vi};
;                         f32x2 y0 = {0.f, 0.f}, y1 = {0.f, 0.f};
;                         SB; LDG(G2, 2) SB; CMP(G0, 0) SB;
;                         LDG(G0, 3) SB; CMP(G1, 1) SB;
;                         CMP(G2, 2) SB;
; #pragma unroll
;                         for (int j = 0; j < 8; ++j) KA[j] = *(const f32x4*)(vs + 384 + 256 + 4 * j);
;                         SB; CMP(G0, 3) SB;
;                         float ys = (y0.x + y0.y) + (y1.x + y1.y);
;                         ys += dpp_f(ys, 0);
;                         if ((lane & 1) == 0) yb[s * 64 + srow] = ys;
	ds_read_b64 v[120:121], v233 offset:15872
	v_pk_mul_f32 v[216:217], v[88:89], v[212:213] op_sel_hi:[1,0] neg_lo:[0,1] neg_hi:[0,1]
	v_pk_mul_f32 v[218:219], v[90:91], v[212:213] op_sel_hi:[1,0] neg_lo:[0,1] neg_hi:[0,1]
	v_pk_mul_f32 v[220:221], v[88:89], v[212:213] op_sel:[0,1] op_sel_hi:[1,1] neg_lo:[0,1] neg_hi:[0,1]
	v_pk_mul_f32 v[222:223], v[90:91], v[212:213] op_sel:[0,1] op_sel_hi:[1,1] neg_lo:[0,1] neg_hi:[0,1]
	v_pk_fma_f32 v[216:217], v[104:105], v[122:123], v[216:217] op_sel_hi:[1,0,1]
	v_pk_fma_f32 v[218:219], v[106:107], v[122:123], v[218:219] op_sel_hi:[1,0,1]
	v_pk_fma_f32 v[220:221], v[104:105], v[122:123], v[220:221] op_sel:[0,1,0] op_sel_hi:[1,1,1]
	v_pk_fma_f32 v[222:223], v[106:107], v[122:123], v[222:223] op_sel:[0,1,0] op_sel_hi:[1,1,1]
	v_pk_fma_f32 v[0:1], v[0:1], v[180:181], v[216:217]
	v_pk_fma_f32 v[2:3], v[2:3], v[182:183], v[218:219]
	v_pk_fma_f32 v[16:17], v[16:17], v[180:181], v[220:221]
	v_pk_fma_f32 v[18:19], v[18:19], v[182:183], v[222:223]
	ds_read_b128 v[88:91], v232 offset:16640
	ds_read_b128 v[104:107], v232 offset:15616
	ds_read_b128 v[180:183], v232 offset:16128
	v_pk_mul_f32 v[224:225], v[92:93], v[212:213] op_sel_hi:[1,0] neg_lo:[0,1] neg_hi:[0,1]
	v_pk_mul_f32 v[226:227], v[94:95], v[212:213] op_sel_hi:[1,0] neg_lo:[0,1] neg_hi:[0,1]
	v_pk_mul_f32 v[228:229], v[92:93], v[212:213] op_sel:[0,1] op_sel_hi:[1,1] neg_lo:[0,1] neg_hi:[0,1]
	v_pk_mul_f32 v[230:231], v[94:95], v[212:213] op_sel:[0,1] op_sel_hi:[1,1] neg_lo:[0,1] neg_hi:[0,1]
	v_pk_fma_f32 v[224:225], v[108:109], v[122:123], v[224:225] op_sel_hi:[1,0,1]
	v_pk_fma_f32 v[226:227], v[110:111], v[122:123], v[226:227] op_sel_hi:[1,0,1]
	v_pk_fma_f32 v[228:229], v[108:109], v[122:123], v[228:229] op_sel:[0,1,0] op_sel_hi:[1,1,1]
	v_pk_fma_f32 v[230:231], v[110:111], v[122:123], v[230:231] op_sel:[0,1,0] op_sel_hi:[1,1,1]
	v_pk_fma_f32 v[4:5], v[4:5], v[184:185], v[224:225]
	v_pk_fma_f32 v[6:7], v[6:7], v[186:187], v[226:227]
	v_pk_fma_f32 v[20:21], v[20:21], v[184:185], v[228:229]
	v_pk_fma_f32 v[22:23], v[22:23], v[186:187], v[230:231]
	ds_read_b128 v[92:95], v232 offset:16656
	ds_read_b128 v[108:111], v232 offset:15632
	ds_read_b128 v[184:187], v232 offset:16144
	v_pk_mul_f32 v[216:217], v[96:97], v[212:213] op_sel_hi:[1,0] neg_lo:[0,1] neg_hi:[0,1]
	v_pk_mul_f32 v[218:219], v[98:99], v[212:213] op_sel_hi:[1,0] neg_lo:[0,1] neg_hi:[0,1]
	v_pk_mul_f32 v[220:221], v[96:97], v[212:213] op_sel:[0,1] op_sel_hi:[1,1] neg_lo:[0,1] neg_hi:[0,1]
	v_pk_mul_f32 v[222:223], v[98:99], v[212:213] op_sel:[0,1] op_sel_hi:[1,1] neg_lo:[0,1] neg_hi:[0,1]
	v_pk_fma_f32 v[216:217], v[112:113], v[122:123], v[216:217] op_sel_hi:[1,0,1]
	v_pk_fma_f32 v[218:219], v[114:115], v[122:123], v[218:219] op_sel_hi:[1,0,1]
	v_pk_fma_f32 v[220:221], v[112:113], v[122:123], v[220:221] op_sel:[0,1,0] op_sel_hi:[1,1,1]
	v_pk_fma_f32 v[222:223], v[114:115], v[122:123], v[222:223] op_sel:[0,1,0] op_sel_hi:[1,1,1]
	v_pk_fma_f32 v[8:9], v[8:9], v[188:189], v[216:217]
	v_pk_fma_f32 v[10:11], v[10:11], v[190:191], v[218:219]
	v_pk_fma_f32 v[24:25], v[24:25], v[188:189], v[220:221]
	v_pk_fma_f32 v[26:27], v[26:27], v[190:191], v[222:223]
	ds_read_b128 v[96:99], v232 offset:16672
	ds_read_b128 v[112:115], v232 offset:15648
	ds_read_b128 v[188:191], v232 offset:16160
	v_pk_mul_f32 v[224:225], v[100:101], v[212:213] op_sel_hi:[1,0] neg_lo:[0,1] neg_hi:[0,1]
	v_pk_mul_f32 v[226:227], v[102:103], v[212:213] op_sel_hi:[1,0] neg_lo:[0,1] neg_hi:[0,1]
	v_pk_mul_f32 v[228:229], v[100:101], v[212:213] op_sel:[0,1] op_sel_hi:[1,1] neg_lo:[0,1] neg_hi:[0,1]
	v_pk_mul_f32 v[230:231], v[102:103], v[212:213] op_sel:[0,1] op_sel_hi:[1,1] neg_lo:[0,1] neg_hi:[0,1]
	v_pk_fma_f32 v[224:225], v[116:117], v[122:123], v[224:225] op_sel_hi:[1,0,1]
	v_pk_fma_f32 v[226:227], v[118:119], v[122:123], v[226:227] op_sel_hi:[1,0,1]
	v_pk_fma_f32 v[228:229], v[116:117], v[122:123], v[228:229] op_sel:[0,1,0] op_sel_hi:[1,1,1]
	v_pk_fma_f32 v[230:231], v[118:119], v[122:123], v[230:231] op_sel:[0,1,0] op_sel_hi:[1,1,1]
	v_pk_fma_f32 v[12:13], v[12:13], v[192:193], v[224:225]
	v_pk_fma_f32 v[14:15], v[14:15], v[194:195], v[226:227]
	v_pk_fma_f32 v[28:29], v[28:29], v[192:193], v[228:229]
	v_pk_fma_f32 v[30:31], v[30:31], v[194:195], v[230:231]
	ds_read_b128 v[100:103], v232 offset:16688
	ds_read_b128 v[116:119], v232 offset:15664
	ds_read_b128 v[192:195], v232 offset:16176
	s_waitcnt lgkmcnt(13)
; #define SB __builtin_amdgcn_sched_barrier(0)
; #define CMP(G, c8) { CMP1(G, 0, 2 * (c8)) CMP1(G, 1, 2 * (c8) + 1) }
; __device__ __forceinline__ void phase_scan(const Args& a, unsigned char* lds) {
;     ...
;                     f32x4 KA[8];
; #pragma unroll
;                     for (int j = 0; j < 8; ++j) KA[j] = *(const f32x4*)(vb + 256 + 4 * j);
; #pragma nounroll
;                     for (int s = 0; s < 16; ++s) {
;                         const float* vs = vb + s * 384;
;                         const float vi = vs[128 - cb + srow];
;                         f32x4 G0[8], G1[8], G2[8];
;                         LDG(G0, 0) SB;
;                         LDG(G1, 1) SB;
;                         f32x2 c0 = {0.f, 0.f}, c1 = {0.f, 0.f};
; #pragma unroll
;                         for (int j = 0; j < 8; ++j) { c0 += S2[2 * j] * (f32x2){KA[j][0], KA[j][1]}; c1 += S2[2 * j + 1] * (f32x2){KA[j][2], KA[j][3]}; }
;                         float cs = (c0.x + c0.y) + (c1.x + c1.y);
;                         cs += dpp_f(cs, 0);
;                         const float sa = -cs;
;                         const f32x2 sa2 = {sa, sa}, v2 = {vi, vi};
;                         f32x2 y0 = {0.f, 0.f}, y1 = {0.f, 0.f};
;                         SB; LDG(G2, 2) SB; CMP(G0, 0) SB;
;                         LDG(G0, 3) SB; CMP(G1, 1) SB;
;                         CMP(G2, 2) SB;
; #pragma unroll
;                         for (int j = 0; j < 8; ++j) KA[j] = *(const f32x4*)(vs + 384 + 256 + 4 * j);
;                         SB; CMP(G0, 3) SB;
;                         float ys = (y0.x + y0.y) + (y1.x + y1.y);
;                         ys += dpp_f(ys, 0);
;                         if ((lane & 1) == 0) yb[s * 64 + srow] = ys;
	v_pk_mul_f32 v[196:197], v[0:1], v[32:33]
	v_pk_mul_f32 v[200:201], v[16:17], v[32:33]
	v_pk_mul_f32 v[204:205], v[0:1], v[48:49]
	v_pk_mul_f32 v[208:209], v[16:17], v[48:49]
	v_pk_fma_f32 v[196:197], v[2:3], v[34:35], v[196:197]
	v_pk_fma_f32 v[200:201], v[18:19], v[34:35], v[200:201]
	v_pk_fma_f32 v[204:205], v[2:3], v[50:51], v[204:205]
	v_pk_fma_f32 v[208:209], v[18:19], v[50:51], v[208:209]
	ds_read_b128 v[32:35], v232 offset:17920
	ds_read_b128 v[48:51], v232 offset:15360
	v_pk_fma_f32 v[196:197], v[4:5], v[36:37], v[196:197]
	v_pk_fma_f32 v[200:201], v[20:21], v[36:37], v[200:201]
	v_pk_fma_f32 v[204:205], v[4:5], v[52:53], v[204:205]
	v_pk_fma_f32 v[208:209], v[20:21], v[52:53], v[208:209]
	v_pk_fma_f32 v[196:197], v[6:7], v[38:39], v[196:197]
	v_pk_fma_f32 v[200:201], v[22:23], v[38:39], v[200:201]
	v_pk_fma_f32 v[204:205], v[6:7], v[54:55], v[204:205]
	v_pk_fma_f32 v[208:209], v[22:23], v[54:55], v[208:209]
	ds_read_b128 v[36:39], v232 offset:17936
	ds_read_b128 v[52:55], v232 offset:15376
	v_pk_fma_f32 v[196:197], v[8:9], v[40:41], v[196:197]
	v_pk_fma_f32 v[200:201], v[24:25], v[40:41], v[200:201]
	v_pk_fma_f32 v[204:205], v[8:9], v[56:57], v[204:205]
	v_pk_fma_f32 v[208:209], v[24:25], v[56:57], v[208:209]
	v_pk_fma_f32 v[196:197], v[10:11], v[42:43], v[196:197]
	v_pk_fma_f32 v[200:201], v[26:27], v[42:43], v[200:201]
	v_pk_fma_f32 v[204:205], v[10:11], v[58:59], v[204:205]
	v_pk_fma_f32 v[208:209], v[26:27], v[58:59], v[208:209]
	ds_read_b128 v[40:43], v232 offset:17952
	ds_read_b128 v[56:59], v232 offset:15392
	v_pk_fma_f32 v[196:197], v[12:13], v[44:45], v[196:197]
	v_pk_fma_f32 v[200:201], v[28:29], v[44:45], v[200:201]
	v_pk_fma_f32 v[204:205], v[12:13], v[60:61], v[204:205]
	v_pk_fma_f32 v[208:209], v[28:29], v[60:61], v[208:209]
	v_pk_fma_f32 v[196:197], v[14:15], v[46:47], v[196:197]
	v_pk_fma_f32 v[200:201], v[30:31], v[46:47], v[200:201]
	v_pk_fma_f32 v[204:205], v[14:15], v[62:63], v[204:205]
	v_pk_fma_f32 v[208:209], v[30:31], v[62:63], v[208:209]
	ds_read_b128 v[44:47], v232 offset:17968
	ds_read_b128 v[60:63], v232 offset:15408
	v_add_f32_e32 v212, v196, v197
	v_add_f32_e32 v213, v200, v201
	v_add_f32_e32 v214, v204, v205
	v_add_f32_e32 v215, v208, v209
	v_add_f32_dpp v212, v212, v212 quad_perm:[1,0,3,2] row_mask:0xf bank_mask:0xf
	v_add_f32_dpp v213, v213, v213 quad_perm:[1,0,3,2] row_mask:0xf bank_mask:0xf
	v_add_f32_dpp v214, v214, v214 quad_perm:[1,0,3,2] row_mask:0xf bank_mask:0xf
	v_add_f32_dpp v215, v215, v215 quad_perm:[1,0,3,2] row_mask:0xf bank_mask:0xf
	v_add_f32_dpp v212, v212, v212 quad_perm:[2,3,0,1] row_mask:0xf bank_mask:0xf
	v_add_f32_dpp v213, v213, v213 quad_perm:[2,3,0,1] row_mask:0xf bank_mask:0xf
	v_add_f32_dpp v214, v214, v214 quad_perm:[2,3,0,1] row_mask:0xf bank_mask:0xf
	v_add_f32_dpp v215, v215, v215 quad_perm:[2,3,0,1] row_mask:0xf bank_mask:0xf
	ds_write_b64 v234, v[214:215] offset:2304
	s_waitcnt lgkmcnt(8)
	ds_read_b64 v[122:123], v233 offset:17408
	v_pk_mul_f32 v[216:217], v[88:89], v[212:213] op_sel_hi:[1,0] neg_lo:[0,1] neg_hi:[0,1]
	v_pk_mul_f32 v[218:219], v[90:91], v[212:213] op_sel_hi:[1,0] neg_lo:[0,1] neg_hi:[0,1]
	v_pk_mul_f32 v[220:221], v[88:89], v[212:213] op_sel:[0,1] op_sel_hi:[1,1] neg_lo:[0,1] neg_hi:[0,1]
	v_pk_mul_f32 v[222:223], v[90:91], v[212:213] op_sel:[0,1] op_sel_hi:[1,1] neg_lo:[0,1] neg_hi:[0,1]
	v_pk_fma_f32 v[216:217], v[104:105], v[120:121], v[216:217] op_sel_hi:[1,0,1]
	v_pk_fma_f32 v[218:219], v[106:107], v[120:121], v[218:219] op_sel_hi:[1,0,1]
	v_pk_fma_f32 v[220:221], v[104:105], v[120:121], v[220:221] op_sel:[0,1,0] op_sel_hi:[1,1,1]
	v_pk_fma_f32 v[222:223], v[106:107], v[120:121], v[222:223] op_sel:[0,1,0] op_sel_hi:[1,1,1]
	v_pk_fma_f32 v[0:1], v[0:1], v[180:181], v[216:217]
	v_pk_fma_f32 v[2:3], v[2:3], v[182:183], v[218:219]
	v_pk_fma_f32 v[16:17], v[16:17], v[180:181], v[220:221]
	v_pk_fma_f32 v[18:19], v[18:19], v[182:183], v[222:223]
	ds_read_b128 v[88:91], v232 offset:18176
	ds_read_b128 v[104:107], v232 offset:17152
	ds_read_b128 v[180:183], v232 offset:17664
	v_pk_mul_f32 v[224:225], v[92:93], v[212:213] op_sel_hi:[1,0] neg_lo:[0,1] neg_hi:[0,1]
	v_pk_mul_f32 v[226:227], v[94:95], v[212:213] op_sel_hi:[1,0] neg_lo:[0,1] neg_hi:[0,1]
	v_pk_mul_f32 v[228:229], v[92:93], v[212:213] op_sel:[0,1] op_sel_hi:[1,1] neg_lo:[0,1] neg_hi:[0,1]
	v_pk_mul_f32 v[230:231], v[94:95], v[212:213] op_sel:[0,1] op_sel_hi:[1,1] neg_lo:[0,1] neg_hi:[0,1]
	v_pk_fma_f32 v[224:225], v[108:109], v[120:121], v[224:225] op_sel_hi:[1,0,1]
	v_pk_fma_f32 v[226:227], v[110:111], v[120:121], v[226:227] op_sel_hi:[1,0,1]
	v_pk_fma_f32 v[228:229], v[108:109], v[120:121], v[228:229] op_sel:[0,1,0] op_sel_hi:[1,1,1]
	v_pk_fma_f32 v[230:231], v[110:111], v[120:121], v[230:231] op_sel:[0,1,0] op_sel_hi:[1,1,1]
	v_pk_fma_f32 v[4:5], v[4:5], v[184:185], v[224:225]
	v_pk_fma_f32 v[6:7], v[6:7], v[186:187], v[226:227]
	v_pk_fma_f32 v[20:21], v[20:21], v[184:185], v[228:229]
	v_pk_fma_f32 v[22:23], v[22:23], v[186:187], v[230:231]
	ds_read_b128 v[92:95], v232 offset:18192
	ds_read_b128 v[108:111], v232 offset:17168
	ds_read_b128 v[184:187], v232 offset:17680
	v_pk_mul_f32 v[216:217], v[96:97], v[212:213] op_sel_hi:[1,0] neg_lo:[0,1] neg_hi:[0,1]
	v_pk_mul_f32 v[218:219], v[98:99], v[212:213] op_sel_hi:[1,0] neg_lo:[0,1] neg_hi:[0,1]
	v_pk_mul_f32 v[220:221], v[96:97], v[212:213] op_sel:[0,1] op_sel_hi:[1,1] neg_lo:[0,1] neg_hi:[0,1]
	v_pk_mul_f32 v[222:223], v[98:99], v[212:213] op_sel:[0,1] op_sel_hi:[1,1] neg_lo:[0,1] neg_hi:[0,1]
	v_pk_fma_f32 v[216:217], v[112:113], v[120:121], v[216:217] op_sel_hi:[1,0,1]
	v_pk_fma_f32 v[218:219], v[114:115], v[120:121], v[218:219] op_sel_hi:[1,0,1]
; #define SB __builtin_amdgcn_sched_barrier(0)
; #define CMP(G, c8) { CMP1(G, 0, 2 * (c8)) CMP1(G, 1, 2 * (c8) + 1) }
; __device__ __forceinline__ void phase_scan(const Args& a, unsigned char* lds) {
;     ...
;                     f32x4 KA[8];
; #pragma unroll
;                     for (int j = 0; j < 8; ++j) KA[j] = *(const f32x4*)(vb + 256 + 4 * j);
; #pragma nounroll
;                     for (int s = 0; s < 16; ++s) {
;                         const float* vs = vb + s * 384;
;                         const float vi = vs[128 - cb + srow];
;                         f32x4 G0[8], G1[8], G2[8];
;                         LDG(G0, 0) SB;
;                         LDG(G1, 1) SB;
;                         f32x2 c0 = {0.f, 0.f}, c1 = {0.f, 0.f};
; #pragma unroll
;                         for (int j = 0; j < 8; ++j) { c0 += S2[2 * j] * (f32x2){KA[j][0], KA[j][1]}; c1 += S2[2 * j + 1] * (f32x2){KA[j][2], KA[j][3]}; }
;                         float cs = (c0.x + c0.y) + (c1.x + c1.y);
;                         cs += dpp_f(cs, 0);
;                         const float sa = -cs;
;                         const f32x2 sa2 = {sa, sa}, v2 = {vi, vi};
;                         f32x2 y0 = {0.f, 0.f}, y1 = {0.f, 0.f};
;                         SB; LDG(G2, 2) SB; CMP(G0, 0) SB;
;                         LDG(G0, 3) SB; CMP(G1, 1) SB;
;                         CMP(G2, 2) SB;
; #pragma unroll
;                         for (int j = 0; j < 8; ++j) KA[j] = *(const f32x4*)(vs + 384 + 256 + 4 * j);
;                         SB; CMP(G0, 3) SB;
;                         float ys = (y0.x + y0.y) + (y1.x + y1.y);
;                         ys += dpp_f(ys, 0);
;                         if ((lane & 1) == 0) yb[s * 64 + srow] = ys;
	v_pk_fma_f32 v[220:221], v[112:113], v[120:121], v[220:221] op_sel:[0,1,0] op_sel_hi:[1,1,1]
	v_pk_fma_f32 v[222:223], v[114:115], v[120:121], v[222:223] op_sel:[0,1,0] op_sel_hi:[1,1,1]
	v_pk_fma_f32 v[8:9], v[8:9], v[188:189], v[216:217]
	v_pk_fma_f32 v[10:11], v[10:11], v[190:191], v[218:219]
	v_pk_fma_f32 v[24:25], v[24:25], v[188:189], v[220:221]
	v_pk_fma_f32 v[26:27], v[26:27], v[190:191], v[222:223]
	ds_read_b128 v[96:99], v232 offset:18208
	ds_read_b128 v[112:115], v232 offset:17184
	ds_read_b128 v[188:191], v232 offset:17696
	v_pk_mul_f32 v[224:225], v[100:101], v[212:213] op_sel_hi:[1,0] neg_lo:[0,1] neg_hi:[0,1]
	v_pk_mul_f32 v[226:227], v[102:103], v[212:213] op_sel_hi:[1,0] neg_lo:[0,1] neg_hi:[0,1]
	v_pk_mul_f32 v[228:229], v[100:101], v[212:213] op_sel:[0,1] op_sel_hi:[1,1] neg_lo:[0,1] neg_hi:[0,1]
	v_pk_mul_f32 v[230:231], v[102:103], v[212:213] op_sel:[0,1] op_sel_hi:[1,1] neg_lo:[0,1] neg_hi:[0,1]
	v_pk_fma_f32 v[224:225], v[116:117], v[120:121], v[224:225] op_sel_hi:[1,0,1]
	v_pk_fma_f32 v[226:227], v[118:119], v[120:121], v[226:227] op_sel_hi:[1,0,1]
	v_pk_fma_f32 v[228:229], v[116:117], v[120:121], v[228:229] op_sel:[0,1,0] op_sel_hi:[1,1,1]
	v_pk_fma_f32 v[230:231], v[118:119], v[120:121], v[230:231] op_sel:[0,1,0] op_sel_hi:[1,1,1]
	v_pk_fma_f32 v[12:13], v[12:13], v[192:193], v[224:225]
	v_pk_fma_f32 v[14:15], v[14:15], v[194:195], v[226:227]
	v_pk_fma_f32 v[28:29], v[28:29], v[192:193], v[228:229]
	v_pk_fma_f32 v[30:31], v[30:31], v[194:195], v[230:231]
	ds_read_b128 v[100:103], v232 offset:18224
	ds_read_b128 v[116:119], v232 offset:17200
	ds_read_b128 v[192:195], v232 offset:17712
	s_waitcnt lgkmcnt(13)
	v_pk_mul_f32 v[196:197], v[0:1], v[32:33]
	v_pk_mul_f32 v[200:201], v[16:17], v[32:33]
	v_pk_mul_f32 v[204:205], v[0:1], v[48:49]
	v_pk_mul_f32 v[208:209], v[16:17], v[48:49]
	v_pk_fma_f32 v[196:197], v[2:3], v[34:35], v[196:197]
	v_pk_fma_f32 v[200:201], v[18:19], v[34:35], v[200:201]
	v_pk_fma_f32 v[204:205], v[2:3], v[50:51], v[204:205]
	v_pk_fma_f32 v[208:209], v[18:19], v[50:51], v[208:209]
	ds_read_b128 v[32:35], v232 offset:19456
	ds_read_b128 v[48:51], v232 offset:16896
	v_pk_fma_f32 v[196:197], v[4:5], v[36:37], v[196:197]
	v_pk_fma_f32 v[200:201], v[20:21], v[36:37], v[200:201]
	v_pk_fma_f32 v[204:205], v[4:5], v[52:53], v[204:205]
	v_pk_fma_f32 v[208:209], v[20:21], v[52:53], v[208:209]
	v_pk_fma_f32 v[196:197], v[6:7], v[38:39], v[196:197]
	v_pk_fma_f32 v[200:201], v[22:23], v[38:39], v[200:201]
	v_pk_fma_f32 v[204:205], v[6:7], v[54:55], v[204:205]
	v_pk_fma_f32 v[208:209], v[22:23], v[54:55], v[208:209]
	ds_read_b128 v[36:39], v232 offset:19472
	ds_read_b128 v[52:55], v232 offset:16912
	v_pk_fma_f32 v[196:197], v[8:9], v[40:41], v[196:197]
	v_pk_fma_f32 v[200:201], v[24:25], v[40:41], v[200:201]
	v_pk_fma_f32 v[204:205], v[8:9], v[56:57], v[204:205]
	v_pk_fma_f32 v[208:209], v[24:25], v[56:57], v[208:209]
	v_pk_fma_f32 v[196:197], v[10:11], v[42:43], v[196:197]
	v_pk_fma_f32 v[200:201], v[26:27], v[42:43], v[200:201]
	v_pk_fma_f32 v[204:205], v[10:11], v[58:59], v[204:205]
	v_pk_fma_f32 v[208:209], v[26:27], v[58:59], v[208:209]
	ds_read_b128 v[40:43], v232 offset:19488
	ds_read_b128 v[56:59], v232 offset:16928
	v_pk_fma_f32 v[196:197], v[12:13], v[44:45], v[196:197]
	v_pk_fma_f32 v[200:201], v[28:29], v[44:45], v[200:201]
	v_pk_fma_f32 v[204:205], v[12:13], v[60:61], v[204:205]
	v_pk_fma_f32 v[208:209], v[28:29], v[60:61], v[208:209]
	v_pk_fma_f32 v[196:197], v[14:15], v[46:47], v[196:197]
	v_pk_fma_f32 v[200:201], v[30:31], v[46:47], v[200:201]
	v_pk_fma_f32 v[204:205], v[14:15], v[62:63], v[204:205]
	v_pk_fma_f32 v[208:209], v[30:31], v[62:63], v[208:209]
	ds_read_b128 v[44:47], v232 offset:19504
	ds_read_b128 v[60:63], v232 offset:16944
	v_add_f32_e32 v212, v196, v197
	v_add_f32_e32 v213, v200, v201
	v_add_f32_e32 v214, v204, v205
	v_add_f32_e32 v215, v208, v209
	v_add_f32_dpp v212, v212, v212 quad_perm:[1,0,3,2] row_mask:0xf bank_mask:0xf
	v_add_f32_dpp v213, v213, v213 quad_perm:[1,0,3,2] row_mask:0xf bank_mask:0xf
	v_add_f32_dpp v214, v214, v214 quad_perm:[1,0,3,2] row_mask:0xf bank_mask:0xf
	v_add_f32_dpp v215, v215, v215 quad_perm:[1,0,3,2] row_mask:0xf bank_mask:0xf
	v_add_f32_dpp v212, v212, v212 quad_perm:[2,3,0,1] row_mask:0xf bank_mask:0xf
	v_add_f32_dpp v213, v213, v213 quad_perm:[2,3,0,1] row_mask:0xf bank_mask:0xf
	v_add_f32_dpp v214, v214, v214 quad_perm:[2,3,0,1] row_mask:0xf bank_mask:0xf
	v_add_f32_dpp v215, v215, v215 quad_perm:[2,3,0,1] row_mask:0xf bank_mask:0xf
	ds_write_b64 v234, v[214:215] offset:2560
	s_waitcnt lgkmcnt(8)
; #define SB __builtin_amdgcn_sched_barrier(0)
; #define CMP(G, c8) { CMP1(G, 0, 2 * (c8)) CMP1(G, 1, 2 * (c8) + 1) }
; __device__ __forceinline__ void phase_scan(const Args& a, unsigned char* lds) {
;     ...
;                     f32x4 KA[8];
; #pragma unroll
;                     for (int j = 0; j < 8; ++j) KA[j] = *(const f32x4*)(vb + 256 + 4 * j);
; #pragma nounroll
;                     for (int s = 0; s < 16; ++s) {
;                         const float* vs = vb + s * 384;
;                         const float vi = vs[128 - cb + srow];
;                         f32x4 G0[8], G1[8], G2[8];
;                         LDG(G0, 0) SB;
;                         LDG(G1, 1) SB;
;                         f32x2 c0 = {0.f, 0.f}, c1 = {0.f, 0.f};
; #pragma unroll
;                         for (int j = 0; j < 8; ++j) { c0 += S2[2 * j] * (f32x2){KA[j][0], KA[j][1]}; c1 += S2[2 * j + 1] * (f32x2){KA[j][2], KA[j][3]}; }
;                         float cs = (c0.x + c0.y) + (c1.x + c1.y);
;                         cs += dpp_f(cs, 0);
;                         const float sa = -cs;
;                         const f32x2 sa2 = {sa, sa}, v2 = {vi, vi};
;                         f32x2 y0 = {0.f, 0.f}, y1 = {0.f, 0.f};
;                         SB; LDG(G2, 2) SB; CMP(G0, 0) SB;
;                         LDG(G0, 3) SB; CMP(G1, 1) SB;
;                         CMP(G2, 2) SB;
; #pragma unroll
;                         for (int j = 0; j < 8; ++j) KA[j] = *(const f32x4*)(vs + 384 + 256 + 4 * j);
;                         SB; CMP(G0, 3) SB;
;                         float ys = (y0.x + y0.y) + (y1.x + y1.y);
;                         ys += dpp_f(ys, 0);
;                         if ((lane & 1) == 0) yb[s * 64 + srow] = ys;
	ds_read_b64 v[120:121], v233 offset:18944
	v_pk_mul_f32 v[216:217], v[88:89], v[212:213] op_sel_hi:[1,0] neg_lo:[0,1] neg_hi:[0,1]
	v_pk_mul_f32 v[218:219], v[90:91], v[212:213] op_sel_hi:[1,0] neg_lo:[0,1] neg_hi:[0,1]
	v_pk_mul_f32 v[220:221], v[88:89], v[212:213] op_sel:[0,1] op_sel_hi:[1,1] neg_lo:[0,1] neg_hi:[0,1]
	v_pk_mul_f32 v[222:223], v[90:91], v[212:213] op_sel:[0,1] op_sel_hi:[1,1] neg_lo:[0,1] neg_hi:[0,1]
	v_pk_fma_f32 v[216:217], v[104:105], v[122:123], v[216:217] op_sel_hi:[1,0,1]
	v_pk_fma_f32 v[218:219], v[106:107], v[122:123], v[218:219] op_sel_hi:[1,0,1]
	v_pk_fma_f32 v[220:221], v[104:105], v[122:123], v[220:221] op_sel:[0,1,0] op_sel_hi:[1,1,1]
	v_pk_fma_f32 v[222:223], v[106:107], v[122:123], v[222:223] op_sel:[0,1,0] op_sel_hi:[1,1,1]
	v_pk_fma_f32 v[0:1], v[0:1], v[180:181], v[216:217]
	v_pk_fma_f32 v[2:3], v[2:3], v[182:183], v[218:219]
	v_pk_fma_f32 v[16:17], v[16:17], v[180:181], v[220:221]
	v_pk_fma_f32 v[18:19], v[18:19], v[182:183], v[222:223]
	ds_read_b128 v[88:91], v232 offset:19712
	ds_read_b128 v[104:107], v232 offset:18688
	ds_read_b128 v[180:183], v232 offset:19200
	v_pk_mul_f32 v[224:225], v[92:93], v[212:213] op_sel_hi:[1,0] neg_lo:[0,1] neg_hi:[0,1]
	v_pk_mul_f32 v[226:227], v[94:95], v[212:213] op_sel_hi:[1,0] neg_lo:[0,1] neg_hi:[0,1]
	v_pk_mul_f32 v[228:229], v[92:93], v[212:213] op_sel:[0,1] op_sel_hi:[1,1] neg_lo:[0,1] neg_hi:[0,1]
	v_pk_mul_f32 v[230:231], v[94:95], v[212:213] op_sel:[0,1] op_sel_hi:[1,1] neg_lo:[0,1] neg_hi:[0,1]
	v_pk_fma_f32 v[224:225], v[108:109], v[122:123], v[224:225] op_sel_hi:[1,0,1]
	v_pk_fma_f32 v[226:227], v[110:111], v[122:123], v[226:227] op_sel_hi:[1,0,1]
	v_pk_fma_f32 v[228:229], v[108:109], v[122:123], v[228:229] op_sel:[0,1,0] op_sel_hi:[1,1,1]
	v_pk_fma_f32 v[230:231], v[110:111], v[122:123], v[230:231] op_sel:[0,1,0] op_sel_hi:[1,1,1]
	v_pk_fma_f32 v[4:5], v[4:5], v[184:185], v[224:225]
	v_pk_fma_f32 v[6:7], v[6:7], v[186:187], v[226:227]
	v_pk_fma_f32 v[20:21], v[20:21], v[184:185], v[228:229]
	v_pk_fma_f32 v[22:23], v[22:23], v[186:187], v[230:231]
	ds_read_b128 v[92:95], v232 offset:19728
	ds_read_b128 v[108:111], v232 offset:18704
	ds_read_b128 v[184:187], v232 offset:19216
	v_pk_mul_f32 v[216:217], v[96:97], v[212:213] op_sel_hi:[1,0] neg_lo:[0,1] neg_hi:[0,1]
	v_pk_mul_f32 v[218:219], v[98:99], v[212:213] op_sel_hi:[1,0] neg_lo:[0,1] neg_hi:[0,1]
	v_pk_mul_f32 v[220:221], v[96:97], v[212:213] op_sel:[0,1] op_sel_hi:[1,1] neg_lo:[0,1] neg_hi:[0,1]
	v_pk_mul_f32 v[222:223], v[98:99], v[212:213] op_sel:[0,1] op_sel_hi:[1,1] neg_lo:[0,1] neg_hi:[0,1]
	v_pk_fma_f32 v[216:217], v[112:113], v[122:123], v[216:217] op_sel_hi:[1,0,1]
	v_pk_fma_f32 v[218:219], v[114:115], v[122:123], v[218:219] op_sel_hi:[1,0,1]
	v_pk_fma_f32 v[220:221], v[112:113], v[122:123], v[220:221] op_sel:[0,1,0] op_sel_hi:[1,1,1]
	v_pk_fma_f32 v[222:223], v[114:115], v[122:123], v[222:223] op_sel:[0,1,0] op_sel_hi:[1,1,1]
	v_pk_fma_f32 v[8:9], v[8:9], v[188:189], v[216:217]
	v_pk_fma_f32 v[10:11], v[10:11], v[190:191], v[218:219]
	v_pk_fma_f32 v[24:25], v[24:25], v[188:189], v[220:221]
	v_pk_fma_f32 v[26:27], v[26:27], v[190:191], v[222:223]
	ds_read_b128 v[96:99], v232 offset:19744
	ds_read_b128 v[112:115], v232 offset:18720
	ds_read_b128 v[188:191], v232 offset:19232
	v_pk_mul_f32 v[224:225], v[100:101], v[212:213] op_sel_hi:[1,0] neg_lo:[0,1] neg_hi:[0,1]
	v_pk_mul_f32 v[226:227], v[102:103], v[212:213] op_sel_hi:[1,0] neg_lo:[0,1] neg_hi:[0,1]
	v_pk_mul_f32 v[228:229], v[100:101], v[212:213] op_sel:[0,1] op_sel_hi:[1,1] neg_lo:[0,1] neg_hi:[0,1]
	v_pk_mul_f32 v[230:231], v[102:103], v[212:213] op_sel:[0,1] op_sel_hi:[1,1] neg_lo:[0,1] neg_hi:[0,1]
	v_pk_fma_f32 v[224:225], v[116:117], v[122:123], v[224:225] op_sel_hi:[1,0,1]
	v_pk_fma_f32 v[226:227], v[118:119], v[122:123], v[226:227] op_sel_hi:[1,0,1]
	v_pk_fma_f32 v[228:229], v[116:117], v[122:123], v[228:229] op_sel:[0,1,0] op_sel_hi:[1,1,1]
	v_pk_fma_f32 v[230:231], v[118:119], v[122:123], v[230:231] op_sel:[0,1,0] op_sel_hi:[1,1,1]
	v_pk_fma_f32 v[12:13], v[12:13], v[192:193], v[224:225]
	v_pk_fma_f32 v[14:15], v[14:15], v[194:195], v[226:227]
	v_pk_fma_f32 v[28:29], v[28:29], v[192:193], v[228:229]
	v_pk_fma_f32 v[30:31], v[30:31], v[194:195], v[230:231]
	ds_read_b128 v[100:103], v232 offset:19760
	ds_read_b128 v[116:119], v232 offset:18736
	ds_read_b128 v[192:195], v232 offset:19248
	s_waitcnt lgkmcnt(13)
; #define SB __builtin_amdgcn_sched_barrier(0)
; #define CMP(G, c8) { CMP1(G, 0, 2 * (c8)) CMP1(G, 1, 2 * (c8) + 1) }
; __device__ __forceinline__ void phase_scan(const Args& a, unsigned char* lds) {
;     ...
;                     f32x4 KA[8];
; #pragma unroll
;                     for (int j = 0; j < 8; ++j) KA[j] = *(const f32x4*)(vb + 256 + 4 * j);
; #pragma nounroll
;                     for (int s = 0; s < 16; ++s) {
;                         const float* vs = vb + s * 384;
;                         const float vi = vs[128 - cb + srow];
;                         f32x4 G0[8], G1[8], G2[8];
;                         LDG(G0, 0) SB;
;                         LDG(G1, 1) SB;
;                         f32x2 c0 = {0.f, 0.f}, c1 = {0.f, 0.f};
; #pragma unroll
;                         for (int j = 0; j < 8; ++j) { c0 += S2[2 * j] * (f32x2){KA[j][0], KA[j][1]}; c1 += S2[2 * j + 1] * (f32x2){KA[j][2], KA[j][3]}; }
;                         float cs = (c0.x + c0.y) + (c1.x + c1.y);
;                         cs += dpp_f(cs, 0);
;                         const float sa = -cs;
;                         const f32x2 sa2 = {sa, sa}, v2 = {vi, vi};
;                         f32x2 y0 = {0.f, 0.f}, y1 = {0.f, 0.f};
;                         SB; LDG(G2, 2) SB; CMP(G0, 0) SB;
;                         LDG(G0, 3) SB; CMP(G1, 1) SB;
;                         CMP(G2, 2) SB;
; #pragma unroll
;                         for (int j = 0; j < 8; ++j) KA[j] = *(const f32x4*)(vs + 384 + 256 + 4 * j);
;                         SB; CMP(G0, 3) SB;
;                         float ys = (y0.x + y0.y) + (y1.x + y1.y);
;                         ys += dpp_f(ys, 0);
;                         if ((lane & 1) == 0) yb[s * 64 + srow] = ys;
	v_pk_mul_f32 v[196:197], v[0:1], v[32:33]
	v_pk_mul_f32 v[200:201], v[16:17], v[32:33]
	v_pk_mul_f32 v[204:205], v[0:1], v[48:49]
	v_pk_mul_f32 v[208:209], v[16:17], v[48:49]
	v_pk_fma_f32 v[196:197], v[2:3], v[34:35], v[196:197]
	v_pk_fma_f32 v[200:201], v[18:19], v[34:35], v[200:201]
	v_pk_fma_f32 v[204:205], v[2:3], v[50:51], v[204:205]
	v_pk_fma_f32 v[208:209], v[18:19], v[50:51], v[208:209]
	ds_read_b128 v[32:35], v232 offset:20992
	ds_read_b128 v[48:51], v232 offset:18432
	v_pk_fma_f32 v[196:197], v[4:5], v[36:37], v[196:197]
	v_pk_fma_f32 v[200:201], v[20:21], v[36:37], v[200:201]
	v_pk_fma_f32 v[204:205], v[4:5], v[52:53], v[204:205]
	v_pk_fma_f32 v[208:209], v[20:21], v[52:53], v[208:209]
	v_pk_fma_f32 v[196:197], v[6:7], v[38:39], v[196:197]
	v_pk_fma_f32 v[200:201], v[22:23], v[38:39], v[200:201]
	v_pk_fma_f32 v[204:205], v[6:7], v[54:55], v[204:205]
	v_pk_fma_f32 v[208:209], v[22:23], v[54:55], v[208:209]
	ds_read_b128 v[36:39], v232 offset:21008
	ds_read_b128 v[52:55], v232 offset:18448
	v_pk_fma_f32 v[196:197], v[8:9], v[40:41], v[196:197]
	v_pk_fma_f32 v[200:201], v[24:25], v[40:41], v[200:201]
	v_pk_fma_f32 v[204:205], v[8:9], v[56:57], v[204:205]
	v_pk_fma_f32 v[208:209], v[24:25], v[56:57], v[208:209]
	v_pk_fma_f32 v[196:197], v[10:11], v[42:43], v[196:197]
	v_pk_fma_f32 v[200:201], v[26:27], v[42:43], v[200:201]
	v_pk_fma_f32 v[204:205], v[10:11], v[58:59], v[204:205]
	v_pk_fma_f32 v[208:209], v[26:27], v[58:59], v[208:209]
	ds_read_b128 v[40:43], v232 offset:21024
	ds_read_b128 v[56:59], v232 offset:18464
	v_pk_fma_f32 v[196:197], v[12:13], v[44:45], v[196:197]
	v_pk_fma_f32 v[200:201], v[28:29], v[44:45], v[200:201]
	v_pk_fma_f32 v[204:205], v[12:13], v[60:61], v[204:205]
	v_pk_fma_f32 v[208:209], v[28:29], v[60:61], v[208:209]
	v_pk_fma_f32 v[196:197], v[14:15], v[46:47], v[196:197]
	v_pk_fma_f32 v[200:201], v[30:31], v[46:47], v[200:201]
	v_pk_fma_f32 v[204:205], v[14:15], v[62:63], v[204:205]
	v_pk_fma_f32 v[208:209], v[30:31], v[62:63], v[208:209]
	ds_read_b128 v[44:47], v232 offset:21040
	ds_read_b128 v[60:63], v232 offset:18480
	v_add_f32_e32 v212, v196, v197
	v_add_f32_e32 v213, v200, v201
	v_add_f32_e32 v214, v204, v205
	v_add_f32_e32 v215, v208, v209
	v_add_f32_dpp v212, v212, v212 quad_perm:[1,0,3,2] row_mask:0xf bank_mask:0xf
	v_add_f32_dpp v213, v213, v213 quad_perm:[1,0,3,2] row_mask:0xf bank_mask:0xf
	v_add_f32_dpp v214, v214, v214 quad_perm:[1,0,3,2] row_mask:0xf bank_mask:0xf
	v_add_f32_dpp v215, v215, v215 quad_perm:[1,0,3,2] row_mask:0xf bank_mask:0xf
	v_add_f32_dpp v212, v212, v212 quad_perm:[2,3,0,1] row_mask:0xf bank_mask:0xf
	v_add_f32_dpp v213, v213, v213 quad_perm:[2,3,0,1] row_mask:0xf bank_mask:0xf
	v_add_f32_dpp v214, v214, v214 quad_perm:[2,3,0,1] row_mask:0xf bank_mask:0xf
	v_add_f32_dpp v215, v215, v215 quad_perm:[2,3,0,1] row_mask:0xf bank_mask:0xf
	ds_write_b64 v234, v[214:215] offset:2816
	s_waitcnt lgkmcnt(8)
	ds_read_b64 v[122:123], v233 offset:20480
	v_pk_mul_f32 v[216:217], v[88:89], v[212:213] op_sel_hi:[1,0] neg_lo:[0,1] neg_hi:[0,1]
	v_pk_mul_f32 v[218:219], v[90:91], v[212:213] op_sel_hi:[1,0] neg_lo:[0,1] neg_hi:[0,1]
	v_pk_mul_f32 v[220:221], v[88:89], v[212:213] op_sel:[0,1] op_sel_hi:[1,1] neg_lo:[0,1] neg_hi:[0,1]
	v_pk_mul_f32 v[222:223], v[90:91], v[212:213] op_sel:[0,1] op_sel_hi:[1,1] neg_lo:[0,1] neg_hi:[0,1]
	v_pk_fma_f32 v[216:217], v[104:105], v[120:121], v[216:217] op_sel_hi:[1,0,1]
	v_pk_fma_f32 v[218:219], v[106:107], v[120:121], v[218:219] op_sel_hi:[1,0,1]
	v_pk_fma_f32 v[220:221], v[104:105], v[120:121], v[220:221] op_sel:[0,1,0] op_sel_hi:[1,1,1]
	v_pk_fma_f32 v[222:223], v[106:107], v[120:121], v[222:223] op_sel:[0,1,0] op_sel_hi:[1,1,1]
	v_pk_fma_f32 v[0:1], v[0:1], v[180:181], v[216:217]
	v_pk_fma_f32 v[2:3], v[2:3], v[182:183], v[218:219]
	v_pk_fma_f32 v[16:17], v[16:17], v[180:181], v[220:221]
	v_pk_fma_f32 v[18:19], v[18:19], v[182:183], v[222:223]
	ds_read_b128 v[88:91], v232 offset:21248
	ds_read_b128 v[104:107], v232 offset:20224
	ds_read_b128 v[180:183], v232 offset:20736
	v_pk_mul_f32 v[224:225], v[92:93], v[212:213] op_sel_hi:[1,0] neg_lo:[0,1] neg_hi:[0,1]
	v_pk_mul_f32 v[226:227], v[94:95], v[212:213] op_sel_hi:[1,0] neg_lo:[0,1] neg_hi:[0,1]
	v_pk_mul_f32 v[228:229], v[92:93], v[212:213] op_sel:[0,1] op_sel_hi:[1,1] neg_lo:[0,1] neg_hi:[0,1]
	v_pk_mul_f32 v[230:231], v[94:95], v[212:213] op_sel:[0,1] op_sel_hi:[1,1] neg_lo:[0,1] neg_hi:[0,1]
	v_pk_fma_f32 v[224:225], v[108:109], v[120:121], v[224:225] op_sel_hi:[1,0,1]
	v_pk_fma_f32 v[226:227], v[110:111], v[120:121], v[226:227] op_sel_hi:[1,0,1]
	v_pk_fma_f32 v[228:229], v[108:109], v[120:121], v[228:229] op_sel:[0,1,0] op_sel_hi:[1,1,1]
	v_pk_fma_f32 v[230:231], v[110:111], v[120:121], v[230:231] op_sel:[0,1,0] op_sel_hi:[1,1,1]
	v_pk_fma_f32 v[4:5], v[4:5], v[184:185], v[224:225]
	v_pk_fma_f32 v[6:7], v[6:7], v[186:187], v[226:227]
	v_pk_fma_f32 v[20:21], v[20:21], v[184:185], v[228:229]
	v_pk_fma_f32 v[22:23], v[22:23], v[186:187], v[230:231]
	ds_read_b128 v[92:95], v232 offset:21264
	ds_read_b128 v[108:111], v232 offset:20240
	ds_read_b128 v[184:187], v232 offset:20752
	v_pk_mul_f32 v[216:217], v[96:97], v[212:213] op_sel_hi:[1,0] neg_lo:[0,1] neg_hi:[0,1]
	v_pk_mul_f32 v[218:219], v[98:99], v[212:213] op_sel_hi:[1,0] neg_lo:[0,1] neg_hi:[0,1]
	v_pk_mul_f32 v[220:221], v[96:97], v[212:213] op_sel:[0,1] op_sel_hi:[1,1] neg_lo:[0,1] neg_hi:[0,1]
	v_pk_mul_f32 v[222:223], v[98:99], v[212:213] op_sel:[0,1] op_sel_hi:[1,1] neg_lo:[0,1] neg_hi:[0,1]
	v_pk_fma_f32 v[216:217], v[112:113], v[120:121], v[216:217] op_sel_hi:[1,0,1]
	v_pk_fma_f32 v[218:219], v[114:115], v[120:121], v[218:219] op_sel_hi:[1,0,1]
; #define SB __builtin_amdgcn_sched_barrier(0)
; #define CMP(G, c8) { CMP1(G, 0, 2 * (c8)) CMP1(G, 1, 2 * (c8) + 1) }
; __device__ __forceinline__ void phase_scan(const Args& a, unsigned char* lds) {
;     ...
;                     f32x4 KA[8];
; #pragma unroll
;                     for (int j = 0; j < 8; ++j) KA[j] = *(const f32x4*)(vb + 256 + 4 * j);
; #pragma nounroll
;                     for (int s = 0; s < 16; ++s) {
;                         const float* vs = vb + s * 384;
;                         const float vi = vs[128 - cb + srow];
;                         f32x4 G0[8], G1[8], G2[8];
;                         LDG(G0, 0) SB;
;                         LDG(G1, 1) SB;
;                         f32x2 c0 = {0.f, 0.f}, c1 = {0.f, 0.f};
; #pragma unroll
;                         for (int j = 0; j < 8; ++j) { c0 += S2[2 * j] * (f32x2){KA[j][0], KA[j][1]}; c1 += S2[2 * j + 1] * (f32x2){KA[j][2], KA[j][3]}; }
;                         float cs = (c0.x + c0.y) + (c1.x + c1.y);
;                         cs += dpp_f(cs, 0);
;                         const float sa = -cs;
;                         const f32x2 sa2 = {sa, sa}, v2 = {vi, vi};
;                         f32x2 y0 = {0.f, 0.f}, y1 = {0.f, 0.f};
;                         SB; LDG(G2, 2) SB; CMP(G0, 0) SB;
;                         LDG(G0, 3) SB; CMP(G1, 1) SB;
;                         CMP(G2, 2) SB;
; #pragma unroll
;                         for (int j = 0; j < 8; ++j) KA[j] = *(const f32x4*)(vs + 384 + 256 + 4 * j);
;                         SB; CMP(G0, 3) SB;
;                         float ys = (y0.x + y0.y) + (y1.x + y1.y);
;                         ys += dpp_f(ys, 0);
;                         if ((lane & 1) == 0) yb[s * 64 + srow] = ys;
	v_pk_fma_f32 v[220:221], v[112:113], v[120:121], v[220:221] op_sel:[0,1,0] op_sel_hi:[1,1,1]
	v_pk_fma_f32 v[222:223], v[114:115], v[120:121], v[222:223] op_sel:[0,1,0] op_sel_hi:[1,1,1]
	v_pk_fma_f32 v[8:9], v[8:9], v[188:189], v[216:217]
	v_pk_fma_f32 v[10:11], v[10:11], v[190:191], v[218:219]
	v_pk_fma_f32 v[24:25], v[24:25], v[188:189], v[220:221]
	v_pk_fma_f32 v[26:27], v[26:27], v[190:191], v[222:223]
	ds_read_b128 v[96:99], v232 offset:21280
	ds_read_b128 v[112:115], v232 offset:20256
	ds_read_b128 v[188:191], v232 offset:20768
	v_pk_mul_f32 v[224:225], v[100:101], v[212:213] op_sel_hi:[1,0] neg_lo:[0,1] neg_hi:[0,1]
	v_pk_mul_f32 v[226:227], v[102:103], v[212:213] op_sel_hi:[1,0] neg_lo:[0,1] neg_hi:[0,1]
	v_pk_mul_f32 v[228:229], v[100:101], v[212:213] op_sel:[0,1] op_sel_hi:[1,1] neg_lo:[0,1] neg_hi:[0,1]
	v_pk_mul_f32 v[230:231], v[102:103], v[212:213] op_sel:[0,1] op_sel_hi:[1,1] neg_lo:[0,1] neg_hi:[0,1]
	v_pk_fma_f32 v[224:225], v[116:117], v[120:121], v[224:225] op_sel_hi:[1,0,1]
	v_pk_fma_f32 v[226:227], v[118:119], v[120:121], v[226:227] op_sel_hi:[1,0,1]
	v_pk_fma_f32 v[228:229], v[116:117], v[120:121], v[228:229] op_sel:[0,1,0] op_sel_hi:[1,1,1]
	v_pk_fma_f32 v[230:231], v[118:119], v[120:121], v[230:231] op_sel:[0,1,0] op_sel_hi:[1,1,1]
	v_pk_fma_f32 v[12:13], v[12:13], v[192:193], v[224:225]
	v_pk_fma_f32 v[14:15], v[14:15], v[194:195], v[226:227]
	v_pk_fma_f32 v[28:29], v[28:29], v[192:193], v[228:229]
	v_pk_fma_f32 v[30:31], v[30:31], v[194:195], v[230:231]
	ds_read_b128 v[100:103], v232 offset:21296
	ds_read_b128 v[116:119], v232 offset:20272
	ds_read_b128 v[192:195], v232 offset:20784
	s_waitcnt lgkmcnt(13)
	v_pk_mul_f32 v[196:197], v[0:1], v[32:33]
	v_pk_mul_f32 v[200:201], v[16:17], v[32:33]
	v_pk_mul_f32 v[204:205], v[0:1], v[48:49]
	v_pk_mul_f32 v[208:209], v[16:17], v[48:49]
	v_pk_fma_f32 v[196:197], v[2:3], v[34:35], v[196:197]
	v_pk_fma_f32 v[200:201], v[18:19], v[34:35], v[200:201]
	v_pk_fma_f32 v[204:205], v[2:3], v[50:51], v[204:205]
	v_pk_fma_f32 v[208:209], v[18:19], v[50:51], v[208:209]
	ds_read_b128 v[32:35], v232 offset:22528
	ds_read_b128 v[48:51], v232 offset:19968
	v_pk_fma_f32 v[196:197], v[4:5], v[36:37], v[196:197]
	v_pk_fma_f32 v[200:201], v[20:21], v[36:37], v[200:201]
	v_pk_fma_f32 v[204:205], v[4:5], v[52:53], v[204:205]
	v_pk_fma_f32 v[208:209], v[20:21], v[52:53], v[208:209]
	v_pk_fma_f32 v[196:197], v[6:7], v[38:39], v[196:197]
	v_pk_fma_f32 v[200:201], v[22:23], v[38:39], v[200:201]
	v_pk_fma_f32 v[204:205], v[6:7], v[54:55], v[204:205]
	v_pk_fma_f32 v[208:209], v[22:23], v[54:55], v[208:209]
	ds_read_b128 v[36:39], v232 offset:22544
	ds_read_b128 v[52:55], v232 offset:19984
	v_pk_fma_f32 v[196:197], v[8:9], v[40:41], v[196:197]
	v_pk_fma_f32 v[200:201], v[24:25], v[40:41], v[200:201]
	v_pk_fma_f32 v[204:205], v[8:9], v[56:57], v[204:205]
	v_pk_fma_f32 v[208:209], v[24:25], v[56:57], v[208:209]
	v_pk_fma_f32 v[196:197], v[10:11], v[42:43], v[196:197]
	v_pk_fma_f32 v[200:201], v[26:27], v[42:43], v[200:201]
	v_pk_fma_f32 v[204:205], v[10:11], v[58:59], v[204:205]
	v_pk_fma_f32 v[208:209], v[26:27], v[58:59], v[208:209]
	ds_read_b128 v[40:43], v232 offset:22560
	ds_read_b128 v[56:59], v232 offset:20000
	v_pk_fma_f32 v[196:197], v[12:13], v[44:45], v[196:197]
	v_pk_fma_f32 v[200:201], v[28:29], v[44:45], v[200:201]
	v_pk_fma_f32 v[204:205], v[12:13], v[60:61], v[204:205]
	v_pk_fma_f32 v[208:209], v[28:29], v[60:61], v[208:209]
	v_pk_fma_f32 v[196:197], v[14:15], v[46:47], v[196:197]
	v_pk_fma_f32 v[200:201], v[30:31], v[46:47], v[200:201]
	v_pk_fma_f32 v[204:205], v[14:15], v[62:63], v[204:205]
	v_pk_fma_f32 v[208:209], v[30:31], v[62:63], v[208:209]
	ds_read_b128 v[44:47], v232 offset:22576
	ds_read_b128 v[60:63], v232 offset:20016
	v_add_f32_e32 v212, v196, v197
	v_add_f32_e32 v213, v200, v201
	v_add_f32_e32 v214, v204, v205
	v_add_f32_e32 v215, v208, v209
	v_add_f32_dpp v212, v212, v212 quad_perm:[1,0,3,2] row_mask:0xf bank_mask:0xf
	v_add_f32_dpp v213, v213, v213 quad_perm:[1,0,3,2] row_mask:0xf bank_mask:0xf
	v_add_f32_dpp v214, v214, v214 quad_perm:[1,0,3,2] row_mask:0xf bank_mask:0xf
	v_add_f32_dpp v215, v215, v215 quad_perm:[1,0,3,2] row_mask:0xf bank_mask:0xf
	v_add_f32_dpp v212, v212, v212 quad_perm:[2,3,0,1] row_mask:0xf bank_mask:0xf
	v_add_f32_dpp v213, v213, v213 quad_perm:[2,3,0,1] row_mask:0xf bank_mask:0xf
	v_add_f32_dpp v214, v214, v214 quad_perm:[2,3,0,1] row_mask:0xf bank_mask:0xf
	v_add_f32_dpp v215, v215, v215 quad_perm:[2,3,0,1] row_mask:0xf bank_mask:0xf
	ds_write_b64 v234, v[214:215] offset:3072
	s_waitcnt lgkmcnt(8)
; #define SB __builtin_amdgcn_sched_barrier(0)
; #define CMP(G, c8) { CMP1(G, 0, 2 * (c8)) CMP1(G, 1, 2 * (c8) + 1) }
; __device__ __forceinline__ void phase_scan(const Args& a, unsigned char* lds) {
;     ...
;                     f32x4 KA[8];
; #pragma unroll
;                     for (int j = 0; j < 8; ++j) KA[j] = *(const f32x4*)(vb + 256 + 4 * j);
; #pragma nounroll
;                     for (int s = 0; s < 16; ++s) {
;                         const float* vs = vb + s * 384;
;                         const float vi = vs[128 - cb + srow];
;                         f32x4 G0[8], G1[8], G2[8];
;                         LDG(G0, 0) SB;
;                         LDG(G1, 1) SB;
;                         f32x2 c0 = {0.f, 0.f}, c1 = {0.f, 0.f};
; #pragma unroll
;                         for (int j = 0; j < 8; ++j) { c0 += S2[2 * j] * (f32x2){KA[j][0], KA[j][1]}; c1 += S2[2 * j + 1] * (f32x2){KA[j][2], KA[j][3]}; }
;                         float cs = (c0.x + c0.y) + (c1.x + c1.y);
;                         cs += dpp_f(cs, 0);
;                         const float sa = -cs;
;                         const f32x2 sa2 = {sa, sa}, v2 = {vi, vi};
;                         f32x2 y0 = {0.f, 0.f}, y1 = {0.f, 0.f};
;                         SB; LDG(G2, 2) SB; CMP(G0, 0) SB;
;                         LDG(G0, 3) SB; CMP(G1, 1) SB;
;                         CMP(G2, 2) SB;
; #pragma unroll
;                         for (int j = 0; j < 8; ++j) KA[j] = *(const f32x4*)(vs + 384 + 256 + 4 * j);
;                         SB; CMP(G0, 3) SB;
;                         float ys = (y0.x + y0.y) + (y1.x + y1.y);
;                         ys += dpp_f(ys, 0);
;                         if ((lane & 1) == 0) yb[s * 64 + srow] = ys;
	ds_read_b64 v[120:121], v233 offset:22016
	v_pk_mul_f32 v[216:217], v[88:89], v[212:213] op_sel_hi:[1,0] neg_lo:[0,1] neg_hi:[0,1]
	v_pk_mul_f32 v[218:219], v[90:91], v[212:213] op_sel_hi:[1,0] neg_lo:[0,1] neg_hi:[0,1]
	v_pk_mul_f32 v[220:221], v[88:89], v[212:213] op_sel:[0,1] op_sel_hi:[1,1] neg_lo:[0,1] neg_hi:[0,1]
	v_pk_mul_f32 v[222:223], v[90:91], v[212:213] op_sel:[0,1] op_sel_hi:[1,1] neg_lo:[0,1] neg_hi:[0,1]
	v_pk_fma_f32 v[216:217], v[104:105], v[122:123], v[216:217] op_sel_hi:[1,0,1]
	v_pk_fma_f32 v[218:219], v[106:107], v[122:123], v[218:219] op_sel_hi:[1,0,1]
	v_pk_fma_f32 v[220:221], v[104:105], v[122:123], v[220:221] op_sel:[0,1,0] op_sel_hi:[1,1,1]
	v_pk_fma_f32 v[222:223], v[106:107], v[122:123], v[222:223] op_sel:[0,1,0] op_sel_hi:[1,1,1]
	v_pk_fma_f32 v[0:1], v[0:1], v[180:181], v[216:217]
	v_pk_fma_f32 v[2:3], v[2:3], v[182:183], v[218:219]
	v_pk_fma_f32 v[16:17], v[16:17], v[180:181], v[220:221]
	v_pk_fma_f32 v[18:19], v[18:19], v[182:183], v[222:223]
	ds_read_b128 v[88:91], v232 offset:22784
	ds_read_b128 v[104:107], v232 offset:21760
	ds_read_b128 v[180:183], v232 offset:22272
	v_pk_mul_f32 v[224:225], v[92:93], v[212:213] op_sel_hi:[1,0] neg_lo:[0,1] neg_hi:[0,1]
	v_pk_mul_f32 v[226:227], v[94:95], v[212:213] op_sel_hi:[1,0] neg_lo:[0,1] neg_hi:[0,1]
	v_pk_mul_f32 v[228:229], v[92:93], v[212:213] op_sel:[0,1] op_sel_hi:[1,1] neg_lo:[0,1] neg_hi:[0,1]
	v_pk_mul_f32 v[230:231], v[94:95], v[212:213] op_sel:[0,1] op_sel_hi:[1,1] neg_lo:[0,1] neg_hi:[0,1]
	v_pk_fma_f32 v[224:225], v[108:109], v[122:123], v[224:225] op_sel_hi:[1,0,1]
	v_pk_fma_f32 v[226:227], v[110:111], v[122:123], v[226:227] op_sel_hi:[1,0,1]
	v_pk_fma_f32 v[228:229], v[108:109], v[122:123], v[228:229] op_sel:[0,1,0] op_sel_hi:[1,1,1]
	v_pk_fma_f32 v[230:231], v[110:111], v[122:123], v[230:231] op_sel:[0,1,0] op_sel_hi:[1,1,1]
	v_pk_fma_f32 v[4:5], v[4:5], v[184:185], v[224:225]
	v_pk_fma_f32 v[6:7], v[6:7], v[186:187], v[226:227]
	v_pk_fma_f32 v[20:21], v[20:21], v[184:185], v[228:229]
	v_pk_fma_f32 v[22:23], v[22:23], v[186:187], v[230:231]
	ds_read_b128 v[92:95], v232 offset:22800
	ds_read_b128 v[108:111], v232 offset:21776
	ds_read_b128 v[184:187], v232 offset:22288
	v_pk_mul_f32 v[216:217], v[96:97], v[212:213] op_sel_hi:[1,0] neg_lo:[0,1] neg_hi:[0,1]
	v_pk_mul_f32 v[218:219], v[98:99], v[212:213] op_sel_hi:[1,0] neg_lo:[0,1] neg_hi:[0,1]
	v_pk_mul_f32 v[220:221], v[96:97], v[212:213] op_sel:[0,1] op_sel_hi:[1,1] neg_lo:[0,1] neg_hi:[0,1]
	v_pk_mul_f32 v[222:223], v[98:99], v[212:213] op_sel:[0,1] op_sel_hi:[1,1] neg_lo:[0,1] neg_hi:[0,1]
	v_pk_fma_f32 v[216:217], v[112:113], v[122:123], v[216:217] op_sel_hi:[1,0,1]
	v_pk_fma_f32 v[218:219], v[114:115], v[122:123], v[218:219] op_sel_hi:[1,0,1]
	v_pk_fma_f32 v[220:221], v[112:113], v[122:123], v[220:221] op_sel:[0,1,0] op_sel_hi:[1,1,1]
	v_pk_fma_f32 v[222:223], v[114:115], v[122:123], v[222:223] op_sel:[0,1,0] op_sel_hi:[1,1,1]
	v_pk_fma_f32 v[8:9], v[8:9], v[188:189], v[216:217]
	v_pk_fma_f32 v[10:11], v[10:11], v[190:191], v[218:219]
	v_pk_fma_f32 v[24:25], v[24:25], v[188:189], v[220:221]
	v_pk_fma_f32 v[26:27], v[26:27], v[190:191], v[222:223]
	ds_read_b128 v[96:99], v232 offset:22816
	ds_read_b128 v[112:115], v232 offset:21792
	ds_read_b128 v[188:191], v232 offset:22304
	v_pk_mul_f32 v[224:225], v[100:101], v[212:213] op_sel_hi:[1,0] neg_lo:[0,1] neg_hi:[0,1]
	v_pk_mul_f32 v[226:227], v[102:103], v[212:213] op_sel_hi:[1,0] neg_lo:[0,1] neg_hi:[0,1]
	v_pk_mul_f32 v[228:229], v[100:101], v[212:213] op_sel:[0,1] op_sel_hi:[1,1] neg_lo:[0,1] neg_hi:[0,1]
	v_pk_mul_f32 v[230:231], v[102:103], v[212:213] op_sel:[0,1] op_sel_hi:[1,1] neg_lo:[0,1] neg_hi:[0,1]
	v_pk_fma_f32 v[224:225], v[116:117], v[122:123], v[224:225] op_sel_hi:[1,0,1]
	v_pk_fma_f32 v[226:227], v[118:119], v[122:123], v[226:227] op_sel_hi:[1,0,1]
	v_pk_fma_f32 v[228:229], v[116:117], v[122:123], v[228:229] op_sel:[0,1,0] op_sel_hi:[1,1,1]
	v_pk_fma_f32 v[230:231], v[118:119], v[122:123], v[230:231] op_sel:[0,1,0] op_sel_hi:[1,1,1]
	v_pk_fma_f32 v[12:13], v[12:13], v[192:193], v[224:225]
	v_pk_fma_f32 v[14:15], v[14:15], v[194:195], v[226:227]
	v_pk_fma_f32 v[28:29], v[28:29], v[192:193], v[228:229]
	v_pk_fma_f32 v[30:31], v[30:31], v[194:195], v[230:231]
	ds_read_b128 v[100:103], v232 offset:22832
	ds_read_b128 v[116:119], v232 offset:21808
	ds_read_b128 v[192:195], v232 offset:22320
	s_waitcnt lgkmcnt(13)
; #define SB __builtin_amdgcn_sched_barrier(0)
; #define CMP(G, c8) { CMP1(G, 0, 2 * (c8)) CMP1(G, 1, 2 * (c8) + 1) }
; __device__ __forceinline__ void phase_scan(const Args& a, unsigned char* lds) {
;     ...
;                     f32x4 KA[8];
; #pragma unroll
;                     for (int j = 0; j < 8; ++j) KA[j] = *(const f32x4*)(vb + 256 + 4 * j);
; #pragma nounroll
;                     for (int s = 0; s < 16; ++s) {
;                         const float* vs = vb + s * 384;
;                         const float vi = vs[128 - cb + srow];
;                         f32x4 G0[8], G1[8], G2[8];
;                         LDG(G0, 0) SB;
;                         LDG(G1, 1) SB;
;                         f32x2 c0 = {0.f, 0.f}, c1 = {0.f, 0.f};
; #pragma unroll
;                         for (int j = 0; j < 8; ++j) { c0 += S2[2 * j] * (f32x2){KA[j][0], KA[j][1]}; c1 += S2[2 * j + 1] * (f32x2){KA[j][2], KA[j][3]}; }
;                         float cs = (c0.x + c0.y) + (c1.x + c1.y);
;                         cs += dpp_f(cs, 0);
;                         const float sa = -cs;
;                         const f32x2 sa2 = {sa, sa}, v2 = {vi, vi};
;                         f32x2 y0 = {0.f, 0.f}, y1 = {0.f, 0.f};
;                         SB; LDG(G2, 2) SB; CMP(G0, 0) SB;
;                         LDG(G0, 3) SB; CMP(G1, 1) SB;
;                         CMP(G2, 2) SB;
; #pragma unroll
;                         for (int j = 0; j < 8; ++j) KA[j] = *(const f32x4*)(vs + 384 + 256 + 4 * j);
;                         SB; CMP(G0, 3) SB;
;                         float ys = (y0.x + y0.y) + (y1.x + y1.y);
;                         ys += dpp_f(ys, 0);
;                         if ((lane & 1) == 0) yb[s * 64 + srow] = ys;
	v_pk_mul_f32 v[196:197], v[0:1], v[32:33]
	v_pk_mul_f32 v[200:201], v[16:17], v[32:33]
	v_pk_mul_f32 v[204:205], v[0:1], v[48:49]
	v_pk_mul_f32 v[208:209], v[16:17], v[48:49]
	v_pk_fma_f32 v[196:197], v[2:3], v[34:35], v[196:197]
	v_pk_fma_f32 v[200:201], v[18:19], v[34:35], v[200:201]
	v_pk_fma_f32 v[204:205], v[2:3], v[50:51], v[204:205]
	v_pk_fma_f32 v[208:209], v[18:19], v[50:51], v[208:209]
	ds_read_b128 v[32:35], v232 offset:24064
	ds_read_b128 v[48:51], v232 offset:21504
	v_pk_fma_f32 v[196:197], v[4:5], v[36:37], v[196:197]
	v_pk_fma_f32 v[200:201], v[20:21], v[36:37], v[200:201]
	v_pk_fma_f32 v[204:205], v[4:5], v[52:53], v[204:205]
	v_pk_fma_f32 v[208:209], v[20:21], v[52:53], v[208:209]
	v_pk_fma_f32 v[196:197], v[6:7], v[38:39], v[196:197]
	v_pk_fma_f32 v[200:201], v[22:23], v[38:39], v[200:201]
	v_pk_fma_f32 v[204:205], v[6:7], v[54:55], v[204:205]
	v_pk_fma_f32 v[208:209], v[22:23], v[54:55], v[208:209]
	ds_read_b128 v[36:39], v232 offset:24080
	ds_read_b128 v[52:55], v232 offset:21520
	v_pk_fma_f32 v[196:197], v[8:9], v[40:41], v[196:197]
	v_pk_fma_f32 v[200:201], v[24:25], v[40:41], v[200:201]
	v_pk_fma_f32 v[204:205], v[8:9], v[56:57], v[204:205]
	v_pk_fma_f32 v[208:209], v[24:25], v[56:57], v[208:209]
	v_pk_fma_f32 v[196:197], v[10:11], v[42:43], v[196:197]
	v_pk_fma_f32 v[200:201], v[26:27], v[42:43], v[200:201]
	v_pk_fma_f32 v[204:205], v[10:11], v[58:59], v[204:205]
	v_pk_fma_f32 v[208:209], v[26:27], v[58:59], v[208:209]
	ds_read_b128 v[40:43], v232 offset:24096
	ds_read_b128 v[56:59], v232 offset:21536
	v_pk_fma_f32 v[196:197], v[12:13], v[44:45], v[196:197]
	v_pk_fma_f32 v[200:201], v[28:29], v[44:45], v[200:201]
	v_pk_fma_f32 v[204:205], v[12:13], v[60:61], v[204:205]
	v_pk_fma_f32 v[208:209], v[28:29], v[60:61], v[208:209]
	v_pk_fma_f32 v[196:197], v[14:15], v[46:47], v[196:197]
	v_pk_fma_f32 v[200:201], v[30:31], v[46:47], v[200:201]
	v_pk_fma_f32 v[204:205], v[14:15], v[62:63], v[204:205]
	v_pk_fma_f32 v[208:209], v[30:31], v[62:63], v[208:209]
	ds_read_b128 v[44:47], v232 offset:24112
	ds_read_b128 v[60:63], v232 offset:21552
	v_add_f32_e32 v212, v196, v197
	v_add_f32_e32 v213, v200, v201
	v_add_f32_e32 v214, v204, v205
	v_add_f32_e32 v215, v208, v209
	v_add_f32_dpp v212, v212, v212 quad_perm:[1,0,3,2] row_mask:0xf bank_mask:0xf
	v_add_f32_dpp v213, v213, v213 quad_perm:[1,0,3,2] row_mask:0xf bank_mask:0xf
	v_add_f32_dpp v214, v214, v214 quad_perm:[1,0,3,2] row_mask:0xf bank_mask:0xf
	v_add_f32_dpp v215, v215, v215 quad_perm:[1,0,3,2] row_mask:0xf bank_mask:0xf
	v_add_f32_dpp v212, v212, v212 quad_perm:[2,3,0,1] row_mask:0xf bank_mask:0xf
	v_add_f32_dpp v213, v213, v213 quad_perm:[2,3,0,1] row_mask:0xf bank_mask:0xf
	v_add_f32_dpp v214, v214, v214 quad_perm:[2,3,0,1] row_mask:0xf bank_mask:0xf
	v_add_f32_dpp v215, v215, v215 quad_perm:[2,3,0,1] row_mask:0xf bank_mask:0xf
	ds_write_b64 v234, v[214:215] offset:3328
	s_waitcnt lgkmcnt(8)
	ds_read_b64 v[122:123], v233 offset:23552
	v_pk_mul_f32 v[216:217], v[88:89], v[212:213] op_sel_hi:[1,0] neg_lo:[0,1] neg_hi:[0,1]
	v_pk_mul_f32 v[218:219], v[90:91], v[212:213] op_sel_hi:[1,0] neg_lo:[0,1] neg_hi:[0,1]
	v_pk_mul_f32 v[220:221], v[88:89], v[212:213] op_sel:[0,1] op_sel_hi:[1,1] neg_lo:[0,1] neg_hi:[0,1]
	v_pk_mul_f32 v[222:223], v[90:91], v[212:213] op_sel:[0,1] op_sel_hi:[1,1] neg_lo:[0,1] neg_hi:[0,1]
	v_pk_fma_f32 v[216:217], v[104:105], v[120:121], v[216:217] op_sel_hi:[1,0,1]
	v_pk_fma_f32 v[218:219], v[106:107], v[120:121], v[218:219] op_sel_hi:[1,0,1]
	v_pk_fma_f32 v[220:221], v[104:105], v[120:121], v[220:221] op_sel:[0,1,0] op_sel_hi:[1,1,1]
	v_pk_fma_f32 v[222:223], v[106:107], v[120:121], v[222:223] op_sel:[0,1,0] op_sel_hi:[1,1,1]
	v_pk_fma_f32 v[0:1], v[0:1], v[180:181], v[216:217]
	v_pk_fma_f32 v[2:3], v[2:3], v[182:183], v[218:219]
	v_pk_fma_f32 v[16:17], v[16:17], v[180:181], v[220:221]
	v_pk_fma_f32 v[18:19], v[18:19], v[182:183], v[222:223]
	ds_read_b128 v[88:91], v232 offset:24320
	ds_read_b128 v[104:107], v232 offset:23296
	ds_read_b128 v[180:183], v232 offset:23808
	v_pk_mul_f32 v[224:225], v[92:93], v[212:213] op_sel_hi:[1,0] neg_lo:[0,1] neg_hi:[0,1]
	v_pk_mul_f32 v[226:227], v[94:95], v[212:213] op_sel_hi:[1,0] neg_lo:[0,1] neg_hi:[0,1]
	v_pk_mul_f32 v[228:229], v[92:93], v[212:213] op_sel:[0,1] op_sel_hi:[1,1] neg_lo:[0,1] neg_hi:[0,1]
	v_pk_mul_f32 v[230:231], v[94:95], v[212:213] op_sel:[0,1] op_sel_hi:[1,1] neg_lo:[0,1] neg_hi:[0,1]
	v_pk_fma_f32 v[224:225], v[108:109], v[120:121], v[224:225] op_sel_hi:[1,0,1]
	v_pk_fma_f32 v[226:227], v[110:111], v[120:121], v[226:227] op_sel_hi:[1,0,1]
	v_pk_fma_f32 v[228:229], v[108:109], v[120:121], v[228:229] op_sel:[0,1,0] op_sel_hi:[1,1,1]
	v_pk_fma_f32 v[230:231], v[110:111], v[120:121], v[230:231] op_sel:[0,1,0] op_sel_hi:[1,1,1]
	v_pk_fma_f32 v[4:5], v[4:5], v[184:185], v[224:225]
	v_pk_fma_f32 v[6:7], v[6:7], v[186:187], v[226:227]
	v_pk_fma_f32 v[20:21], v[20:21], v[184:185], v[228:229]
	v_pk_fma_f32 v[22:23], v[22:23], v[186:187], v[230:231]
	ds_read_b128 v[92:95], v232 offset:24336
	ds_read_b128 v[108:111], v232 offset:23312
	ds_read_b128 v[184:187], v232 offset:23824
	v_pk_mul_f32 v[216:217], v[96:97], v[212:213] op_sel_hi:[1,0] neg_lo:[0,1] neg_hi:[0,1]
	v_pk_mul_f32 v[218:219], v[98:99], v[212:213] op_sel_hi:[1,0] neg_lo:[0,1] neg_hi:[0,1]
	v_pk_mul_f32 v[220:221], v[96:97], v[212:213] op_sel:[0,1] op_sel_hi:[1,1] neg_lo:[0,1] neg_hi:[0,1]
	v_pk_mul_f32 v[222:223], v[98:99], v[212:213] op_sel:[0,1] op_sel_hi:[1,1] neg_lo:[0,1] neg_hi:[0,1]
	v_pk_fma_f32 v[216:217], v[112:113], v[120:121], v[216:217] op_sel_hi:[1,0,1]
	v_pk_fma_f32 v[218:219], v[114:115], v[120:121], v[218:219] op_sel_hi:[1,0,1]
; #define SB __builtin_amdgcn_sched_barrier(0)
; #define CMP(G, c8) { CMP1(G, 0, 2 * (c8)) CMP1(G, 1, 2 * (c8) + 1) }
; __device__ __forceinline__ void phase_scan(const Args& a, unsigned char* lds) {
;     ...
;                     f32x4 KA[8];
; #pragma unroll
;                     for (int j = 0; j < 8; ++j) KA[j] = *(const f32x4*)(vb + 256 + 4 * j);
; #pragma nounroll
;                     for (int s = 0; s < 16; ++s) {
;                         const float* vs = vb + s * 384;
;                         const float vi = vs[128 - cb + srow];
;                         f32x4 G0[8], G1[8], G2[8];
;                         LDG(G0, 0) SB;
;                         LDG(G1, 1) SB;
;                         f32x2 c0 = {0.f, 0.f}, c1 = {0.f, 0.f};
; #pragma unroll
;                         for (int j = 0; j < 8; ++j) { c0 += S2[2 * j] * (f32x2){KA[j][0], KA[j][1]}; c1 += S2[2 * j + 1] * (f32x2){KA[j][2], KA[j][3]}; }
;                         float cs = (c0.x + c0.y) + (c1.x + c1.y);
;                         cs += dpp_f(cs, 0);
;                         const float sa = -cs;
;                         const f32x2 sa2 = {sa, sa}, v2 = {vi, vi};
;                         f32x2 y0 = {0.f, 0.f}, y1 = {0.f, 0.f};
;                         SB; LDG(G2, 2) SB; CMP(G0, 0) SB;
;                         LDG(G0, 3) SB; CMP(G1, 1) SB;
;                         CMP(G2, 2) SB;
; #pragma unroll
;                         for (int j = 0; j < 8; ++j) KA[j] = *(const f32x4*)(vs + 384 + 256 + 4 * j);
;                         SB; CMP(G0, 3) SB;
;                         float ys = (y0.x + y0.y) + (y1.x + y1.y);
;                         ys += dpp_f(ys, 0);
;                         if ((lane & 1) == 0) yb[s * 64 + srow] = ys;
	v_pk_fma_f32 v[220:221], v[112:113], v[120:121], v[220:221] op_sel:[0,1,0] op_sel_hi:[1,1,1]
	v_pk_fma_f32 v[222:223], v[114:115], v[120:121], v[222:223] op_sel:[0,1,0] op_sel_hi:[1,1,1]
	v_pk_fma_f32 v[8:9], v[8:9], v[188:189], v[216:217]
	v_pk_fma_f32 v[10:11], v[10:11], v[190:191], v[218:219]
	v_pk_fma_f32 v[24:25], v[24:25], v[188:189], v[220:221]
	v_pk_fma_f32 v[26:27], v[26:27], v[190:191], v[222:223]
	ds_read_b128 v[96:99], v232 offset:24352
	ds_read_b128 v[112:115], v232 offset:23328
	ds_read_b128 v[188:191], v232 offset:23840
	v_pk_mul_f32 v[224:225], v[100:101], v[212:213] op_sel_hi:[1,0] neg_lo:[0,1] neg_hi:[0,1]
	v_pk_mul_f32 v[226:227], v[102:103], v[212:213] op_sel_hi:[1,0] neg_lo:[0,1] neg_hi:[0,1]
	v_pk_mul_f32 v[228:229], v[100:101], v[212:213] op_sel:[0,1] op_sel_hi:[1,1] neg_lo:[0,1] neg_hi:[0,1]
	v_pk_mul_f32 v[230:231], v[102:103], v[212:213] op_sel:[0,1] op_sel_hi:[1,1] neg_lo:[0,1] neg_hi:[0,1]
	v_pk_fma_f32 v[224:225], v[116:117], v[120:121], v[224:225] op_sel_hi:[1,0,1]
	v_pk_fma_f32 v[226:227], v[118:119], v[120:121], v[226:227] op_sel_hi:[1,0,1]
	v_pk_fma_f32 v[228:229], v[116:117], v[120:121], v[228:229] op_sel:[0,1,0] op_sel_hi:[1,1,1]
	v_pk_fma_f32 v[230:231], v[118:119], v[120:121], v[230:231] op_sel:[0,1,0] op_sel_hi:[1,1,1]
	v_pk_fma_f32 v[12:13], v[12:13], v[192:193], v[224:225]
	v_pk_fma_f32 v[14:15], v[14:15], v[194:195], v[226:227]
	v_pk_fma_f32 v[28:29], v[28:29], v[192:193], v[228:229]
	v_pk_fma_f32 v[30:31], v[30:31], v[194:195], v[230:231]
	ds_read_b128 v[100:103], v232 offset:24368
	ds_read_b128 v[116:119], v232 offset:23344
	ds_read_b128 v[192:195], v232 offset:23856
	s_waitcnt lgkmcnt(13)
	v_pk_mul_f32 v[196:197], v[0:1], v[32:33]
	v_pk_mul_f32 v[200:201], v[16:17], v[32:33]
	v_pk_mul_f32 v[204:205], v[0:1], v[48:49]
	v_pk_mul_f32 v[208:209], v[16:17], v[48:49]
	v_pk_fma_f32 v[196:197], v[2:3], v[34:35], v[196:197]
	v_pk_fma_f32 v[200:201], v[18:19], v[34:35], v[200:201]
	v_pk_fma_f32 v[204:205], v[2:3], v[50:51], v[204:205]
	v_pk_fma_f32 v[208:209], v[18:19], v[50:51], v[208:209]
	ds_read_b128 v[32:35], v232 offset:25600
	ds_read_b128 v[48:51], v232 offset:23040
	v_pk_fma_f32 v[196:197], v[4:5], v[36:37], v[196:197]
	v_pk_fma_f32 v[200:201], v[20:21], v[36:37], v[200:201]
	v_pk_fma_f32 v[204:205], v[4:5], v[52:53], v[204:205]
	v_pk_fma_f32 v[208:209], v[20:21], v[52:53], v[208:209]
	v_pk_fma_f32 v[196:197], v[6:7], v[38:39], v[196:197]
	v_pk_fma_f32 v[200:201], v[22:23], v[38:39], v[200:201]
	v_pk_fma_f32 v[204:205], v[6:7], v[54:55], v[204:205]
	v_pk_fma_f32 v[208:209], v[22:23], v[54:55], v[208:209]
	ds_read_b128 v[36:39], v232 offset:25616
	ds_read_b128 v[52:55], v232 offset:23056
	v_pk_fma_f32 v[196:197], v[8:9], v[40:41], v[196:197]
	v_pk_fma_f32 v[200:201], v[24:25], v[40:41], v[200:201]
	v_pk_fma_f32 v[204:205], v[8:9], v[56:57], v[204:205]
	v_pk_fma_f32 v[208:209], v[24:25], v[56:57], v[208:209]
	v_pk_fma_f32 v[196:197], v[10:11], v[42:43], v[196:197]
	v_pk_fma_f32 v[200:201], v[26:27], v[42:43], v[200:201]
	v_pk_fma_f32 v[204:205], v[10:11], v[58:59], v[204:205]
	v_pk_fma_f32 v[208:209], v[26:27], v[58:59], v[208:209]
	ds_read_b128 v[40:43], v232 offset:25632
	ds_read_b128 v[56:59], v232 offset:23072
	v_pk_fma_f32 v[196:197], v[12:13], v[44:45], v[196:197]
	v_pk_fma_f32 v[200:201], v[28:29], v[44:45], v[200:201]
	v_pk_fma_f32 v[204:205], v[12:13], v[60:61], v[204:205]
	v_pk_fma_f32 v[208:209], v[28:29], v[60:61], v[208:209]
	v_pk_fma_f32 v[196:197], v[14:15], v[46:47], v[196:197]
	v_pk_fma_f32 v[200:201], v[30:31], v[46:47], v[200:201]
	v_pk_fma_f32 v[204:205], v[14:15], v[62:63], v[204:205]
	v_pk_fma_f32 v[208:209], v[30:31], v[62:63], v[208:209]
	ds_read_b128 v[44:47], v232 offset:25648
	ds_read_b128 v[60:63], v232 offset:23088
	v_add_f32_e32 v212, v196, v197
	v_add_f32_e32 v213, v200, v201
	v_add_f32_e32 v214, v204, v205
	v_add_f32_e32 v215, v208, v209
	v_add_f32_dpp v212, v212, v212 quad_perm:[1,0,3,2] row_mask:0xf bank_mask:0xf
	v_add_f32_dpp v213, v213, v213 quad_perm:[1,0,3,2] row_mask:0xf bank_mask:0xf
	v_add_f32_dpp v214, v214, v214 quad_perm:[1,0,3,2] row_mask:0xf bank_mask:0xf
	v_add_f32_dpp v215, v215, v215 quad_perm:[1,0,3,2] row_mask:0xf bank_mask:0xf
	v_add_f32_dpp v212, v212, v212 quad_perm:[2,3,0,1] row_mask:0xf bank_mask:0xf
	v_add_f32_dpp v213, v213, v213 quad_perm:[2,3,0,1] row_mask:0xf bank_mask:0xf
	v_add_f32_dpp v214, v214, v214 quad_perm:[2,3,0,1] row_mask:0xf bank_mask:0xf
	v_add_f32_dpp v215, v215, v215 quad_perm:[2,3,0,1] row_mask:0xf bank_mask:0xf
	ds_write_b64 v234, v[214:215] offset:3584
	s_waitcnt lgkmcnt(8)
; #define SB __builtin_amdgcn_sched_barrier(0)
; #define CMP(G, c8) { CMP1(G, 0, 2 * (c8)) CMP1(G, 1, 2 * (c8) + 1) }
; __device__ __forceinline__ void phase_scan(const Args& a, unsigned char* lds) {
;     ...
;                     f32x4 KA[8];
; #pragma unroll
;                     for (int j = 0; j < 8; ++j) KA[j] = *(const f32x4*)(vb + 256 + 4 * j);
; #pragma nounroll
;                     for (int s = 0; s < 16; ++s) {
;                         const float* vs = vb + s * 384;
;                         const float vi = vs[128 - cb + srow];
;                         f32x4 G0[8], G1[8], G2[8];
;                         LDG(G0, 0) SB;
;                         LDG(G1, 1) SB;
;                         f32x2 c0 = {0.f, 0.f}, c1 = {0.f, 0.f};
; #pragma unroll
;                         for (int j = 0; j < 8; ++j) { c0 += S2[2 * j] * (f32x2){KA[j][0], KA[j][1]}; c1 += S2[2 * j + 1] * (f32x2){KA[j][2], KA[j][3]}; }
;                         float cs = (c0.x + c0.y) + (c1.x + c1.y);
;                         cs += dpp_f(cs, 0);
;                         const float sa = -cs;
;                         const f32x2 sa2 = {sa, sa}, v2 = {vi, vi};
;                         f32x2 y0 = {0.f, 0.f}, y1 = {0.f, 0.f};
;                         SB; LDG(G2, 2) SB; CMP(G0, 0) SB;
;                         LDG(G0, 3) SB; CMP(G1, 1) SB;
;                         CMP(G2, 2) SB;
; #pragma unroll
;                         for (int j = 0; j < 8; ++j) KA[j] = *(const f32x4*)(vs + 384 + 256 + 4 * j);
;                         SB; CMP(G0, 3) SB;
;                         float ys = (y0.x + y0.y) + (y1.x + y1.y);
;                         ys += dpp_f(ys, 0);
;                         if ((lane & 1) == 0) yb[s * 64 + srow] = ys;
	ds_read_b64 v[120:121], v233 offset:25088
	v_pk_mul_f32 v[216:217], v[88:89], v[212:213] op_sel_hi:[1,0] neg_lo:[0,1] neg_hi:[0,1]
	v_pk_mul_f32 v[218:219], v[90:91], v[212:213] op_sel_hi:[1,0] neg_lo:[0,1] neg_hi:[0,1]
	v_pk_mul_f32 v[220:221], v[88:89], v[212:213] op_sel:[0,1] op_sel_hi:[1,1] neg_lo:[0,1] neg_hi:[0,1]
	v_pk_mul_f32 v[222:223], v[90:91], v[212:213] op_sel:[0,1] op_sel_hi:[1,1] neg_lo:[0,1] neg_hi:[0,1]
	v_pk_fma_f32 v[216:217], v[104:105], v[122:123], v[216:217] op_sel_hi:[1,0,1]
	v_pk_fma_f32 v[218:219], v[106:107], v[122:123], v[218:219] op_sel_hi:[1,0,1]
	v_pk_fma_f32 v[220:221], v[104:105], v[122:123], v[220:221] op_sel:[0,1,0] op_sel_hi:[1,1,1]
	v_pk_fma_f32 v[222:223], v[106:107], v[122:123], v[222:223] op_sel:[0,1,0] op_sel_hi:[1,1,1]
	v_pk_fma_f32 v[0:1], v[0:1], v[180:181], v[216:217]
	v_pk_fma_f32 v[2:3], v[2:3], v[182:183], v[218:219]
	v_pk_fma_f32 v[16:17], v[16:17], v[180:181], v[220:221]
	v_pk_fma_f32 v[18:19], v[18:19], v[182:183], v[222:223]
	ds_read_b128 v[88:91], v232 offset:25856
	ds_read_b128 v[104:107], v232 offset:24832
	ds_read_b128 v[180:183], v232 offset:25344
	v_pk_mul_f32 v[224:225], v[92:93], v[212:213] op_sel_hi:[1,0] neg_lo:[0,1] neg_hi:[0,1]
	v_pk_mul_f32 v[226:227], v[94:95], v[212:213] op_sel_hi:[1,0] neg_lo:[0,1] neg_hi:[0,1]
	v_pk_mul_f32 v[228:229], v[92:93], v[212:213] op_sel:[0,1] op_sel_hi:[1,1] neg_lo:[0,1] neg_hi:[0,1]
	v_pk_mul_f32 v[230:231], v[94:95], v[212:213] op_sel:[0,1] op_sel_hi:[1,1] neg_lo:[0,1] neg_hi:[0,1]
	v_pk_fma_f32 v[224:225], v[108:109], v[122:123], v[224:225] op_sel_hi:[1,0,1]
	v_pk_fma_f32 v[226:227], v[110:111], v[122:123], v[226:227] op_sel_hi:[1,0,1]
	v_pk_fma_f32 v[228:229], v[108:109], v[122:123], v[228:229] op_sel:[0,1,0] op_sel_hi:[1,1,1]
	v_pk_fma_f32 v[230:231], v[110:111], v[122:123], v[230:231] op_sel:[0,1,0] op_sel_hi:[1,1,1]
	v_pk_fma_f32 v[4:5], v[4:5], v[184:185], v[224:225]
	v_pk_fma_f32 v[6:7], v[6:7], v[186:187], v[226:227]
	v_pk_fma_f32 v[20:21], v[20:21], v[184:185], v[228:229]
	v_pk_fma_f32 v[22:23], v[22:23], v[186:187], v[230:231]
	ds_read_b128 v[92:95], v232 offset:25872
	ds_read_b128 v[108:111], v232 offset:24848
	ds_read_b128 v[184:187], v232 offset:25360
	v_pk_mul_f32 v[216:217], v[96:97], v[212:213] op_sel_hi:[1,0] neg_lo:[0,1] neg_hi:[0,1]
	v_pk_mul_f32 v[218:219], v[98:99], v[212:213] op_sel_hi:[1,0] neg_lo:[0,1] neg_hi:[0,1]
	v_pk_mul_f32 v[220:221], v[96:97], v[212:213] op_sel:[0,1] op_sel_hi:[1,1] neg_lo:[0,1] neg_hi:[0,1]
	v_pk_mul_f32 v[222:223], v[98:99], v[212:213] op_sel:[0,1] op_sel_hi:[1,1] neg_lo:[0,1] neg_hi:[0,1]
	v_pk_fma_f32 v[216:217], v[112:113], v[122:123], v[216:217] op_sel_hi:[1,0,1]
	v_pk_fma_f32 v[218:219], v[114:115], v[122:123], v[218:219] op_sel_hi:[1,0,1]
	v_pk_fma_f32 v[220:221], v[112:113], v[122:123], v[220:221] op_sel:[0,1,0] op_sel_hi:[1,1,1]
	v_pk_fma_f32 v[222:223], v[114:115], v[122:123], v[222:223] op_sel:[0,1,0] op_sel_hi:[1,1,1]
	v_pk_fma_f32 v[8:9], v[8:9], v[188:189], v[216:217]
	v_pk_fma_f32 v[10:11], v[10:11], v[190:191], v[218:219]
	v_pk_fma_f32 v[24:25], v[24:25], v[188:189], v[220:221]
	v_pk_fma_f32 v[26:27], v[26:27], v[190:191], v[222:223]
	ds_read_b128 v[96:99], v232 offset:25888
	ds_read_b128 v[112:115], v232 offset:24864
	ds_read_b128 v[188:191], v232 offset:25376
	v_pk_mul_f32 v[224:225], v[100:101], v[212:213] op_sel_hi:[1,0] neg_lo:[0,1] neg_hi:[0,1]
	v_pk_mul_f32 v[226:227], v[102:103], v[212:213] op_sel_hi:[1,0] neg_lo:[0,1] neg_hi:[0,1]
	v_pk_mul_f32 v[228:229], v[100:101], v[212:213] op_sel:[0,1] op_sel_hi:[1,1] neg_lo:[0,1] neg_hi:[0,1]
	v_pk_mul_f32 v[230:231], v[102:103], v[212:213] op_sel:[0,1] op_sel_hi:[1,1] neg_lo:[0,1] neg_hi:[0,1]
	v_pk_fma_f32 v[224:225], v[116:117], v[122:123], v[224:225] op_sel_hi:[1,0,1]
	v_pk_fma_f32 v[226:227], v[118:119], v[122:123], v[226:227] op_sel_hi:[1,0,1]
	v_pk_fma_f32 v[228:229], v[116:117], v[122:123], v[228:229] op_sel:[0,1,0] op_sel_hi:[1,1,1]
	v_pk_fma_f32 v[230:231], v[118:119], v[122:123], v[230:231] op_sel:[0,1,0] op_sel_hi:[1,1,1]
	v_pk_fma_f32 v[12:13], v[12:13], v[192:193], v[224:225]
	v_pk_fma_f32 v[14:15], v[14:15], v[194:195], v[226:227]
	v_pk_fma_f32 v[28:29], v[28:29], v[192:193], v[228:229]
	v_pk_fma_f32 v[30:31], v[30:31], v[194:195], v[230:231]
	ds_read_b128 v[100:103], v232 offset:25904
	ds_read_b128 v[116:119], v232 offset:24880
	ds_read_b128 v[192:195], v232 offset:25392
	s_waitcnt lgkmcnt(13)
	v_pk_mul_f32 v[204:205], v[0:1], v[48:49]
	v_pk_mul_f32 v[208:209], v[16:17], v[48:49]
	s_nop 1
	v_pk_fma_f32 v[204:205], v[2:3], v[50:51], v[204:205]
	v_pk_fma_f32 v[208:209], v[18:19], v[50:51], v[208:209]
	s_nop 1
	v_pk_fma_f32 v[204:205], v[4:5], v[52:53], v[204:205]
	v_pk_fma_f32 v[208:209], v[20:21], v[52:53], v[208:209]
	s_nop 1
	v_pk_fma_f32 v[204:205], v[6:7], v[54:55], v[204:205]
	v_pk_fma_f32 v[208:209], v[22:23], v[54:55], v[208:209]
	s_nop 1
	v_pk_fma_f32 v[204:205], v[8:9], v[56:57], v[204:205]
	v_pk_fma_f32 v[208:209], v[24:25], v[56:57], v[208:209]
	s_nop 1
	v_pk_fma_f32 v[204:205], v[10:11], v[58:59], v[204:205]
	v_pk_fma_f32 v[208:209], v[26:27], v[58:59], v[208:209]
	s_nop 1
	v_pk_fma_f32 v[204:205], v[12:13], v[60:61], v[204:205]
	v_pk_fma_f32 v[208:209], v[28:29], v[60:61], v[208:209]
	s_nop 1
	v_pk_fma_f32 v[204:205], v[14:15], v[62:63], v[204:205]
	v_pk_fma_f32 v[208:209], v[30:31], v[62:63], v[208:209]
	s_nop 1
	s_nop 0
	v_add_f32_e32 v214, v204, v205
	v_add_f32_e32 v215, v208, v209
	s_nop 1
	v_add_f32_dpp v214, v214, v214 quad_perm:[1,0,3,2] row_mask:0xf bank_mask:0xf
	v_add_f32_dpp v215, v215, v215 quad_perm:[1,0,3,2] row_mask:0xf bank_mask:0xf
	s_nop 1
	v_add_f32_dpp v214, v214, v214 quad_perm:[2,3,0,1] row_mask:0xf bank_mask:0xf
	v_add_f32_dpp v215, v215, v215 quad_perm:[2,3,0,1] row_mask:0xf bank_mask:0xf
	s_nop 0
	ds_write_b64 v234, v[214:215] offset:3840

; __device__ __forceinline__ void phase_scan(const Args& a, unsigned char* lds) {
;     ...
; #pragma unroll
;                 for (int pp = 0; pp < 2; ++pp)
; #pragma unroll
;                     for (int k = 0; k < 9; ++k) PFU(pp, k) = __builtin_bit_cast(f32x2, N[pp][k]);
;             }
;             __syncthreads();
.LBB0_655:
	s_or_b64 exec, exec, s[54:55]
	s_add_i32 s54, s71, 1
	s_cmp_eq_u32 s71, s70
	s_waitcnt vmcnt(0) lgkmcnt(0)
	s_barrier
	s_cbranch_scc1 .LBB0_657
	s_mov_b32 s71, s54
	s_cmp_eq_u64 s[4:5], 0
	s_cbranch_scc1 .Lscan_nophi
	v_mov_b64_e32 v[118:119], v[44:45]
	v_mov_b64_e32 v[110:111], v[46:47]
	v_mov_b64_e32 v[114:115], v[42:43]
	v_mov_b64_e32 v[116:117], v[34:35]
	v_mov_b64_e32 v[112:113], v[32:33]
	v_mov_b64_e32 v[104:105], v[40:41]
	v_mov_b64_e32 v[106:107], v[38:39]
	v_mov_b64_e32 v[108:109], v[36:37]
	v_mov_b64_e32 v[98:99], v[120:121]
	v_mov_b64_e32 v[94:95], v[62:63]
	v_mov_b64_e32 v[96:97], v[60:61]
	v_mov_b64_e32 v[102:103], v[50:51]
	v_mov_b64_e32 v[100:101], v[52:53]
	v_mov_b64_e32 v[92:93], v[56:57]
	v_mov_b64_e32 v[88:89], v[58:59]
	v_mov_b64_e32 v[90:91], v[54:55]
	v_mov_b32_e32 v135, v48
	v_mov_b32_e32 v136, v49
	v_mov_b32_e32 v133, v122
	v_mov_b32_e32 v134, v123
.Lscan_nophi:
	s_and_saveexec_b64 s[54:55], s[4:5]
	s_xor_b64 s[54:55], exec, s[54:55]
	s_cbranch_execnz .LBB0_630
	s_branch .LBB0_648

; __device__ __forceinline__ unsigned pk_bf16(float lo, float hi) { const f32x2 v = {lo, hi}; return __builtin_bit_cast(unsigned, __builtin_convertvector(v, nbf16x2)); }
;     __device__ __forceinline__ void store8(int row, int col, const f32x4 v, const f32x4 w) const { st8_bf16((bf16_t*)((unsigned char*)out + T_D0) + (size_t)row * DM + col, v, w); }
;     __device__ __forceinline__ void store8(int row, int col, const f32x4 v, const f32x4 w) const { store4(row, col, v); store4(row, col + 4, w); }
; __device__ __forceinline__ void st8_bf16(bf16_t* p, const f32x4 a, const f32x4 b) { __builtin_nontemporal_store((u32x4){pk_bf16(a[0], a[1]), pk_bf16(a[2], a[3]), pk_bf16(b[0], b[1]), pk_bf16(b[2], b[3])}, (u32x4*)p); }
; __device__ __forceinline__ void st8_f32(float* p, const f32x4 a, const f32x4 b) { __builtin_nontemporal_store(a, (f32x4*)p); __builtin_nontemporal_store(b, (f32x4*)(p + 4)); }
; __device__ __forceinline__ f32x4 silu4(const f32x4 v) { return (f32x4){v[0] / (1.f + __expf(-v[0])), v[1] / (1.f + __expf(-v[1])), v[2] / (1.f + __expf(-v[2])), v[3] / (1.f + __expf(-v[3]))}; }
;     __device__ __forceinline__ void store8(int row, int col, const f32x4 v, const f32x4 w) const {
;         if (col < 1536) st8_bf16((bf16_t*)(ws + WS_BRANCH) + (size_t)row * BR + col, v, w);
;         else if (col < 3072) { const int c = col - 1536; st8_bf16((bf16_t*)(ws + WS_KB) + (size_t)row * MIXW + c, v, w);
;             if (row < MP) st8_f32(out + O_PK + (size_t)row * MIXW + c, v, w); else st8_f32(out + O_SK + (size_t)(row - MP) * MIXW + c, v, w); }
;         else if (col < 4608) { const int c = col - 3072; st8_bf16((bf16_t*)(ws + WS_VB) + (size_t)row * MIXW + c, v, w);
;             if (row < MP) st8_f32(out + O_PV + (size_t)row * MIXW + c, v, w); else st8_f32(out + O_SV + (size_t)(row - MP) * MIXW + c, v, w); }
;         else if (col < 5120) st8_bf16((bf16_t*)(ws + WS_BRANCH) + (size_t)row * BR + 1536 + (col - 4608), v, w);
;         else st8_bf16((bf16_t*)(ws + WS_GATE) + (size_t)row * BR + (col - 5120), silu4(v), silu4(w));
.Le6_g:
	s_mul_i32 s85, s84, 0x1000
	s_add_u32 s86, s14, s85
	s_addc_u32 s87, s15, 0
	s_add_u32 s86, s86, 0x15ae0000
	s_addc_u32 s87, s87, 0
	s_sub_i32 s85, s6, 20
	s_lshl_b32 s85, s85, 9
	s_add_u32 s86, s86, s85
	s_addc_u32 s87, s87, 0
	v_lshlrev_b32_e32 v146, 1, v154
	s_movk_i32 s85, 0x1000
	v_mad_u32_u24 v146, v152, s85, v146
	s_mov_b32 s98, 0xbfb8aa3b
	s_mov_b32 s99, 0xbfb8aa3b
	s_mov_b64 s[92:93], s[86:87]
	v_pk_mul_f32 v[148:149], v[124:125], s[98:99]
	v_pk_mul_f32 v[150:151], v[126:127], s[98:99]
	v_pk_mul_f32 v[164:165], v[120:121], s[98:99]
	v_pk_mul_f32 v[166:167], v[122:123], s[98:99]
	v_exp_f32_e32 v148, v148
	v_exp_f32_e32 v149, v149
	v_exp_f32_e32 v150, v150
	v_exp_f32_e32 v151, v151
	v_exp_f32_e32 v164, v164
	v_exp_f32_e32 v165, v165
	v_exp_f32_e32 v166, v166
	v_exp_f32_e32 v167, v167
	v_pk_add_f32 v[148:149], v[148:149], 1.0 op_sel_hi:[1,0]
	v_pk_add_f32 v[150:151], v[150:151], 1.0 op_sel_hi:[1,0]
	v_pk_add_f32 v[164:165], v[164:165], 1.0 op_sel_hi:[1,0]
	v_pk_add_f32 v[166:167], v[166:167], 1.0 op_sel_hi:[1,0]
	v_rcp_f32_e32 v148, v148
	v_rcp_f32_e32 v149, v149
	v_rcp_f32_e32 v150, v150
	v_rcp_f32_e32 v151, v151
	v_rcp_f32_e32 v164, v164
	v_rcp_f32_e32 v165, v165
	v_rcp_f32_e32 v166, v166
	v_rcp_f32_e32 v167, v167
	v_pk_mul_f32 v[124:125], v[124:125], v[148:149]
	v_pk_mul_f32 v[126:127], v[126:127], v[150:151]
	v_pk_mul_f32 v[120:121], v[120:121], v[164:165]
	v_pk_mul_f32 v[122:123], v[122:123], v[166:167]
	v_cvt_pk_bf16_f32 v124, v124, v125
	v_cvt_pk_bf16_f32 v125, v126, v127
	v_cvt_pk_bf16_f32 v126, v120, v121
	v_cvt_pk_bf16_f32 v127, v122, v123
	global_store_dwordx4 v146, v[124:127], s[92:93]
	s_add_u32 s92, s86, 0x10000
	s_addc_u32 s93, s87, 0
	v_pk_mul_f32 v[148:149], v[116:117], s[98:99]
	v_pk_mul_f32 v[150:151], v[118:119], s[98:99]
	v_pk_mul_f32 v[164:165], v[112:113], s[98:99]
	v_pk_mul_f32 v[166:167], v[114:115], s[98:99]
	v_exp_f32_e32 v148, v148
	v_exp_f32_e32 v149, v149
	v_exp_f32_e32 v150, v150
	v_exp_f32_e32 v151, v151
	v_exp_f32_e32 v164, v164
	v_exp_f32_e32 v165, v165
	v_exp_f32_e32 v166, v166
	v_exp_f32_e32 v167, v167
	v_pk_add_f32 v[148:149], v[148:149], 1.0 op_sel_hi:[1,0]
	v_pk_add_f32 v[150:151], v[150:151], 1.0 op_sel_hi:[1,0]
	v_pk_add_f32 v[164:165], v[164:165], 1.0 op_sel_hi:[1,0]
	v_pk_add_f32 v[166:167], v[166:167], 1.0 op_sel_hi:[1,0]
	v_rcp_f32_e32 v148, v148
	v_rcp_f32_e32 v149, v149
	v_rcp_f32_e32 v150, v150
	v_rcp_f32_e32 v151, v151
	v_rcp_f32_e32 v164, v164
	v_rcp_f32_e32 v165, v165
	v_rcp_f32_e32 v166, v166
	v_rcp_f32_e32 v167, v167
	v_pk_mul_f32 v[116:117], v[116:117], v[148:149]
	v_pk_mul_f32 v[118:119], v[118:119], v[150:151]
	v_pk_mul_f32 v[112:113], v[112:113], v[164:165]
	v_pk_mul_f32 v[114:115], v[114:115], v[166:167]
	v_cvt_pk_bf16_f32 v116, v116, v117
	v_cvt_pk_bf16_f32 v117, v118, v119
	v_cvt_pk_bf16_f32 v118, v112, v113
	v_cvt_pk_bf16_f32 v119, v114, v115
	global_store_dwordx4 v146, v[116:119], s[92:93]
	s_add_u32 s92, s86, 0x20000
	s_addc_u32 s93, s87, 0
	v_pk_mul_f32 v[148:149], v[108:109], s[98:99]
	v_pk_mul_f32 v[150:151], v[110:111], s[98:99]
	v_pk_mul_f32 v[164:165], v[104:105], s[98:99]
	v_pk_mul_f32 v[166:167], v[106:107], s[98:99]
	v_exp_f32_e32 v148, v148
	v_exp_f32_e32 v149, v149
	v_exp_f32_e32 v150, v150
	v_exp_f32_e32 v151, v151
	v_exp_f32_e32 v164, v164
	v_exp_f32_e32 v165, v165
	v_exp_f32_e32 v166, v166
	v_exp_f32_e32 v167, v167
	v_pk_add_f32 v[148:149], v[148:149], 1.0 op_sel_hi:[1,0]
	v_pk_add_f32 v[150:151], v[150:151], 1.0 op_sel_hi:[1,0]
	v_pk_add_f32 v[164:165], v[164:165], 1.0 op_sel_hi:[1,0]
	v_pk_add_f32 v[166:167], v[166:167], 1.0 op_sel_hi:[1,0]
	v_rcp_f32_e32 v148, v148
	v_rcp_f32_e32 v149, v149
	v_rcp_f32_e32 v150, v150
	v_rcp_f32_e32 v151, v151
	v_rcp_f32_e32 v164, v164
	v_rcp_f32_e32 v165, v165
	v_rcp_f32_e32 v166, v166
	v_rcp_f32_e32 v167, v167
	v_pk_mul_f32 v[108:109], v[108:109], v[148:149]
	v_pk_mul_f32 v[110:111], v[110:111], v[150:151]
	v_pk_mul_f32 v[104:105], v[104:105], v[164:165]
	v_pk_mul_f32 v[106:107], v[106:107], v[166:167]
	v_cvt_pk_bf16_f32 v108, v108, v109
	v_cvt_pk_bf16_f32 v109, v110, v111
	v_cvt_pk_bf16_f32 v110, v104, v105
	v_cvt_pk_bf16_f32 v111, v106, v107
	global_store_dwordx4 v146, v[108:111], s[92:93]
	s_add_u32 s92, s86, 0x30000
	s_addc_u32 s93, s87, 0
	v_pk_mul_f32 v[148:149], v[100:101], s[98:99]
	v_pk_mul_f32 v[150:151], v[102:103], s[98:99]
	v_pk_mul_f32 v[164:165], v[96:97], s[98:99]
	v_pk_mul_f32 v[166:167], v[98:99], s[98:99]
	v_exp_f32_e32 v148, v148
	v_exp_f32_e32 v149, v149
	v_exp_f32_e32 v150, v150
	v_exp_f32_e32 v151, v151
	v_exp_f32_e32 v164, v164
	v_exp_f32_e32 v165, v165
	v_exp_f32_e32 v166, v166
	v_exp_f32_e32 v167, v167
	v_pk_add_f32 v[148:149], v[148:149], 1.0 op_sel_hi:[1,0]
	v_pk_add_f32 v[150:151], v[150:151], 1.0 op_sel_hi:[1,0]
	v_pk_add_f32 v[164:165], v[164:165], 1.0 op_sel_hi:[1,0]
	v_pk_add_f32 v[166:167], v[166:167], 1.0 op_sel_hi:[1,0]
	v_rcp_f32_e32 v148, v148
	v_rcp_f32_e32 v149, v149
	v_rcp_f32_e32 v150, v150
	v_rcp_f32_e32 v151, v151
	v_rcp_f32_e32 v164, v164
	v_rcp_f32_e32 v165, v165
	v_rcp_f32_e32 v166, v166
	v_rcp_f32_e32 v167, v167
	v_pk_mul_f32 v[100:101], v[100:101], v[148:149]
	v_pk_mul_f32 v[102:103], v[102:103], v[150:151]
	v_pk_mul_f32 v[96:97], v[96:97], v[164:165]
	v_pk_mul_f32 v[98:99], v[98:99], v[166:167]
	v_cvt_pk_bf16_f32 v100, v100, v101
	v_cvt_pk_bf16_f32 v101, v102, v103
	v_cvt_pk_bf16_f32 v102, v96, v97
	v_cvt_pk_bf16_f32 v103, v98, v99
	global_store_dwordx4 v146, v[100:103], s[92:93]
	s_add_u32 s92, s86, 0x100
	s_addc_u32 s93, s87, 0
	v_pk_mul_f32 v[148:149], v[92:93], s[98:99]
	v_pk_mul_f32 v[150:151], v[94:95], s[98:99]
	v_pk_mul_f32 v[164:165], v[88:89], s[98:99]
; __device__ __forceinline__ unsigned pk_bf16(float lo, float hi) { const f32x2 v = {lo, hi}; return __builtin_bit_cast(unsigned, __builtin_convertvector(v, nbf16x2)); }
;     __device__ __forceinline__ void store8(int row, int col, const f32x4 v, const f32x4 w) const { st8_bf16((bf16_t*)((unsigned char*)out + T_D0) + (size_t)row * DM + col, v, w); }
;     __device__ __forceinline__ void store8(int row, int col, const f32x4 v, const f32x4 w) const { store4(row, col, v); store4(row, col + 4, w); }
; __device__ __forceinline__ void st8_bf16(bf16_t* p, const f32x4 a, const f32x4 b) { __builtin_nontemporal_store((u32x4){pk_bf16(a[0], a[1]), pk_bf16(a[2], a[3]), pk_bf16(b[0], b[1]), pk_bf16(b[2], b[3])}, (u32x4*)p); }
; __device__ __forceinline__ void st8_f32(float* p, const f32x4 a, const f32x4 b) { __builtin_nontemporal_store(a, (f32x4*)p); __builtin_nontemporal_store(b, (f32x4*)(p + 4)); }
; __device__ __forceinline__ f32x4 silu4(const f32x4 v) { return (f32x4){v[0] / (1.f + __expf(-v[0])), v[1] / (1.f + __expf(-v[1])), v[2] / (1.f + __expf(-v[2])), v[3] / (1.f + __expf(-v[3]))}; }
;     __device__ __forceinline__ void store8(int row, int col, const f32x4 v, const f32x4 w) const {
;         if (col < 1536) st8_bf16((bf16_t*)(ws + WS_BRANCH) + (size_t)row * BR + col, v, w);
;         else if (col < 3072) { const int c = col - 1536; st8_bf16((bf16_t*)(ws + WS_KB) + (size_t)row * MIXW + c, v, w);
;             if (row < MP) st8_f32(out + O_PK + (size_t)row * MIXW + c, v, w); else st8_f32(out + O_SK + (size_t)(row - MP) * MIXW + c, v, w); }
;         else if (col < 4608) { const int c = col - 3072; st8_bf16((bf16_t*)(ws + WS_VB) + (size_t)row * MIXW + c, v, w);
;             if (row < MP) st8_f32(out + O_PV + (size_t)row * MIXW + c, v, w); else st8_f32(out + O_SV + (size_t)(row - MP) * MIXW + c, v, w); }
;         else if (col < 5120) st8_bf16((bf16_t*)(ws + WS_BRANCH) + (size_t)row * BR + 1536 + (col - 4608), v, w);
;         else st8_bf16((bf16_t*)(ws + WS_GATE) + (size_t)row * BR + (col - 5120), silu4(v), silu4(w));
	v_pk_mul_f32 v[166:167], v[90:91], s[98:99]
	v_exp_f32_e32 v148, v148
	v_exp_f32_e32 v149, v149
	v_exp_f32_e32 v150, v150
	v_exp_f32_e32 v151, v151
	v_exp_f32_e32 v164, v164
	v_exp_f32_e32 v165, v165
	v_exp_f32_e32 v166, v166
	v_exp_f32_e32 v167, v167
	v_pk_add_f32 v[148:149], v[148:149], 1.0 op_sel_hi:[1,0]
	v_pk_add_f32 v[150:151], v[150:151], 1.0 op_sel_hi:[1,0]
	v_pk_add_f32 v[164:165], v[164:165], 1.0 op_sel_hi:[1,0]
	v_pk_add_f32 v[166:167], v[166:167], 1.0 op_sel_hi:[1,0]
	v_rcp_f32_e32 v148, v148
	v_rcp_f32_e32 v149, v149
	v_rcp_f32_e32 v150, v150
	v_rcp_f32_e32 v151, v151
	v_rcp_f32_e32 v164, v164
	v_rcp_f32_e32 v165, v165
	v_rcp_f32_e32 v166, v166
	v_rcp_f32_e32 v167, v167
	v_pk_mul_f32 v[92:93], v[92:93], v[148:149]
	v_pk_mul_f32 v[94:95], v[94:95], v[150:151]
	v_pk_mul_f32 v[88:89], v[88:89], v[164:165]
	v_pk_mul_f32 v[90:91], v[90:91], v[166:167]
	v_cvt_pk_bf16_f32 v92, v92, v93
	v_cvt_pk_bf16_f32 v93, v94, v95
	v_cvt_pk_bf16_f32 v94, v88, v89
	v_cvt_pk_bf16_f32 v95, v90, v91
	global_store_dwordx4 v146, v[92:95], s[92:93]
	s_add_u32 s92, s86, 0x10100
	s_addc_u32 s93, s87, 0
	v_pk_mul_f32 v[148:149], v[84:85], s[98:99]
	v_pk_mul_f32 v[150:151], v[86:87], s[98:99]
	v_pk_mul_f32 v[164:165], v[80:81], s[98:99]
	v_pk_mul_f32 v[166:167], v[82:83], s[98:99]
	v_exp_f32_e32 v148, v148
	v_exp_f32_e32 v149, v149
	v_exp_f32_e32 v150, v150
	v_exp_f32_e32 v151, v151
	v_exp_f32_e32 v164, v164
	v_exp_f32_e32 v165, v165
	v_exp_f32_e32 v166, v166
	v_exp_f32_e32 v167, v167
	v_pk_add_f32 v[148:149], v[148:149], 1.0 op_sel_hi:[1,0]
	v_pk_add_f32 v[150:151], v[150:151], 1.0 op_sel_hi:[1,0]
	v_pk_add_f32 v[164:165], v[164:165], 1.0 op_sel_hi:[1,0]
	v_pk_add_f32 v[166:167], v[166:167], 1.0 op_sel_hi:[1,0]
	v_rcp_f32_e32 v148, v148
	v_rcp_f32_e32 v149, v149
	v_rcp_f32_e32 v150, v150
	v_rcp_f32_e32 v151, v151
	v_rcp_f32_e32 v164, v164
	v_rcp_f32_e32 v165, v165
	v_rcp_f32_e32 v166, v166
	v_rcp_f32_e32 v167, v167
	v_pk_mul_f32 v[84:85], v[84:85], v[148:149]
	v_pk_mul_f32 v[86:87], v[86:87], v[150:151]
	v_pk_mul_f32 v[80:81], v[80:81], v[164:165]
	v_pk_mul_f32 v[82:83], v[82:83], v[166:167]
	v_cvt_pk_bf16_f32 v84, v84, v85
	v_cvt_pk_bf16_f32 v85, v86, v87
	v_cvt_pk_bf16_f32 v86, v80, v81
	v_cvt_pk_bf16_f32 v87, v82, v83
	global_store_dwordx4 v146, v[84:87], s[92:93]
	s_add_u32 s92, s86, 0x20100
	s_addc_u32 s93, s87, 0
	v_pk_mul_f32 v[148:149], v[76:77], s[98:99]
	v_pk_mul_f32 v[150:151], v[78:79], s[98:99]
	v_pk_mul_f32 v[164:165], v[72:73], s[98:99]
	v_pk_mul_f32 v[166:167], v[74:75], s[98:99]
	v_exp_f32_e32 v148, v148
	v_exp_f32_e32 v149, v149
	v_exp_f32_e32 v150, v150
	v_exp_f32_e32 v151, v151
	v_exp_f32_e32 v164, v164
	v_exp_f32_e32 v165, v165
	v_exp_f32_e32 v166, v166
	v_exp_f32_e32 v167, v167
	v_pk_add_f32 v[148:149], v[148:149], 1.0 op_sel_hi:[1,0]
	v_pk_add_f32 v[150:151], v[150:151], 1.0 op_sel_hi:[1,0]
	v_pk_add_f32 v[164:165], v[164:165], 1.0 op_sel_hi:[1,0]
	v_pk_add_f32 v[166:167], v[166:167], 1.0 op_sel_hi:[1,0]
	v_rcp_f32_e32 v148, v148
	v_rcp_f32_e32 v149, v149
	v_rcp_f32_e32 v150, v150
	v_rcp_f32_e32 v151, v151
	v_rcp_f32_e32 v164, v164
	v_rcp_f32_e32 v165, v165
	v_rcp_f32_e32 v166, v166
	v_rcp_f32_e32 v167, v167
	v_pk_mul_f32 v[76:77], v[76:77], v[148:149]
	v_pk_mul_f32 v[78:79], v[78:79], v[150:151]
	v_pk_mul_f32 v[72:73], v[72:73], v[164:165]
	v_pk_mul_f32 v[74:75], v[74:75], v[166:167]
	v_cvt_pk_bf16_f32 v76, v76, v77
	v_cvt_pk_bf16_f32 v77, v78, v79
	v_cvt_pk_bf16_f32 v78, v72, v73
	v_cvt_pk_bf16_f32 v79, v74, v75
	global_store_dwordx4 v146, v[76:79], s[92:93]
	s_add_u32 s92, s86, 0x30100
	s_addc_u32 s93, s87, 0
	v_pk_mul_f32 v[148:149], v[68:69], s[98:99]
	v_pk_mul_f32 v[150:151], v[70:71], s[98:99]
	v_pk_mul_f32 v[164:165], v[64:65], s[98:99]
	v_pk_mul_f32 v[166:167], v[66:67], s[98:99]
	v_exp_f32_e32 v148, v148
	v_exp_f32_e32 v149, v149
	v_exp_f32_e32 v150, v150
	v_exp_f32_e32 v151, v151
	v_exp_f32_e32 v164, v164
	v_exp_f32_e32 v165, v165
	v_exp_f32_e32 v166, v166
	v_exp_f32_e32 v167, v167
	v_pk_add_f32 v[148:149], v[148:149], 1.0 op_sel_hi:[1,0]
	v_pk_add_f32 v[150:151], v[150:151], 1.0 op_sel_hi:[1,0]
	v_pk_add_f32 v[164:165], v[164:165], 1.0 op_sel_hi:[1,0]
	v_pk_add_f32 v[166:167], v[166:167], 1.0 op_sel_hi:[1,0]
	v_rcp_f32_e32 v148, v148
	v_rcp_f32_e32 v149, v149
	v_rcp_f32_e32 v150, v150
	v_rcp_f32_e32 v151, v151
	v_rcp_f32_e32 v164, v164
	v_rcp_f32_e32 v165, v165
	v_rcp_f32_e32 v166, v166
	v_rcp_f32_e32 v167, v167
	v_pk_mul_f32 v[68:69], v[68:69], v[148:149]
	v_pk_mul_f32 v[70:71], v[70:71], v[150:151]
	v_pk_mul_f32 v[64:65], v[64:65], v[164:165]
	v_pk_mul_f32 v[66:67], v[66:67], v[166:167]
	v_cvt_pk_bf16_f32 v68, v68, v69
	v_cvt_pk_bf16_f32 v69, v70, v71
	v_cvt_pk_bf16_f32 v70, v64, v65
	v_cvt_pk_bf16_f32 v71, v66, v67
	global_store_dwordx4 v146, v[68:71], s[92:93]
	s_add_u32 s92, s86, 0x80000
	s_addc_u32 s93, s87, 0
	v_pk_mul_f32 v[148:149], v[60:61], s[98:99]
	v_pk_mul_f32 v[150:151], v[62:63], s[98:99]
	v_pk_mul_f32 v[164:165], v[56:57], s[98:99]
	v_pk_mul_f32 v[166:167], v[58:59], s[98:99]
	v_exp_f32_e32 v148, v148
	v_exp_f32_e32 v149, v149
	v_exp_f32_e32 v150, v150
	v_exp_f32_e32 v151, v151
	v_exp_f32_e32 v164, v164
	v_exp_f32_e32 v165, v165
	v_exp_f32_e32 v166, v166
	v_exp_f32_e32 v167, v167
	v_pk_add_f32 v[148:149], v[148:149], 1.0 op_sel_hi:[1,0]
	v_pk_add_f32 v[150:151], v[150:151], 1.0 op_sel_hi:[1,0]
	v_pk_add_f32 v[164:165], v[164:165], 1.0 op_sel_hi:[1,0]
	v_pk_add_f32 v[166:167], v[166:167], 1.0 op_sel_hi:[1,0]
	v_rcp_f32_e32 v148, v148
	v_rcp_f32_e32 v149, v149
	v_rcp_f32_e32 v150, v150
	v_rcp_f32_e32 v151, v151
	v_rcp_f32_e32 v164, v164
	v_rcp_f32_e32 v165, v165
	v_rcp_f32_e32 v166, v166
; __device__ __forceinline__ unsigned pk_bf16(float lo, float hi) { const f32x2 v = {lo, hi}; return __builtin_bit_cast(unsigned, __builtin_convertvector(v, nbf16x2)); }
;     __device__ __forceinline__ void store8(int row, int col, const f32x4 v, const f32x4 w) const { st8_bf16((bf16_t*)((unsigned char*)out + T_D0) + (size_t)row * DM + col, v, w); }
;     __device__ __forceinline__ void store8(int row, int col, const f32x4 v, const f32x4 w) const { store4(row, col, v); store4(row, col + 4, w); }
; __device__ __forceinline__ void st8_bf16(bf16_t* p, const f32x4 a, const f32x4 b) { __builtin_nontemporal_store((u32x4){pk_bf16(a[0], a[1]), pk_bf16(a[2], a[3]), pk_bf16(b[0], b[1]), pk_bf16(b[2], b[3])}, (u32x4*)p); }
; __device__ __forceinline__ void st8_f32(float* p, const f32x4 a, const f32x4 b) { __builtin_nontemporal_store(a, (f32x4*)p); __builtin_nontemporal_store(b, (f32x4*)(p + 4)); }
; __device__ __forceinline__ f32x4 silu4(const f32x4 v) { return (f32x4){v[0] / (1.f + __expf(-v[0])), v[1] / (1.f + __expf(-v[1])), v[2] / (1.f + __expf(-v[2])), v[3] / (1.f + __expf(-v[3]))}; }
;     __device__ __forceinline__ void store8(int row, int col, const f32x4 v, const f32x4 w) const {
;         if (col < 1536) st8_bf16((bf16_t*)(ws + WS_BRANCH) + (size_t)row * BR + col, v, w);
;         else if (col < 3072) { const int c = col - 1536; st8_bf16((bf16_t*)(ws + WS_KB) + (size_t)row * MIXW + c, v, w);
;             if (row < MP) st8_f32(out + O_PK + (size_t)row * MIXW + c, v, w); else st8_f32(out + O_SK + (size_t)(row - MP) * MIXW + c, v, w); }
;         else if (col < 4608) { const int c = col - 3072; st8_bf16((bf16_t*)(ws + WS_VB) + (size_t)row * MIXW + c, v, w);
;             if (row < MP) st8_f32(out + O_PV + (size_t)row * MIXW + c, v, w); else st8_f32(out + O_SV + (size_t)(row - MP) * MIXW + c, v, w); }
;         else if (col < 5120) st8_bf16((bf16_t*)(ws + WS_BRANCH) + (size_t)row * BR + 1536 + (col - 4608), v, w);
;         else st8_bf16((bf16_t*)(ws + WS_GATE) + (size_t)row * BR + (col - 5120), silu4(v), silu4(w));
	v_rcp_f32_e32 v167, v167
	v_pk_mul_f32 v[60:61], v[60:61], v[148:149]
	v_pk_mul_f32 v[62:63], v[62:63], v[150:151]
	v_pk_mul_f32 v[56:57], v[56:57], v[164:165]
	v_pk_mul_f32 v[58:59], v[58:59], v[166:167]
	v_cvt_pk_bf16_f32 v60, v60, v61
	v_cvt_pk_bf16_f32 v61, v62, v63
	v_cvt_pk_bf16_f32 v62, v56, v57
	v_cvt_pk_bf16_f32 v63, v58, v59
	global_store_dwordx4 v146, v[60:63], s[92:93]
	s_add_u32 s92, s86, 0x90000
	s_addc_u32 s93, s87, 0
	v_pk_mul_f32 v[148:149], v[52:53], s[98:99]
	v_pk_mul_f32 v[150:151], v[54:55], s[98:99]
	v_pk_mul_f32 v[164:165], v[48:49], s[98:99]
	v_pk_mul_f32 v[166:167], v[50:51], s[98:99]
	v_exp_f32_e32 v148, v148
	v_exp_f32_e32 v149, v149
	v_exp_f32_e32 v150, v150
	v_exp_f32_e32 v151, v151
	v_exp_f32_e32 v164, v164
	v_exp_f32_e32 v165, v165
	v_exp_f32_e32 v166, v166
	v_exp_f32_e32 v167, v167
	v_pk_add_f32 v[148:149], v[148:149], 1.0 op_sel_hi:[1,0]
	v_pk_add_f32 v[150:151], v[150:151], 1.0 op_sel_hi:[1,0]
	v_pk_add_f32 v[164:165], v[164:165], 1.0 op_sel_hi:[1,0]
	v_pk_add_f32 v[166:167], v[166:167], 1.0 op_sel_hi:[1,0]
	v_rcp_f32_e32 v148, v148
	v_rcp_f32_e32 v149, v149
	v_rcp_f32_e32 v150, v150
	v_rcp_f32_e32 v151, v151
	v_rcp_f32_e32 v164, v164
	v_rcp_f32_e32 v165, v165
	v_rcp_f32_e32 v166, v166
	v_rcp_f32_e32 v167, v167
	v_pk_mul_f32 v[52:53], v[52:53], v[148:149]
	v_pk_mul_f32 v[54:55], v[54:55], v[150:151]
	v_pk_mul_f32 v[48:49], v[48:49], v[164:165]
	v_pk_mul_f32 v[50:51], v[50:51], v[166:167]
	v_cvt_pk_bf16_f32 v52, v52, v53
	v_cvt_pk_bf16_f32 v53, v54, v55
	v_cvt_pk_bf16_f32 v54, v48, v49
	v_cvt_pk_bf16_f32 v55, v50, v51
	global_store_dwordx4 v146, v[52:55], s[92:93]
	s_add_u32 s92, s86, 0xa0000
	s_addc_u32 s93, s87, 0
	v_pk_mul_f32 v[148:149], v[44:45], s[98:99]
	v_pk_mul_f32 v[150:151], v[46:47], s[98:99]
	v_pk_mul_f32 v[164:165], v[40:41], s[98:99]
	v_pk_mul_f32 v[166:167], v[42:43], s[98:99]
	v_exp_f32_e32 v148, v148
	v_exp_f32_e32 v149, v149
	v_exp_f32_e32 v150, v150
	v_exp_f32_e32 v151, v151
	v_exp_f32_e32 v164, v164
	v_exp_f32_e32 v165, v165
	v_exp_f32_e32 v166, v166
	v_exp_f32_e32 v167, v167
	v_pk_add_f32 v[148:149], v[148:149], 1.0 op_sel_hi:[1,0]
	v_pk_add_f32 v[150:151], v[150:151], 1.0 op_sel_hi:[1,0]
	v_pk_add_f32 v[164:165], v[164:165], 1.0 op_sel_hi:[1,0]
	v_pk_add_f32 v[166:167], v[166:167], 1.0 op_sel_hi:[1,0]
	v_rcp_f32_e32 v148, v148
	v_rcp_f32_e32 v149, v149
	v_rcp_f32_e32 v150, v150
	v_rcp_f32_e32 v151, v151
	v_rcp_f32_e32 v164, v164
	v_rcp_f32_e32 v165, v165
	v_rcp_f32_e32 v166, v166
	v_rcp_f32_e32 v167, v167
	v_pk_mul_f32 v[44:45], v[44:45], v[148:149]
	v_pk_mul_f32 v[46:47], v[46:47], v[150:151]
	v_pk_mul_f32 v[40:41], v[40:41], v[164:165]
	v_pk_mul_f32 v[42:43], v[42:43], v[166:167]
	v_cvt_pk_bf16_f32 v44, v44, v45
	v_cvt_pk_bf16_f32 v45, v46, v47
	v_cvt_pk_bf16_f32 v46, v40, v41
	v_cvt_pk_bf16_f32 v47, v42, v43
	global_store_dwordx4 v146, v[44:47], s[92:93]
	s_add_u32 s92, s86, 0xb0000
	s_addc_u32 s93, s87, 0
	v_pk_mul_f32 v[148:149], v[36:37], s[98:99]
	v_pk_mul_f32 v[150:151], v[38:39], s[98:99]
	v_pk_mul_f32 v[164:165], v[32:33], s[98:99]
	v_pk_mul_f32 v[166:167], v[34:35], s[98:99]
	v_exp_f32_e32 v148, v148
	v_exp_f32_e32 v149, v149
	v_exp_f32_e32 v150, v150
	v_exp_f32_e32 v151, v151
	v_exp_f32_e32 v164, v164
	v_exp_f32_e32 v165, v165
	v_exp_f32_e32 v166, v166
	v_exp_f32_e32 v167, v167
	v_pk_add_f32 v[148:149], v[148:149], 1.0 op_sel_hi:[1,0]
	v_pk_add_f32 v[150:151], v[150:151], 1.0 op_sel_hi:[1,0]
	v_pk_add_f32 v[164:165], v[164:165], 1.0 op_sel_hi:[1,0]
	v_pk_add_f32 v[166:167], v[166:167], 1.0 op_sel_hi:[1,0]
	v_rcp_f32_e32 v148, v148
	v_rcp_f32_e32 v149, v149
	v_rcp_f32_e32 v150, v150
	v_rcp_f32_e32 v151, v151
	v_rcp_f32_e32 v164, v164
	v_rcp_f32_e32 v165, v165
	v_rcp_f32_e32 v166, v166
	v_rcp_f32_e32 v167, v167
	v_pk_mul_f32 v[36:37], v[36:37], v[148:149]
	v_pk_mul_f32 v[38:39], v[38:39], v[150:151]
	v_pk_mul_f32 v[32:33], v[32:33], v[164:165]
	v_pk_mul_f32 v[34:35], v[34:35], v[166:167]
	v_cvt_pk_bf16_f32 v36, v36, v37
	v_cvt_pk_bf16_f32 v37, v38, v39
	v_cvt_pk_bf16_f32 v38, v32, v33
	v_cvt_pk_bf16_f32 v39, v34, v35
	global_store_dwordx4 v146, v[36:39], s[92:93]
	s_add_u32 s92, s86, 0x80100
	s_addc_u32 s93, s87, 0
	v_pk_mul_f32 v[148:149], v[28:29], s[98:99]
	v_pk_mul_f32 v[150:151], v[30:31], s[98:99]
	v_pk_mul_f32 v[164:165], v[24:25], s[98:99]
	v_pk_mul_f32 v[166:167], v[26:27], s[98:99]
	v_exp_f32_e32 v148, v148
	v_exp_f32_e32 v149, v149
	v_exp_f32_e32 v150, v150
	v_exp_f32_e32 v151, v151
	v_exp_f32_e32 v164, v164
	v_exp_f32_e32 v165, v165
	v_exp_f32_e32 v166, v166
	v_exp_f32_e32 v167, v167
	v_pk_add_f32 v[148:149], v[148:149], 1.0 op_sel_hi:[1,0]
	v_pk_add_f32 v[150:151], v[150:151], 1.0 op_sel_hi:[1,0]
	v_pk_add_f32 v[164:165], v[164:165], 1.0 op_sel_hi:[1,0]
	v_pk_add_f32 v[166:167], v[166:167], 1.0 op_sel_hi:[1,0]
	v_rcp_f32_e32 v148, v148
	v_rcp_f32_e32 v149, v149
	v_rcp_f32_e32 v150, v150
	v_rcp_f32_e32 v151, v151
	v_rcp_f32_e32 v164, v164
	v_rcp_f32_e32 v165, v165
	v_rcp_f32_e32 v166, v166
	v_rcp_f32_e32 v167, v167
	v_pk_mul_f32 v[28:29], v[28:29], v[148:149]
	v_pk_mul_f32 v[30:31], v[30:31], v[150:151]
	v_pk_mul_f32 v[24:25], v[24:25], v[164:165]
	v_pk_mul_f32 v[26:27], v[26:27], v[166:167]
	v_cvt_pk_bf16_f32 v28, v28, v29
	v_cvt_pk_bf16_f32 v29, v30, v31
	v_cvt_pk_bf16_f32 v30, v24, v25
	v_cvt_pk_bf16_f32 v31, v26, v27
	global_store_dwordx4 v146, v[28:31], s[92:93]
	s_add_u32 s92, s86, 0x90100
	s_addc_u32 s93, s87, 0
	v_pk_mul_f32 v[148:149], v[20:21], s[98:99]
	v_pk_mul_f32 v[150:151], v[22:23], s[98:99]
	v_pk_mul_f32 v[164:165], v[16:17], s[98:99]
	v_pk_mul_f32 v[166:167], v[18:19], s[98:99]
	v_exp_f32_e32 v148, v148
	v_exp_f32_e32 v149, v149
; __device__ __forceinline__ unsigned pk_bf16(float lo, float hi) { const f32x2 v = {lo, hi}; return __builtin_bit_cast(unsigned, __builtin_convertvector(v, nbf16x2)); }
;     __device__ __forceinline__ void store8(int row, int col, const f32x4 v, const f32x4 w) const { st8_bf16((bf16_t*)((unsigned char*)out + T_D0) + (size_t)row * DM + col, v, w); }
;     __device__ __forceinline__ void store8(int row, int col, const f32x4 v, const f32x4 w) const { store4(row, col, v); store4(row, col + 4, w); }
; __device__ __forceinline__ void st8_bf16(bf16_t* p, const f32x4 a, const f32x4 b) { __builtin_nontemporal_store((u32x4){pk_bf16(a[0], a[1]), pk_bf16(a[2], a[3]), pk_bf16(b[0], b[1]), pk_bf16(b[2], b[3])}, (u32x4*)p); }
; __device__ __forceinline__ void st8_f32(float* p, const f32x4 a, const f32x4 b) { __builtin_nontemporal_store(a, (f32x4*)p); __builtin_nontemporal_store(b, (f32x4*)(p + 4)); }
; __device__ __forceinline__ f32x4 silu4(const f32x4 v) { return (f32x4){v[0] / (1.f + __expf(-v[0])), v[1] / (1.f + __expf(-v[1])), v[2] / (1.f + __expf(-v[2])), v[3] / (1.f + __expf(-v[3]))}; }
;     __device__ __forceinline__ void store8(int row, int col, const f32x4 v, const f32x4 w) const {
;         if (col < 1536) st8_bf16((bf16_t*)(ws + WS_BRANCH) + (size_t)row * BR + col, v, w);
;         else if (col < 3072) { const int c = col - 1536; st8_bf16((bf16_t*)(ws + WS_KB) + (size_t)row * MIXW + c, v, w);
;             if (row < MP) st8_f32(out + O_PK + (size_t)row * MIXW + c, v, w); else st8_f32(out + O_SK + (size_t)(row - MP) * MIXW + c, v, w); }
;         else if (col < 4608) { const int c = col - 3072; st8_bf16((bf16_t*)(ws + WS_VB) + (size_t)row * MIXW + c, v, w);
;             if (row < MP) st8_f32(out + O_PV + (size_t)row * MIXW + c, v, w); else st8_f32(out + O_SV + (size_t)(row - MP) * MIXW + c, v, w); }
;         else if (col < 5120) st8_bf16((bf16_t*)(ws + WS_BRANCH) + (size_t)row * BR + 1536 + (col - 4608), v, w);
;         else st8_bf16((bf16_t*)(ws + WS_GATE) + (size_t)row * BR + (col - 5120), silu4(v), silu4(w));
	v_exp_f32_e32 v150, v150
	v_exp_f32_e32 v151, v151
	v_exp_f32_e32 v164, v164
	v_exp_f32_e32 v165, v165
	v_exp_f32_e32 v166, v166
	v_exp_f32_e32 v167, v167
	v_pk_add_f32 v[148:149], v[148:149], 1.0 op_sel_hi:[1,0]
	v_pk_add_f32 v[150:151], v[150:151], 1.0 op_sel_hi:[1,0]
	v_pk_add_f32 v[164:165], v[164:165], 1.0 op_sel_hi:[1,0]
	v_pk_add_f32 v[166:167], v[166:167], 1.0 op_sel_hi:[1,0]
	v_rcp_f32_e32 v148, v148
	v_rcp_f32_e32 v149, v149
	v_rcp_f32_e32 v150, v150
	v_rcp_f32_e32 v151, v151
	v_rcp_f32_e32 v164, v164
	v_rcp_f32_e32 v165, v165
	v_rcp_f32_e32 v166, v166
	v_rcp_f32_e32 v167, v167
	v_pk_mul_f32 v[20:21], v[20:21], v[148:149]
	v_pk_mul_f32 v[22:23], v[22:23], v[150:151]
	v_pk_mul_f32 v[16:17], v[16:17], v[164:165]
	v_pk_mul_f32 v[18:19], v[18:19], v[166:167]
	v_cvt_pk_bf16_f32 v20, v20, v21
	v_cvt_pk_bf16_f32 v21, v22, v23
	v_cvt_pk_bf16_f32 v22, v16, v17
	v_cvt_pk_bf16_f32 v23, v18, v19
	global_store_dwordx4 v146, v[20:23], s[92:93]
	s_add_u32 s92, s86, 0xa0100
	s_addc_u32 s93, s87, 0
	v_pk_mul_f32 v[148:149], v[12:13], s[98:99]
	v_pk_mul_f32 v[150:151], v[14:15], s[98:99]
	v_pk_mul_f32 v[164:165], v[8:9], s[98:99]
	v_pk_mul_f32 v[166:167], v[10:11], s[98:99]
	v_exp_f32_e32 v148, v148
	v_exp_f32_e32 v149, v149
	v_exp_f32_e32 v150, v150
	v_exp_f32_e32 v151, v151
	v_exp_f32_e32 v164, v164
	v_exp_f32_e32 v165, v165
	v_exp_f32_e32 v166, v166
	v_exp_f32_e32 v167, v167
	v_pk_add_f32 v[148:149], v[148:149], 1.0 op_sel_hi:[1,0]
	v_pk_add_f32 v[150:151], v[150:151], 1.0 op_sel_hi:[1,0]
	v_pk_add_f32 v[164:165], v[164:165], 1.0 op_sel_hi:[1,0]
	v_pk_add_f32 v[166:167], v[166:167], 1.0 op_sel_hi:[1,0]
	v_rcp_f32_e32 v148, v148
	v_rcp_f32_e32 v149, v149
	v_rcp_f32_e32 v150, v150
	v_rcp_f32_e32 v151, v151
	v_rcp_f32_e32 v164, v164
	v_rcp_f32_e32 v165, v165
	v_rcp_f32_e32 v166, v166
	v_rcp_f32_e32 v167, v167
	v_pk_mul_f32 v[12:13], v[12:13], v[148:149]
	v_pk_mul_f32 v[14:15], v[14:15], v[150:151]
	v_pk_mul_f32 v[8:9], v[8:9], v[164:165]
	v_pk_mul_f32 v[10:11], v[10:11], v[166:167]
	v_cvt_pk_bf16_f32 v12, v12, v13
	v_cvt_pk_bf16_f32 v13, v14, v15
	v_cvt_pk_bf16_f32 v14, v8, v9
	v_cvt_pk_bf16_f32 v15, v10, v11
	global_store_dwordx4 v146, v[12:15], s[92:93]
	s_add_u32 s92, s86, 0xb0100
	s_addc_u32 s93, s87, 0
	v_pk_mul_f32 v[148:149], v[4:5], s[98:99]
	v_pk_mul_f32 v[150:151], v[6:7], s[98:99]
	v_pk_mul_f32 v[164:165], v[0:1], s[98:99]
	v_pk_mul_f32 v[166:167], v[2:3], s[98:99]
	v_exp_f32_e32 v148, v148
	v_exp_f32_e32 v149, v149
	v_exp_f32_e32 v150, v150
	v_exp_f32_e32 v151, v151
	v_exp_f32_e32 v164, v164
	v_exp_f32_e32 v165, v165
	v_exp_f32_e32 v166, v166
	v_exp_f32_e32 v167, v167
	v_pk_add_f32 v[148:149], v[148:149], 1.0 op_sel_hi:[1,0]
	v_pk_add_f32 v[150:151], v[150:151], 1.0 op_sel_hi:[1,0]
	v_pk_add_f32 v[164:165], v[164:165], 1.0 op_sel_hi:[1,0]
	v_pk_add_f32 v[166:167], v[166:167], 1.0 op_sel_hi:[1,0]
	v_rcp_f32_e32 v148, v148
	v_rcp_f32_e32 v149, v149
	v_rcp_f32_e32 v150, v150
	v_rcp_f32_e32 v151, v151
	v_rcp_f32_e32 v164, v164
	v_rcp_f32_e32 v165, v165
	v_rcp_f32_e32 v166, v166
	v_rcp_f32_e32 v167, v167
	v_pk_mul_f32 v[4:5], v[4:5], v[148:149]
	v_pk_mul_f32 v[6:7], v[6:7], v[150:151]
	v_pk_mul_f32 v[0:1], v[0:1], v[164:165]
	v_pk_mul_f32 v[2:3], v[2:3], v[166:167]
	v_cvt_pk_bf16_f32 v4, v4, v5
	v_cvt_pk_bf16_f32 v5, v6, v7
	v_cvt_pk_bf16_f32 v6, v0, v1
	v_cvt_pk_bf16_f32 v7, v2, v3
	global_store_dwordx4 v146, v[4:7], s[92:93]
	s_branch .Le6_done
.Le6_q:
	s_mul_i32 s85, s84, 0x1000
	s_add_u32 s86, s14, s85
	s_addc_u32 s87, s15, 0
	s_add_u32 s86, s86, 0x58e0000
	s_addc_u32 s87, s87, 0
	s_sub_i32 s85, s6, 0
	s_lshl_b32 s85, s85, 9
	s_add_u32 s86, s86, s85
	s_addc_u32 s87, s87, 0
	v_lshlrev_b32_e32 v146, 1, v154
	s_movk_i32 s85, 0x1000
	v_mad_u32_u24 v146, v152, s85, v146
	s_mov_b64 s[92:93], s[86:87]
	v_cvt_pk_bf16_f32 v158, v124, v125
	v_cvt_pk_bf16_f32 v159, v126, v127
	v_cvt_pk_bf16_f32 v160, v120, v121
	v_cvt_pk_bf16_f32 v161, v122, v123
	global_store_dwordx4 v146, v[158:161], s[92:93]
	s_add_u32 s92, s86, 0x10000
	s_addc_u32 s93, s87, 0
	v_cvt_pk_bf16_f32 v162, v116, v117
	v_cvt_pk_bf16_f32 v163, v118, v119
	v_cvt_pk_bf16_f32 v164, v112, v113
	v_cvt_pk_bf16_f32 v165, v114, v115
	global_store_dwordx4 v146, v[162:165], s[92:93]
	s_add_u32 s92, s86, 0x20000
	s_addc_u32 s93, s87, 0
	v_cvt_pk_bf16_f32 v158, v108, v109
	v_cvt_pk_bf16_f32 v159, v110, v111
	v_cvt_pk_bf16_f32 v160, v104, v105
	v_cvt_pk_bf16_f32 v161, v106, v107
	global_store_dwordx4 v146, v[158:161], s[92:93]
	s_add_u32 s92, s86, 0x30000
	s_addc_u32 s93, s87, 0
	v_cvt_pk_bf16_f32 v162, v100, v101
	v_cvt_pk_bf16_f32 v163, v102, v103
	v_cvt_pk_bf16_f32 v164, v96, v97
	v_cvt_pk_bf16_f32 v165, v98, v99
	global_store_dwordx4 v146, v[162:165], s[92:93]
	s_add_u32 s92, s86, 0x100
	s_addc_u32 s93, s87, 0
	v_cvt_pk_bf16_f32 v158, v92, v93
	v_cvt_pk_bf16_f32 v159, v94, v95
	v_cvt_pk_bf16_f32 v160, v88, v89
	v_cvt_pk_bf16_f32 v161, v90, v91
	global_store_dwordx4 v146, v[158:161], s[92:93]
	s_add_u32 s92, s86, 0x10100
	s_addc_u32 s93, s87, 0
	v_cvt_pk_bf16_f32 v162, v84, v85
	v_cvt_pk_bf16_f32 v163, v86, v87
	v_cvt_pk_bf16_f32 v164, v80, v81
	v_cvt_pk_bf16_f32 v165, v82, v83
	global_store_dwordx4 v146, v[162:165], s[92:93]
	s_add_u32 s92, s86, 0x20100
	s_addc_u32 s93, s87, 0
	v_cvt_pk_bf16_f32 v158, v76, v77
	v_cvt_pk_bf16_f32 v159, v78, v79
	v_cvt_pk_bf16_f32 v160, v72, v73
	v_cvt_pk_bf16_f32 v161, v74, v75
	global_store_dwordx4 v146, v[158:161], s[92:93]
	s_add_u32 s92, s86, 0x30100
	s_addc_u32 s93, s87, 0
	v_cvt_pk_bf16_f32 v162, v68, v69
	v_cvt_pk_bf16_f32 v163, v70, v71
	v_cvt_pk_bf16_f32 v164, v64, v65
	v_cvt_pk_bf16_f32 v165, v66, v67
	global_store_dwordx4 v146, v[162:165], s[92:93]
; __device__ __forceinline__ void st8_bf16(bf16_t* p, const f32x4 a, const f32x4 b) { __builtin_nontemporal_store((u32x4){pk_bf16(a[0], a[1]), pk_bf16(a[2], a[3]), pk_bf16(b[0], b[1]), pk_bf16(b[2], b[3])}, (u32x4*)p); }
; __device__ __forceinline__ void st8_f32(float* p, const f32x4 a, const f32x4 b) { __builtin_nontemporal_store(a, (f32x4*)p); __builtin_nontemporal_store(b, (f32x4*)(p + 4)); }
;     __device__ __forceinline__ void store8(int row, int col, const f32x4 v, const f32x4 w) const {
;         if (col < 1536) st8_bf16((bf16_t*)(ws + WS_BRANCH) + (size_t)row * BR + col, v, w);
;         else if (col < 3072) { const int c = col - 1536; st8_bf16((bf16_t*)(ws + WS_KB) + (size_t)row * MIXW + c, v, w);
;             if (row < MP) st8_f32(out + O_PK + (size_t)row * MIXW + c, v, w); else st8_f32(out + O_SK + (size_t)(row - MP) * MIXW + c, v, w); }
;         else if (col < 4608) { const int c = col - 3072; st8_bf16((bf16_t*)(ws + WS_VB) + (size_t)row * MIXW + c, v, w);
;             if (row < MP) st8_f32(out + O_PV + (size_t)row * MIXW + c, v, w); else st8_f32(out + O_SV + (size_t)(row - MP) * MIXW + c, v, w); }
;         else if (col < 5120) st8_bf16((bf16_t*)(ws + WS_BRANCH) + (size_t)row * BR + 1536 + (col - 4608), v, w);
	s_add_u32 s92, s86, 0x80000
	s_addc_u32 s93, s87, 0
	v_cvt_pk_bf16_f32 v158, v60, v61
	v_cvt_pk_bf16_f32 v159, v62, v63
	v_cvt_pk_bf16_f32 v160, v56, v57
	v_cvt_pk_bf16_f32 v161, v58, v59
	global_store_dwordx4 v146, v[158:161], s[92:93]
	s_add_u32 s92, s86, 0x90000
	s_addc_u32 s93, s87, 0
	v_cvt_pk_bf16_f32 v162, v52, v53
	v_cvt_pk_bf16_f32 v163, v54, v55
	v_cvt_pk_bf16_f32 v164, v48, v49
	v_cvt_pk_bf16_f32 v165, v50, v51
	global_store_dwordx4 v146, v[162:165], s[92:93]
	s_add_u32 s92, s86, 0xa0000
	s_addc_u32 s93, s87, 0
	v_cvt_pk_bf16_f32 v158, v44, v45
	v_cvt_pk_bf16_f32 v159, v46, v47
	v_cvt_pk_bf16_f32 v160, v40, v41
	v_cvt_pk_bf16_f32 v161, v42, v43
	global_store_dwordx4 v146, v[158:161], s[92:93]
	s_add_u32 s92, s86, 0xb0000
	s_addc_u32 s93, s87, 0
	v_cvt_pk_bf16_f32 v162, v36, v37
	v_cvt_pk_bf16_f32 v163, v38, v39
	v_cvt_pk_bf16_f32 v164, v32, v33
	v_cvt_pk_bf16_f32 v165, v34, v35
	global_store_dwordx4 v146, v[162:165], s[92:93]
	s_add_u32 s92, s86, 0x80100
	s_addc_u32 s93, s87, 0
	v_cvt_pk_bf16_f32 v158, v28, v29
	v_cvt_pk_bf16_f32 v159, v30, v31
	v_cvt_pk_bf16_f32 v160, v24, v25
	v_cvt_pk_bf16_f32 v161, v26, v27
	global_store_dwordx4 v146, v[158:161], s[92:93]
	s_add_u32 s92, s86, 0x90100
	s_addc_u32 s93, s87, 0
	v_cvt_pk_bf16_f32 v162, v20, v21
	v_cvt_pk_bf16_f32 v163, v22, v23
	v_cvt_pk_bf16_f32 v164, v16, v17
	v_cvt_pk_bf16_f32 v165, v18, v19
	global_store_dwordx4 v146, v[162:165], s[92:93]
	s_add_u32 s92, s86, 0xa0100
	s_addc_u32 s93, s87, 0
	v_cvt_pk_bf16_f32 v158, v12, v13
	v_cvt_pk_bf16_f32 v159, v14, v15
	v_cvt_pk_bf16_f32 v160, v8, v9
	v_cvt_pk_bf16_f32 v161, v10, v11
	global_store_dwordx4 v146, v[158:161], s[92:93]
	s_add_u32 s92, s86, 0xb0100
	s_addc_u32 s93, s87, 0
	v_cvt_pk_bf16_f32 v162, v4, v5
	v_cvt_pk_bf16_f32 v163, v6, v7
	v_cvt_pk_bf16_f32 v164, v0, v1
	v_cvt_pk_bf16_f32 v165, v2, v3
	global_store_dwordx4 v146, v[162:165], s[92:93]
	s_branch .Le6_done
.Le6_b2:
	s_mul_i32 s85, s84, 0x1000
	s_add_u32 s86, s14, s85
	s_addc_u32 s87, s15, 0
	s_add_u32 s86, s86, 0x58e0c00
	s_addc_u32 s87, s87, 0
	s_sub_i32 s85, s6, 18
	s_lshl_b32 s85, s85, 9
	s_add_u32 s86, s86, s85
	s_addc_u32 s87, s87, 0
	v_lshlrev_b32_e32 v146, 1, v154
	s_movk_i32 s85, 0x1000
	v_mad_u32_u24 v146, v152, s85, v146
	s_mov_b64 s[92:93], s[86:87]
	v_cvt_pk_bf16_f32 v158, v124, v125
	v_cvt_pk_bf16_f32 v159, v126, v127
	v_cvt_pk_bf16_f32 v160, v120, v121
	v_cvt_pk_bf16_f32 v161, v122, v123
	global_store_dwordx4 v146, v[158:161], s[92:93]
	s_add_u32 s92, s86, 0x10000
	s_addc_u32 s93, s87, 0
	v_cvt_pk_bf16_f32 v162, v116, v117
	v_cvt_pk_bf16_f32 v163, v118, v119
	v_cvt_pk_bf16_f32 v164, v112, v113
	v_cvt_pk_bf16_f32 v165, v114, v115
	global_store_dwordx4 v146, v[162:165], s[92:93]
	s_add_u32 s92, s86, 0x20000
	s_addc_u32 s93, s87, 0
	v_cvt_pk_bf16_f32 v158, v108, v109
	v_cvt_pk_bf16_f32 v159, v110, v111
	v_cvt_pk_bf16_f32 v160, v104, v105
	v_cvt_pk_bf16_f32 v161, v106, v107
	global_store_dwordx4 v146, v[158:161], s[92:93]
	s_add_u32 s92, s86, 0x30000
	s_addc_u32 s93, s87, 0
	v_cvt_pk_bf16_f32 v162, v100, v101
	v_cvt_pk_bf16_f32 v163, v102, v103
	v_cvt_pk_bf16_f32 v164, v96, v97
	v_cvt_pk_bf16_f32 v165, v98, v99
	global_store_dwordx4 v146, v[162:165], s[92:93]
	s_add_u32 s92, s86, 0x100
	s_addc_u32 s93, s87, 0
	v_cvt_pk_bf16_f32 v158, v92, v93
	v_cvt_pk_bf16_f32 v159, v94, v95
	v_cvt_pk_bf16_f32 v160, v88, v89
	v_cvt_pk_bf16_f32 v161, v90, v91
	global_store_dwordx4 v146, v[158:161], s[92:93]
	s_add_u32 s92, s86, 0x10100
	s_addc_u32 s93, s87, 0
	v_cvt_pk_bf16_f32 v162, v84, v85
	v_cvt_pk_bf16_f32 v163, v86, v87
	v_cvt_pk_bf16_f32 v164, v80, v81
	v_cvt_pk_bf16_f32 v165, v82, v83
	global_store_dwordx4 v146, v[162:165], s[92:93]
	s_add_u32 s92, s86, 0x20100
	s_addc_u32 s93, s87, 0
	v_cvt_pk_bf16_f32 v158, v76, v77
	v_cvt_pk_bf16_f32 v159, v78, v79
	v_cvt_pk_bf16_f32 v160, v72, v73
	v_cvt_pk_bf16_f32 v161, v74, v75
	global_store_dwordx4 v146, v[158:161], s[92:93]
	s_add_u32 s92, s86, 0x30100
	s_addc_u32 s93, s87, 0
	v_cvt_pk_bf16_f32 v162, v68, v69
	v_cvt_pk_bf16_f32 v163, v70, v71
	v_cvt_pk_bf16_f32 v164, v64, v65
	v_cvt_pk_bf16_f32 v165, v66, v67
	global_store_dwordx4 v146, v[162:165], s[92:93]
	s_add_u32 s92, s86, 0x80000
	s_addc_u32 s93, s87, 0
	v_cvt_pk_bf16_f32 v158, v60, v61
	v_cvt_pk_bf16_f32 v159, v62, v63
	v_cvt_pk_bf16_f32 v160, v56, v57
	v_cvt_pk_bf16_f32 v161, v58, v59
	global_store_dwordx4 v146, v[158:161], s[92:93]
	s_add_u32 s92, s86, 0x90000
	s_addc_u32 s93, s87, 0
	v_cvt_pk_bf16_f32 v162, v52, v53
	v_cvt_pk_bf16_f32 v163, v54, v55
	v_cvt_pk_bf16_f32 v164, v48, v49
	v_cvt_pk_bf16_f32 v165, v50, v51
	global_store_dwordx4 v146, v[162:165], s[92:93]
	s_add_u32 s92, s86, 0xa0000
	s_addc_u32 s93, s87, 0
	v_cvt_pk_bf16_f32 v158, v44, v45
	v_cvt_pk_bf16_f32 v159, v46, v47
	v_cvt_pk_bf16_f32 v160, v40, v41
	v_cvt_pk_bf16_f32 v161, v42, v43
	global_store_dwordx4 v146, v[158:161], s[92:93]
	s_add_u32 s92, s86, 0xb0000
	s_addc_u32 s93, s87, 0
	v_cvt_pk_bf16_f32 v162, v36, v37
	v_cvt_pk_bf16_f32 v163, v38, v39
	v_cvt_pk_bf16_f32 v164, v32, v33
	v_cvt_pk_bf16_f32 v165, v34, v35
	global_store_dwordx4 v146, v[162:165], s[92:93]
	s_add_u32 s92, s86, 0x80100
	s_addc_u32 s93, s87, 0
	v_cvt_pk_bf16_f32 v158, v28, v29
	v_cvt_pk_bf16_f32 v159, v30, v31
	v_cvt_pk_bf16_f32 v160, v24, v25
	v_cvt_pk_bf16_f32 v161, v26, v27
	global_store_dwordx4 v146, v[158:161], s[92:93]
	s_add_u32 s92, s86, 0x90100
	s_addc_u32 s93, s87, 0
	v_cvt_pk_bf16_f32 v162, v20, v21
	v_cvt_pk_bf16_f32 v163, v22, v23
	v_cvt_pk_bf16_f32 v164, v16, v17
	v_cvt_pk_bf16_f32 v165, v18, v19
	global_store_dwordx4 v146, v[162:165], s[92:93]
	s_add_u32 s92, s86, 0xa0100
	s_addc_u32 s93, s87, 0
	v_cvt_pk_bf16_f32 v158, v12, v13
	v_cvt_pk_bf16_f32 v159, v14, v15
	v_cvt_pk_bf16_f32 v160, v8, v9
	v_cvt_pk_bf16_f32 v161, v10, v11
	global_store_dwordx4 v146, v[158:161], s[92:93]
	s_add_u32 s92, s86, 0xb0100
	s_addc_u32 s93, s87, 0
	v_cvt_pk_bf16_f32 v162, v4, v5
	v_cvt_pk_bf16_f32 v163, v6, v7
	v_cvt_pk_bf16_f32 v164, v0, v1
	v_cvt_pk_bf16_f32 v165, v2, v3
	global_store_dwordx4 v146, v[162:165], s[92:93]
	s_branch .Le6_done

; __device__ __forceinline__ void st8_bf16(bf16_t* p, const f32x4 a, const f32x4 b) { __builtin_nontemporal_store((u32x4){pk_bf16(a[0], a[1]), pk_bf16(a[2], a[3]), pk_bf16(b[0], b[1]), pk_bf16(b[2], b[3])}, (u32x4*)p); }
; __device__ __forceinline__ void st8_f32(float* p, const f32x4 a, const f32x4 b) { __builtin_nontemporal_store(a, (f32x4*)p); __builtin_nontemporal_store(b, (f32x4*)(p + 4)); }
;     __device__ __forceinline__ void store8(int row, int col, const f32x4 v, const f32x4 w) const {
;     ...
;         else if (col < 3072) { const int c = col - 1536; st8_bf16((bf16_t*)(ws + WS_KB) + (size_t)row * MIXW + c, v, w);
;             if (row < MP) st8_f32(out + O_PK + (size_t)row * MIXW + c, v, w); else st8_f32(out + O_SK + (size_t)(row - MP) * MIXW + c, v, w); }
.Le6_k_rows:
	s_add_u32 s88, s88, s85
	s_addc_u32 s89, s89, 0
	s_sub_i32 s85, s6, 6
	s_lshl_b32 s85, s85, 10
	s_add_u32 s88, s88, s85
	s_addc_u32 s89, s89, 0
	v_lshlrev_b32_e32 v147, 2, v154
	s_movk_i32 s85, 0x1800
	v_mad_u32_u24 v147, v152, s85, v147
	s_mov_b64 s[92:93], s[86:87]
	s_mov_b64 s[94:95], s[88:89]
	global_store_dwordx4 v147, v[124:127], s[94:95]
	global_store_dwordx4 v147, v[120:123], s[94:95] offset:16
	v_cvt_pk_bf16_f32 v158, v124, v125
	v_cvt_pk_bf16_f32 v159, v126, v127
	v_cvt_pk_bf16_f32 v160, v120, v121
	v_cvt_pk_bf16_f32 v161, v122, v123
	global_store_dwordx4 v146, v[158:161], s[92:93]
	s_add_u32 s92, s86, 0xc000
	s_addc_u32 s93, s87, 0
	s_add_u32 s94, s88, 0x18000
	s_addc_u32 s95, s89, 0
	global_store_dwordx4 v147, v[116:119], s[94:95]
	global_store_dwordx4 v147, v[112:115], s[94:95] offset:16
	v_cvt_pk_bf16_f32 v162, v116, v117
	v_cvt_pk_bf16_f32 v163, v118, v119
	v_cvt_pk_bf16_f32 v164, v112, v113
	v_cvt_pk_bf16_f32 v165, v114, v115
	global_store_dwordx4 v146, v[162:165], s[92:93]
	s_add_u32 s92, s86, 0x18000
	s_addc_u32 s93, s87, 0
	s_add_u32 s94, s88, 0x30000
	s_addc_u32 s95, s89, 0
	global_store_dwordx4 v147, v[108:111], s[94:95]
	global_store_dwordx4 v147, v[104:107], s[94:95] offset:16
	v_cvt_pk_bf16_f32 v158, v108, v109
	v_cvt_pk_bf16_f32 v159, v110, v111
	v_cvt_pk_bf16_f32 v160, v104, v105
	v_cvt_pk_bf16_f32 v161, v106, v107
	global_store_dwordx4 v146, v[158:161], s[92:93]
	s_add_u32 s92, s86, 0x24000
	s_addc_u32 s93, s87, 0
	s_add_u32 s94, s88, 0x48000
	s_addc_u32 s95, s89, 0
	global_store_dwordx4 v147, v[100:103], s[94:95]
	global_store_dwordx4 v147, v[96:99], s[94:95] offset:16
	v_cvt_pk_bf16_f32 v162, v100, v101
	v_cvt_pk_bf16_f32 v163, v102, v103
	v_cvt_pk_bf16_f32 v164, v96, v97
	v_cvt_pk_bf16_f32 v165, v98, v99
	global_store_dwordx4 v146, v[162:165], s[92:93]
	s_add_u32 s92, s86, 0x100
	s_addc_u32 s93, s87, 0
	s_add_u32 s94, s88, 0x200
	s_addc_u32 s95, s89, 0
	global_store_dwordx4 v147, v[92:95], s[94:95]
	global_store_dwordx4 v147, v[88:91], s[94:95] offset:16
	v_cvt_pk_bf16_f32 v158, v92, v93
	v_cvt_pk_bf16_f32 v159, v94, v95
	v_cvt_pk_bf16_f32 v160, v88, v89
	v_cvt_pk_bf16_f32 v161, v90, v91
	global_store_dwordx4 v146, v[158:161], s[92:93]
	s_add_u32 s92, s86, 0xc100
	s_addc_u32 s93, s87, 0
	s_add_u32 s94, s88, 0x18200
	s_addc_u32 s95, s89, 0
	global_store_dwordx4 v147, v[84:87], s[94:95]
	global_store_dwordx4 v147, v[80:83], s[94:95] offset:16
	v_cvt_pk_bf16_f32 v162, v84, v85
	v_cvt_pk_bf16_f32 v163, v86, v87
	v_cvt_pk_bf16_f32 v164, v80, v81
	v_cvt_pk_bf16_f32 v165, v82, v83
	global_store_dwordx4 v146, v[162:165], s[92:93]
	s_add_u32 s92, s86, 0x18100
	s_addc_u32 s93, s87, 0
	s_add_u32 s94, s88, 0x30200
	s_addc_u32 s95, s89, 0
	global_store_dwordx4 v147, v[76:79], s[94:95]
	global_store_dwordx4 v147, v[72:75], s[94:95] offset:16
	v_cvt_pk_bf16_f32 v158, v76, v77
	v_cvt_pk_bf16_f32 v159, v78, v79
	v_cvt_pk_bf16_f32 v160, v72, v73
	v_cvt_pk_bf16_f32 v161, v74, v75
	global_store_dwordx4 v146, v[158:161], s[92:93]
	s_add_u32 s92, s86, 0x24100
	s_addc_u32 s93, s87, 0
	s_add_u32 s94, s88, 0x48200
	s_addc_u32 s95, s89, 0
	global_store_dwordx4 v147, v[68:71], s[94:95]
	global_store_dwordx4 v147, v[64:67], s[94:95] offset:16
	v_cvt_pk_bf16_f32 v162, v68, v69
	v_cvt_pk_bf16_f32 v163, v70, v71
	v_cvt_pk_bf16_f32 v164, v64, v65
	v_cvt_pk_bf16_f32 v165, v66, v67
	global_store_dwordx4 v146, v[162:165], s[92:93]
	s_add_u32 s92, s86, 0x60000
	s_addc_u32 s93, s87, 0
	s_add_u32 s94, s88, 0xc0000
	s_addc_u32 s95, s89, 0
	global_store_dwordx4 v147, v[60:63], s[94:95]
	global_store_dwordx4 v147, v[56:59], s[94:95] offset:16
	v_cvt_pk_bf16_f32 v158, v60, v61
	v_cvt_pk_bf16_f32 v159, v62, v63
	v_cvt_pk_bf16_f32 v160, v56, v57
	v_cvt_pk_bf16_f32 v161, v58, v59
	global_store_dwordx4 v146, v[158:161], s[92:93]
	s_add_u32 s92, s86, 0x6c000
	s_addc_u32 s93, s87, 0
	s_add_u32 s94, s88, 0xd8000
	s_addc_u32 s95, s89, 0
	global_store_dwordx4 v147, v[52:55], s[94:95]
	global_store_dwordx4 v147, v[48:51], s[94:95] offset:16
	v_cvt_pk_bf16_f32 v162, v52, v53
	v_cvt_pk_bf16_f32 v163, v54, v55
	v_cvt_pk_bf16_f32 v164, v48, v49
	v_cvt_pk_bf16_f32 v165, v50, v51
	global_store_dwordx4 v146, v[162:165], s[92:93]
	s_add_u32 s92, s86, 0x78000
	s_addc_u32 s93, s87, 0
	s_add_u32 s94, s88, 0xf0000
	s_addc_u32 s95, s89, 0
	global_store_dwordx4 v147, v[44:47], s[94:95]
	global_store_dwordx4 v147, v[40:43], s[94:95] offset:16
	v_cvt_pk_bf16_f32 v158, v44, v45
	v_cvt_pk_bf16_f32 v159, v46, v47
	v_cvt_pk_bf16_f32 v160, v40, v41
	v_cvt_pk_bf16_f32 v161, v42, v43
	global_store_dwordx4 v146, v[158:161], s[92:93]
	s_add_u32 s92, s86, 0x84000
	s_addc_u32 s93, s87, 0
	s_add_u32 s94, s88, 0x108000
	s_addc_u32 s95, s89, 0
	global_store_dwordx4 v147, v[36:39], s[94:95]
	global_store_dwordx4 v147, v[32:35], s[94:95] offset:16
	v_cvt_pk_bf16_f32 v162, v36, v37
	v_cvt_pk_bf16_f32 v163, v38, v39
	v_cvt_pk_bf16_f32 v164, v32, v33
	v_cvt_pk_bf16_f32 v165, v34, v35
	global_store_dwordx4 v146, v[162:165], s[92:93]
	s_add_u32 s92, s86, 0x60100
	s_addc_u32 s93, s87, 0
	s_add_u32 s94, s88, 0xc0200
	s_addc_u32 s95, s89, 0
	global_store_dwordx4 v147, v[28:31], s[94:95]
	global_store_dwordx4 v147, v[24:27], s[94:95] offset:16
	v_cvt_pk_bf16_f32 v158, v28, v29
	v_cvt_pk_bf16_f32 v159, v30, v31
	v_cvt_pk_bf16_f32 v160, v24, v25
	v_cvt_pk_bf16_f32 v161, v26, v27
	global_store_dwordx4 v146, v[158:161], s[92:93]
	s_add_u32 s92, s86, 0x6c100
	s_addc_u32 s93, s87, 0
	s_add_u32 s94, s88, 0xd8200
	s_addc_u32 s95, s89, 0
	global_store_dwordx4 v147, v[20:23], s[94:95]
	global_store_dwordx4 v147, v[16:19], s[94:95] offset:16
	v_cvt_pk_bf16_f32 v162, v20, v21
	v_cvt_pk_bf16_f32 v163, v22, v23
	v_cvt_pk_bf16_f32 v164, v16, v17
	v_cvt_pk_bf16_f32 v165, v18, v19
	global_store_dwordx4 v146, v[162:165], s[92:93]
	s_add_u32 s92, s86, 0x78100
	s_addc_u32 s93, s87, 0
	s_add_u32 s94, s88, 0xf0200
	s_addc_u32 s95, s89, 0
	global_store_dwordx4 v147, v[12:15], s[94:95]
	global_store_dwordx4 v147, v[8:11], s[94:95] offset:16
	v_cvt_pk_bf16_f32 v158, v12, v13
	v_cvt_pk_bf16_f32 v159, v14, v15
	v_cvt_pk_bf16_f32 v160, v8, v9
	v_cvt_pk_bf16_f32 v161, v10, v11
	global_store_dwordx4 v146, v[158:161], s[92:93]
	s_add_u32 s92, s86, 0x84100
	s_addc_u32 s93, s87, 0
	s_add_u32 s94, s88, 0x108200
	s_addc_u32 s95, s89, 0
	global_store_dwordx4 v147, v[4:7], s[94:95]
	global_store_dwordx4 v147, v[0:3], s[94:95] offset:16
	v_cvt_pk_bf16_f32 v162, v4, v5
	v_cvt_pk_bf16_f32 v163, v6, v7
	v_cvt_pk_bf16_f32 v164, v0, v1
	v_cvt_pk_bf16_f32 v165, v2, v3
	global_store_dwordx4 v146, v[162:165], s[92:93]
	s_branch .Le6_done

; __device__ __forceinline__ void st8_bf16(bf16_t* p, const f32x4 a, const f32x4 b) { __builtin_nontemporal_store((u32x4){pk_bf16(a[0], a[1]), pk_bf16(a[2], a[3]), pk_bf16(b[0], b[1]), pk_bf16(b[2], b[3])}, (u32x4*)p); }
; __device__ __forceinline__ void st8_f32(float* p, const f32x4 a, const f32x4 b) { __builtin_nontemporal_store(a, (f32x4*)p); __builtin_nontemporal_store(b, (f32x4*)(p + 4)); }
;     __device__ __forceinline__ void store8(int row, int col, const f32x4 v, const f32x4 w) const {
;     ...
;         else if (col < 4608) { const int c = col - 3072; st8_bf16((bf16_t*)(ws + WS_VB) + (size_t)row * MIXW + c, v, w);
;             if (row < MP) st8_f32(out + O_PV + (size_t)row * MIXW + c, v, w); else st8_f32(out + O_SV + (size_t)(row - MP) * MIXW + c, v, w); }
.Le6_v_rows:
	s_add_u32 s88, s88, s85
	s_addc_u32 s89, s89, 0
	s_sub_i32 s85, s6, 12
	s_lshl_b32 s85, s85, 10
	s_add_u32 s88, s88, s85
	s_addc_u32 s89, s89, 0
	v_lshlrev_b32_e32 v147, 2, v154
	s_movk_i32 s85, 0x1800
	v_mad_u32_u24 v147, v152, s85, v147
	s_mov_b64 s[92:93], s[86:87]
	s_mov_b64 s[94:95], s[88:89]
	global_store_dwordx4 v147, v[124:127], s[94:95]
	global_store_dwordx4 v147, v[120:123], s[94:95] offset:16
	v_cvt_pk_bf16_f32 v158, v124, v125
	v_cvt_pk_bf16_f32 v159, v126, v127
	v_cvt_pk_bf16_f32 v160, v120, v121
	v_cvt_pk_bf16_f32 v161, v122, v123
	global_store_dwordx4 v146, v[158:161], s[92:93]
	s_add_u32 s92, s86, 0xc000
	s_addc_u32 s93, s87, 0
	s_add_u32 s94, s88, 0x18000
	s_addc_u32 s95, s89, 0
	global_store_dwordx4 v147, v[116:119], s[94:95]
	global_store_dwordx4 v147, v[112:115], s[94:95] offset:16
	v_cvt_pk_bf16_f32 v162, v116, v117
	v_cvt_pk_bf16_f32 v163, v118, v119
	v_cvt_pk_bf16_f32 v164, v112, v113
	v_cvt_pk_bf16_f32 v165, v114, v115
	global_store_dwordx4 v146, v[162:165], s[92:93]
	s_add_u32 s92, s86, 0x18000
	s_addc_u32 s93, s87, 0
	s_add_u32 s94, s88, 0x30000
	s_addc_u32 s95, s89, 0
	global_store_dwordx4 v147, v[108:111], s[94:95]
	global_store_dwordx4 v147, v[104:107], s[94:95] offset:16
	v_cvt_pk_bf16_f32 v158, v108, v109
	v_cvt_pk_bf16_f32 v159, v110, v111
	v_cvt_pk_bf16_f32 v160, v104, v105
	v_cvt_pk_bf16_f32 v161, v106, v107
	global_store_dwordx4 v146, v[158:161], s[92:93]
	s_add_u32 s92, s86, 0x24000
	s_addc_u32 s93, s87, 0
	s_add_u32 s94, s88, 0x48000
	s_addc_u32 s95, s89, 0
	global_store_dwordx4 v147, v[100:103], s[94:95]
	global_store_dwordx4 v147, v[96:99], s[94:95] offset:16
	v_cvt_pk_bf16_f32 v162, v100, v101
	v_cvt_pk_bf16_f32 v163, v102, v103
	v_cvt_pk_bf16_f32 v164, v96, v97
	v_cvt_pk_bf16_f32 v165, v98, v99
	global_store_dwordx4 v146, v[162:165], s[92:93]
	s_add_u32 s92, s86, 0x100
	s_addc_u32 s93, s87, 0
	s_add_u32 s94, s88, 0x200
	s_addc_u32 s95, s89, 0
	global_store_dwordx4 v147, v[92:95], s[94:95]
	global_store_dwordx4 v147, v[88:91], s[94:95] offset:16
	v_cvt_pk_bf16_f32 v158, v92, v93
	v_cvt_pk_bf16_f32 v159, v94, v95
	v_cvt_pk_bf16_f32 v160, v88, v89
	v_cvt_pk_bf16_f32 v161, v90, v91
	global_store_dwordx4 v146, v[158:161], s[92:93]
	s_add_u32 s92, s86, 0xc100
	s_addc_u32 s93, s87, 0
	s_add_u32 s94, s88, 0x18200
	s_addc_u32 s95, s89, 0
	global_store_dwordx4 v147, v[84:87], s[94:95]
	global_store_dwordx4 v147, v[80:83], s[94:95] offset:16
	v_cvt_pk_bf16_f32 v162, v84, v85
	v_cvt_pk_bf16_f32 v163, v86, v87
	v_cvt_pk_bf16_f32 v164, v80, v81
	v_cvt_pk_bf16_f32 v165, v82, v83
	global_store_dwordx4 v146, v[162:165], s[92:93]
	s_add_u32 s92, s86, 0x18100
	s_addc_u32 s93, s87, 0
	s_add_u32 s94, s88, 0x30200
	s_addc_u32 s95, s89, 0
	global_store_dwordx4 v147, v[76:79], s[94:95]
	global_store_dwordx4 v147, v[72:75], s[94:95] offset:16
	v_cvt_pk_bf16_f32 v158, v76, v77
	v_cvt_pk_bf16_f32 v159, v78, v79
	v_cvt_pk_bf16_f32 v160, v72, v73
	v_cvt_pk_bf16_f32 v161, v74, v75
	global_store_dwordx4 v146, v[158:161], s[92:93]
	s_add_u32 s92, s86, 0x24100
	s_addc_u32 s93, s87, 0
	s_add_u32 s94, s88, 0x48200
	s_addc_u32 s95, s89, 0
	global_store_dwordx4 v147, v[68:71], s[94:95]
	global_store_dwordx4 v147, v[64:67], s[94:95] offset:16
	v_cvt_pk_bf16_f32 v162, v68, v69
	v_cvt_pk_bf16_f32 v163, v70, v71
	v_cvt_pk_bf16_f32 v164, v64, v65
	v_cvt_pk_bf16_f32 v165, v66, v67
	global_store_dwordx4 v146, v[162:165], s[92:93]
	s_add_u32 s92, s86, 0x60000
	s_addc_u32 s93, s87, 0
	s_add_u32 s94, s88, 0xc0000
	s_addc_u32 s95, s89, 0
	global_store_dwordx4 v147, v[60:63], s[94:95]
	global_store_dwordx4 v147, v[56:59], s[94:95] offset:16
	v_cvt_pk_bf16_f32 v158, v60, v61
	v_cvt_pk_bf16_f32 v159, v62, v63
	v_cvt_pk_bf16_f32 v160, v56, v57
	v_cvt_pk_bf16_f32 v161, v58, v59
	global_store_dwordx4 v146, v[158:161], s[92:93]
	s_add_u32 s92, s86, 0x6c000
	s_addc_u32 s93, s87, 0
	s_add_u32 s94, s88, 0xd8000
	s_addc_u32 s95, s89, 0
	global_store_dwordx4 v147, v[52:55], s[94:95]
	global_store_dwordx4 v147, v[48:51], s[94:95] offset:16
	v_cvt_pk_bf16_f32 v162, v52, v53
	v_cvt_pk_bf16_f32 v163, v54, v55
	v_cvt_pk_bf16_f32 v164, v48, v49
	v_cvt_pk_bf16_f32 v165, v50, v51
	global_store_dwordx4 v146, v[162:165], s[92:93]
	s_add_u32 s92, s86, 0x78000
	s_addc_u32 s93, s87, 0
	s_add_u32 s94, s88, 0xf0000
	s_addc_u32 s95, s89, 0
	global_store_dwordx4 v147, v[44:47], s[94:95]
	global_store_dwordx4 v147, v[40:43], s[94:95] offset:16
	v_cvt_pk_bf16_f32 v158, v44, v45
	v_cvt_pk_bf16_f32 v159, v46, v47
	v_cvt_pk_bf16_f32 v160, v40, v41
	v_cvt_pk_bf16_f32 v161, v42, v43
	global_store_dwordx4 v146, v[158:161], s[92:93]
	s_add_u32 s92, s86, 0x84000
	s_addc_u32 s93, s87, 0
	s_add_u32 s94, s88, 0x108000
	s_addc_u32 s95, s89, 0
	global_store_dwordx4 v147, v[36:39], s[94:95]
	global_store_dwordx4 v147, v[32:35], s[94:95] offset:16
	v_cvt_pk_bf16_f32 v162, v36, v37
	v_cvt_pk_bf16_f32 v163, v38, v39
	v_cvt_pk_bf16_f32 v164, v32, v33
	v_cvt_pk_bf16_f32 v165, v34, v35
	global_store_dwordx4 v146, v[162:165], s[92:93]
	s_add_u32 s92, s86, 0x60100
	s_addc_u32 s93, s87, 0
	s_add_u32 s94, s88, 0xc0200
	s_addc_u32 s95, s89, 0
	global_store_dwordx4 v147, v[28:31], s[94:95]
	global_store_dwordx4 v147, v[24:27], s[94:95] offset:16
	v_cvt_pk_bf16_f32 v158, v28, v29
	v_cvt_pk_bf16_f32 v159, v30, v31
	v_cvt_pk_bf16_f32 v160, v24, v25
	v_cvt_pk_bf16_f32 v161, v26, v27
	global_store_dwordx4 v146, v[158:161], s[92:93]
	s_add_u32 s92, s86, 0x6c100
	s_addc_u32 s93, s87, 0
	s_add_u32 s94, s88, 0xd8200
	s_addc_u32 s95, s89, 0
	global_store_dwordx4 v147, v[20:23], s[94:95]
	global_store_dwordx4 v147, v[16:19], s[94:95] offset:16
	v_cvt_pk_bf16_f32 v162, v20, v21
	v_cvt_pk_bf16_f32 v163, v22, v23
	v_cvt_pk_bf16_f32 v164, v16, v17
	v_cvt_pk_bf16_f32 v165, v18, v19
	global_store_dwordx4 v146, v[162:165], s[92:93]
	s_add_u32 s92, s86, 0x78100
	s_addc_u32 s93, s87, 0
	s_add_u32 s94, s88, 0xf0200
	s_addc_u32 s95, s89, 0
	global_store_dwordx4 v147, v[12:15], s[94:95]
	global_store_dwordx4 v147, v[8:11], s[94:95] offset:16
	v_cvt_pk_bf16_f32 v158, v12, v13
	v_cvt_pk_bf16_f32 v159, v14, v15
	v_cvt_pk_bf16_f32 v160, v8, v9
	v_cvt_pk_bf16_f32 v161, v10, v11
	global_store_dwordx4 v146, v[158:161], s[92:93]
	s_add_u32 s92, s86, 0x84100
	s_addc_u32 s93, s87, 0
	s_add_u32 s94, s88, 0x108200
	s_addc_u32 s95, s89, 0
	global_store_dwordx4 v147, v[4:7], s[94:95]
	global_store_dwordx4 v147, v[0:3], s[94:95] offset:16
	v_cvt_pk_bf16_f32 v162, v4, v5
	v_cvt_pk_bf16_f32 v163, v6, v7
	v_cvt_pk_bf16_f32 v164, v0, v1
	v_cvt_pk_bf16_f32 v165, v2, v3
	global_store_dwordx4 v146, v[162:165], s[92:93]
	s_branch .Le6_done
